# load-segment trimming stacked on v075: M0 write moved ahead of the address add at 62 LDS-DMA sites, the s_nop pads dropped
# baseline (speedup 1.0000x reference)
; #define PG8_STAGE(bufoff, gbase, voff) do { _Pragma("unroll") for (int _i = 0; _i < 2; ++_i) \
;         __builtin_amdgcn_global_load_lds((const unsigned*)((const char*)(gbase) + (voff)[_i]), (PG8_LAS unsigned*)(lds + (bufoff) + ldsw + _i * 8192), 16, 0, 0); } while (0)
; #define PG8_LDA(dst, b, h) do { _Pragma("unroll") for (int m = 0; m < 4; ++m) _Pragma("unroll") for (int k = 0; k < 2; ++k) dst[m][k] = *(const PG8_LAS bf16x8*)(lds + PG8_SA(b, h) + aoff + m * 2048 + k * 1024); } while (0)
; #define PG8_LDB(dst, b, h) do { _Pragma("unroll") for (int n = 0; n < 2; ++n) _Pragma("unroll") for (int k = 0; k < 2; ++k) dst[n][k] = *(const PG8_LAS bf16x8*)(lds + PG8_SB(b, h) + boff + n * 2048 + k * 1024); } while (0)
; #define PG8_MMA(ai, bj, At, Bt) do { __builtin_amdgcn_s_setprio(1); _Pragma("unroll") for (int m = 0; m < 4; ++m) _Pragma("unroll") for (int n = 0; n < 2; ++n) _Pragma("unroll") for (int k = 0; k < 2; ++k) \
;         acc[ai][bj][m][n] = __builtin_amdgcn_mfma_f32_16x16x32_bf16(Bt[n][k], At[m][k], acc[ai][bj][m][n], 0, 0, 0); __builtin_amdgcn_s_setprio(0); } while (0)
; #define PG8_WAIT_V(n) asm volatile("s_waitcnt vmcnt(" #n ")" ::: "memory")
; #define PG8_BAR __builtin_amdgcn_s_barrier()
; template <class Epi, class Sched, bool ALIGN_EPI = false, bool SP2 = false>
; __device__ __forceinline__ void gemm_phase(PG8_LAS unsigned char* lds, const Gemm g, const Sched& S, const Epi& E, int tid_in) {
;     ...
;         for (int t = 0; t < nt; t += 2) {
;             const bool last = (t == nt - 2);
;             const char* a1 = cA + (size_t)(t + 1) * kstep;
;             const char* a2 = last ? nA : cA + (size_t)(t + 2) * kstep; const char* b2 = last ? nB : cB + (size_t)(t + 2) * kstep;
;             const char* a3 = a2 + kstep; const char* b3 = b2 + kstep;
;             if (last && has_next) S.a_ready(nxt);
;             if constexpr (SP2) {
;             PG8_LDB(B0, 0, 0); PG8_LDB(B1, 0, 1); PG8_SCHED; PG8_LDA(At, 0, 0); PG8_STAGE(PG8_SA(1, 1), a1 + hstepA, voffA);
;             PG8_WAIT_V(8); PG8_WAIT_L(0); PG8_BAR; PG8_MMA(0, 0, At, B0); PG8_MMA(0, 1, At, B1); PG8_BAR; PG8_SCHED;
;             PG8_LDA(At, 0, 1); PG8_STAGE(PG8_SB(0, 0), b2, voffB); PG8_STAGE(PG8_SB(0, 1), b2 + hstep, voffB); PG8_STAGE(PG8_SA(0, 0), a2, voffA);
;             PG8_WAIT_V(8); PG8_WAIT_L(0); PG8_BAR; PG8_MMA(1, 0, At, B0); PG8_MMA(1, 1, At, B1); PG8_BAR; PG8_SCHED;
.LBB0_282:
	s_add_u32 s26, s24, 0xfff80080
	s_addc_u32 s27, s25, -1
	s_add_i32 s45, 0, 0x10000
	s_cmp_eq_u32 s23, 28
	s_cselect_b32 s29, s19, s27
	s_cselect_b32 s28, s18, s26
	s_cselect_b32 s27, s21, s17
	s_cselect_b32 s26, s20, s15
	s_add_i32 s48, 0, 0x14000
	v_add_u32_e32 v158, s45, v152
	v_add_u32_e32 v186, s48, v152
	ds_read_b128 v[142:145], v158
	ds_read_b128 v[146:149], v158 offset:1024
	ds_read_b128 v[154:157], v158 offset:2048
	ds_read_b128 v[158:161], v158 offset:3072
	ds_read_b128 v[162:165], v186
	ds_read_b128 v[166:169], v186 offset:1024
	ds_read_b128 v[182:185], v186 offset:2048
	ds_read_b128 v[186:189], v186 offset:3072
	v_lshl_add_u64 v[222:223], s[24:25], 0, v[138:139]
	s_add_i32 m0, s33, 0xc000
	ds_read_b128 v[190:193], v153
	ds_read_b128 v[194:197], v153 offset:1024
	ds_read_b128 v[198:201], v153 offset:2048
	ds_read_b128 v[202:205], v153 offset:3072
	ds_read_b128 v[206:209], v153 offset:4096
	ds_read_b128 v[210:213], v153 offset:5120
	ds_read_b128 v[214:217], v153 offset:6144
	ds_read_b128 v[218:221], v153 offset:7168
	global_load_lds_dwordx4 v[222:223], off
	s_add_i32 m0, s33, 0xe000
	v_lshl_add_u64 v[222:223], s[24:25], 0, v[140:141]
	global_load_lds_dwordx4 v[222:223], off
	s_waitcnt vmcnt(8)
	s_waitcnt lgkmcnt(0)
	s_barrier
	s_setprio 1
	s_waitcnt lgkmcnt(0)
	v_mfma_f32_16x16x32_bf16 v[126:129], v[142:145], v[190:193], v[126:129]
	v_mfma_f32_16x16x32_bf16 v[118:121], v[154:157], v[190:193], v[118:121]
	v_mfma_f32_16x16x32_bf16 v[110:113], v[142:145], v[198:201], v[110:113]
	v_mfma_f32_16x16x32_bf16 v[102:105], v[154:157], v[198:201], v[102:105]
	v_mfma_f32_16x16x32_bf16 v[94:97], v[142:145], v[206:209], v[94:97]
	v_mfma_f32_16x16x32_bf16 v[86:89], v[154:157], v[206:209], v[86:89]
	v_mfma_f32_16x16x32_bf16 v[78:81], v[142:145], v[214:217], v[78:81]
	v_mfma_f32_16x16x32_bf16 v[70:73], v[154:157], v[214:217], v[70:73]
	v_mfma_f32_16x16x32_bf16 v[126:129], v[146:149], v[194:197], v[126:129]
	v_mfma_f32_16x16x32_bf16 v[118:121], v[158:161], v[194:197], v[118:121]
	v_mfma_f32_16x16x32_bf16 v[110:113], v[146:149], v[202:205], v[110:113]
	v_mfma_f32_16x16x32_bf16 v[102:105], v[158:161], v[202:205], v[102:105]
	v_mfma_f32_16x16x32_bf16 v[94:97], v[146:149], v[210:213], v[94:97]
	v_mfma_f32_16x16x32_bf16 v[86:89], v[158:161], v[210:213], v[86:89]
	v_mfma_f32_16x16x32_bf16 v[78:81], v[146:149], v[218:221], v[78:81]
	v_mfma_f32_16x16x32_bf16 v[70:73], v[158:161], v[218:221], v[70:73]
	s_setprio 0
	s_setprio 1
	v_mfma_f32_16x16x32_bf16 v[122:125], v[162:165], v[190:193], v[122:125]
	v_mfma_f32_16x16x32_bf16 v[114:117], v[182:185], v[190:193], v[114:117]
	v_mfma_f32_16x16x32_bf16 v[106:109], v[162:165], v[198:201], v[106:109]
	v_mfma_f32_16x16x32_bf16 v[98:101], v[182:185], v[198:201], v[98:101]
	v_mfma_f32_16x16x32_bf16 v[90:93], v[162:165], v[206:209], v[90:93]
	v_mfma_f32_16x16x32_bf16 v[82:85], v[182:185], v[206:209], v[82:85]
	v_mfma_f32_16x16x32_bf16 v[74:77], v[162:165], v[214:217], v[74:77]
	v_mfma_f32_16x16x32_bf16 v[66:69], v[182:185], v[214:217], v[66:69]
	v_mfma_f32_16x16x32_bf16 v[122:125], v[166:169], v[194:197], v[122:125]
	v_mfma_f32_16x16x32_bf16 v[114:117], v[186:189], v[194:197], v[114:117]
	v_mfma_f32_16x16x32_bf16 v[106:109], v[166:169], v[202:205], v[106:109]
	v_mfma_f32_16x16x32_bf16 v[98:101], v[186:189], v[202:205], v[98:101]
	v_mfma_f32_16x16x32_bf16 v[90:93], v[166:169], v[210:213], v[90:93]
	v_mfma_f32_16x16x32_bf16 v[82:85], v[186:189], v[210:213], v[82:85]
	v_mfma_f32_16x16x32_bf16 v[74:77], v[166:169], v[218:221], v[74:77]
	v_mfma_f32_16x16x32_bf16 v[66:69], v[186:189], v[218:221], v[66:69]
	s_setprio 0
	s_barrier
	s_add_i32 s45, s45, s31
	v_lshl_add_u64 v[222:223], s[26:27], 0, v[0:1]
	s_mov_b32 m0, s45
	ds_read_b128 v[190:193], v153 offset:16384
	ds_read_b128 v[194:197], v153 offset:17408
	ds_read_b128 v[198:201], v153 offset:18432
	ds_read_b128 v[202:205], v153 offset:19456
	ds_read_b128 v[206:209], v153 offset:20480
	ds_read_b128 v[210:213], v153 offset:21504
	ds_read_b128 v[214:217], v153 offset:22528
	ds_read_b128 v[218:221], v153 offset:23552
	global_load_lds_dwordx4 v[222:223], off
	s_add_i32 m0, s45, 0x2000
	s_add_u32 s46, s26, 0x80000
	v_lshl_add_u64 v[224:225], s[26:27], 0, v[130:131]
	s_addc_u32 s47, s27, 0
	s_add_i32 s45, s48, s31
	global_load_lds_dwordx4 v[224:225], off
	v_lshl_add_u64 v[226:227], s[46:47], 0, v[0:1]
	s_mov_b32 m0, s45
	v_lshl_add_u64 v[228:229], s[28:29], 0, v[132:133]
	global_load_lds_dwordx4 v[226:227], off
	s_add_i32 m0, s45, 0x2000
	v_lshl_add_u64 v[226:227], s[46:47], 0, v[130:131]
	global_load_lds_dwordx4 v[226:227], off
	s_waitcnt vmcnt(6)
	s_waitcnt lgkmcnt(0)
	s_barrier
; #define PG8_STAGE(bufoff, gbase, voff) do { _Pragma("unroll") for (int _i = 0; _i < 2; ++_i) \
;         __builtin_amdgcn_global_load_lds((const unsigned*)((const char*)(gbase) + (voff)[_i]), (PG8_LAS unsigned*)(lds + (bufoff) + ldsw + _i * 8192), 16, 0, 0); } while (0)
; #define PG8_LDA(dst, b, h) do { _Pragma("unroll") for (int m = 0; m < 4; ++m) _Pragma("unroll") for (int k = 0; k < 2; ++k) dst[m][k] = *(const PG8_LAS bf16x8*)(lds + PG8_SA(b, h) + aoff + m * 2048 + k * 1024); } while (0)
; #define PG8_LDB(dst, b, h) do { _Pragma("unroll") for (int n = 0; n < 2; ++n) _Pragma("unroll") for (int k = 0; k < 2; ++k) dst[n][k] = *(const PG8_LAS bf16x8*)(lds + PG8_SB(b, h) + boff + n * 2048 + k * 1024); } while (0)
; #define PG8_MMA(ai, bj, At, Bt) do { __builtin_amdgcn_s_setprio(1); _Pragma("unroll") for (int m = 0; m < 4; ++m) _Pragma("unroll") for (int n = 0; n < 2; ++n) _Pragma("unroll") for (int k = 0; k < 2; ++k) \
;         acc[ai][bj][m][n] = __builtin_amdgcn_mfma_f32_16x16x32_bf16(Bt[n][k], At[m][k], acc[ai][bj][m][n], 0, 0, 0); __builtin_amdgcn_s_setprio(0); } while (0)
; #define PG8_WAIT_V(n) asm volatile("s_waitcnt vmcnt(" #n ")" ::: "memory")
; #define PG8_WAIT_L(n) asm volatile("s_waitcnt lgkmcnt(" #n ")" ::: "memory")
; #define PG8_BAR __builtin_amdgcn_s_barrier()
; #define PG8_SCHED __builtin_amdgcn_sched_barrier(0)
; template <class Epi, class Sched, bool ALIGN_EPI = false, bool SP2 = false>
; __device__ __forceinline__ void gemm_phase(PG8_LAS unsigned char* lds, const Gemm g, const Sched& S, const Epi& E, int tid_in) {
;     ...
;             PG8_WAIT_V(8); PG8_WAIT_L(0); PG8_BAR; PG8_MMA(1, 0, At, B0); PG8_MMA(1, 1, At, B1); PG8_BAR; PG8_SCHED;
;             PG8_LDB(B0, 1, 0); PG8_LDB(B1, 1, 1); PG8_SCHED; PG8_LDA(At, 1, 0); PG8_STAGE(PG8_SA(0, 1), a2 + hstepA, voffA);
;             PG8_WAIT_V(8); PG8_WAIT_L(0); PG8_BAR; PG8_MMA(0, 0, At, B0); PG8_MMA(0, 1, At, B1); PG8_BAR; PG8_SCHED;
	s_setprio 1
	s_waitcnt lgkmcnt(0)
	v_mfma_f32_16x16x32_bf16 v[62:65], v[142:145], v[190:193], v[62:65]
	v_mfma_f32_16x16x32_bf16 v[54:57], v[154:157], v[190:193], v[54:57]
	v_mfma_f32_16x16x32_bf16 v[46:49], v[142:145], v[198:201], v[46:49]
	v_mfma_f32_16x16x32_bf16 v[38:41], v[154:157], v[198:201], v[38:41]
	v_mfma_f32_16x16x32_bf16 v[30:33], v[142:145], v[206:209], v[30:33]
	v_mfma_f32_16x16x32_bf16 v[22:25], v[154:157], v[206:209], v[22:25]
	v_mfma_f32_16x16x32_bf16 v[14:17], v[142:145], v[214:217], v[14:17]
	v_mfma_f32_16x16x32_bf16 v[6:9], v[154:157], v[214:217], v[6:9]
	v_mfma_f32_16x16x32_bf16 v[62:65], v[146:149], v[194:197], v[62:65]
	v_mfma_f32_16x16x32_bf16 v[54:57], v[158:161], v[194:197], v[54:57]
	v_mfma_f32_16x16x32_bf16 v[46:49], v[146:149], v[202:205], v[46:49]
	v_mfma_f32_16x16x32_bf16 v[38:41], v[158:161], v[202:205], v[38:41]
	v_mfma_f32_16x16x32_bf16 v[30:33], v[146:149], v[210:213], v[30:33]
	v_mfma_f32_16x16x32_bf16 v[22:25], v[158:161], v[210:213], v[22:25]
	v_mfma_f32_16x16x32_bf16 v[14:17], v[146:149], v[218:221], v[14:17]
	v_mfma_f32_16x16x32_bf16 v[6:9], v[158:161], v[218:221], v[6:9]
	s_setprio 0
	s_setprio 1
	v_mfma_f32_16x16x32_bf16 v[58:61], v[162:165], v[190:193], v[58:61]
	v_mfma_f32_16x16x32_bf16 v[50:53], v[182:185], v[190:193], v[50:53]
	v_mfma_f32_16x16x32_bf16 v[42:45], v[162:165], v[198:201], v[42:45]
	v_mfma_f32_16x16x32_bf16 v[34:37], v[182:185], v[198:201], v[34:37]
	v_mfma_f32_16x16x32_bf16 v[26:29], v[162:165], v[206:209], v[26:29]
	v_mfma_f32_16x16x32_bf16 v[18:21], v[182:185], v[206:209], v[18:21]
	v_mfma_f32_16x16x32_bf16 v[10:13], v[162:165], v[214:217], v[10:13]
	v_mfma_f32_16x16x32_bf16 v[2:5], v[182:185], v[214:217], v[2:5]
	v_mfma_f32_16x16x32_bf16 v[58:61], v[166:169], v[194:197], v[58:61]
	v_mfma_f32_16x16x32_bf16 v[50:53], v[186:189], v[194:197], v[50:53]
	v_mfma_f32_16x16x32_bf16 v[42:45], v[166:169], v[202:205], v[42:45]
	v_mfma_f32_16x16x32_bf16 v[34:37], v[186:189], v[202:205], v[34:37]
	v_mfma_f32_16x16x32_bf16 v[26:29], v[166:169], v[210:213], v[26:29]
	v_mfma_f32_16x16x32_bf16 v[18:21], v[186:189], v[210:213], v[18:21]
	v_mfma_f32_16x16x32_bf16 v[10:13], v[166:169], v[218:221], v[10:13]
	v_mfma_f32_16x16x32_bf16 v[2:5], v[186:189], v[218:221], v[2:5]
	s_setprio 0
	s_barrier
	s_mov_b32 m0, s33
	v_lshl_add_u64 v[226:227], s[28:29], 0, v[134:135]
	global_load_lds_dwordx4 v[226:227], off
	s_mov_b32 m0, s34
	s_nop 0
	global_load_lds_dwordx4 v[228:229], off
	s_add_i32 s45, 0, 0x18000
	s_add_i32 s46, 0, 0x1c000
	v_add_u32_e32 v158, s45, v152
	v_add_u32_e32 v186, s46, v152
	ds_read_b128 v[142:145], v158
	ds_read_b128 v[146:149], v158 offset:1024
	ds_read_b128 v[154:157], v158 offset:2048
	ds_read_b128 v[158:161], v158 offset:3072
	ds_read_b128 v[162:165], v186
	ds_read_b128 v[166:169], v186 offset:1024
	ds_read_b128 v[182:185], v186 offset:2048
	ds_read_b128 v[186:189], v186 offset:3072
	s_add_u32 s28, s28, 0x80000
	s_addc_u32 s29, s29, 0
	s_mov_b32 m0, s35
	v_lshl_add_u64 v[240:241], s[28:29], 0, v[134:135]
	ds_read_b128 v[190:193], v153 offset:32768
	ds_read_b128 v[194:197], v153 offset:33792
	ds_read_b128 v[198:201], v153 offset:34816
	ds_read_b128 v[202:205], v153 offset:35840
	ds_read_b128 v[206:209], v153 offset:36864
	ds_read_b128 v[210:213], v153 offset:37888
	ds_read_b128 v[214:217], v153 offset:38912
	ds_read_b128 v[218:221], v153 offset:39936
	global_load_lds_dwordx4 v[240:241], off
	s_mov_b32 m0, s36
	v_lshl_add_u64 v[240:241], s[28:29], 0, v[132:133]
	global_load_lds_dwordx4 v[240:241], off
	s_waitcnt vmcnt(8)
	s_waitcnt lgkmcnt(0)
	s_barrier
	s_setprio 1
	s_waitcnt lgkmcnt(0)
	v_mfma_f32_16x16x32_bf16 v[126:129], v[142:145], v[190:193], v[126:129]
	v_mfma_f32_16x16x32_bf16 v[118:121], v[154:157], v[190:193], v[118:121]
	v_mfma_f32_16x16x32_bf16 v[110:113], v[142:145], v[198:201], v[110:113]
	v_mfma_f32_16x16x32_bf16 v[102:105], v[154:157], v[198:201], v[102:105]
	v_mfma_f32_16x16x32_bf16 v[94:97], v[142:145], v[206:209], v[94:97]
	v_mfma_f32_16x16x32_bf16 v[86:89], v[154:157], v[206:209], v[86:89]
	v_mfma_f32_16x16x32_bf16 v[78:81], v[142:145], v[214:217], v[78:81]
	v_mfma_f32_16x16x32_bf16 v[70:73], v[154:157], v[214:217], v[70:73]
	v_mfma_f32_16x16x32_bf16 v[126:129], v[146:149], v[194:197], v[126:129]
	v_mfma_f32_16x16x32_bf16 v[118:121], v[158:161], v[194:197], v[118:121]
	v_mfma_f32_16x16x32_bf16 v[110:113], v[146:149], v[202:205], v[110:113]
	v_mfma_f32_16x16x32_bf16 v[102:105], v[158:161], v[202:205], v[102:105]
	v_mfma_f32_16x16x32_bf16 v[94:97], v[146:149], v[210:213], v[94:97]
	v_mfma_f32_16x16x32_bf16 v[86:89], v[158:161], v[210:213], v[86:89]
	v_mfma_f32_16x16x32_bf16 v[78:81], v[146:149], v[218:221], v[78:81]
	v_mfma_f32_16x16x32_bf16 v[70:73], v[158:161], v[218:221], v[70:73]
	s_setprio 0
	s_setprio 1
	v_mfma_f32_16x16x32_bf16 v[122:125], v[162:165], v[190:193], v[122:125]
	v_mfma_f32_16x16x32_bf16 v[114:117], v[182:185], v[190:193], v[114:117]
	v_mfma_f32_16x16x32_bf16 v[106:109], v[162:165], v[198:201], v[106:109]
	v_mfma_f32_16x16x32_bf16 v[98:101], v[182:185], v[198:201], v[98:101]
	v_mfma_f32_16x16x32_bf16 v[90:93], v[162:165], v[206:209], v[90:93]
	v_mfma_f32_16x16x32_bf16 v[82:85], v[182:185], v[206:209], v[82:85]
	v_mfma_f32_16x16x32_bf16 v[74:77], v[162:165], v[214:217], v[74:77]
	v_mfma_f32_16x16x32_bf16 v[66:69], v[182:185], v[214:217], v[66:69]
	v_mfma_f32_16x16x32_bf16 v[122:125], v[166:169], v[194:197], v[122:125]
	v_mfma_f32_16x16x32_bf16 v[114:117], v[186:189], v[194:197], v[114:117]
	v_mfma_f32_16x16x32_bf16 v[106:109], v[166:169], v[202:205], v[106:109]
	v_mfma_f32_16x16x32_bf16 v[98:101], v[186:189], v[202:205], v[98:101]
	v_mfma_f32_16x16x32_bf16 v[90:93], v[166:169], v[210:213], v[90:93]
	v_mfma_f32_16x16x32_bf16 v[82:85], v[186:189], v[210:213], v[82:85]
	v_mfma_f32_16x16x32_bf16 v[74:77], v[166:169], v[218:221], v[74:77]
	v_mfma_f32_16x16x32_bf16 v[66:69], v[186:189], v[218:221], v[66:69]
	s_setprio 0
	s_barrier
; #define PG8_STAGE(bufoff, gbase, voff) do { _Pragma("unroll") for (int _i = 0; _i < 2; ++_i) \
;         __builtin_amdgcn_global_load_lds((const unsigned*)((const char*)(gbase) + (voff)[_i]), (PG8_LAS unsigned*)(lds + (bufoff) + ldsw + _i * 8192), 16, 0, 0); } while (0)
; #define PG8_LDA(dst, b, h) do { _Pragma("unroll") for (int m = 0; m < 4; ++m) _Pragma("unroll") for (int k = 0; k < 2; ++k) dst[m][k] = *(const PG8_LAS bf16x8*)(lds + PG8_SA(b, h) + aoff + m * 2048 + k * 1024); } while (0)
; #define PG8_MMA(ai, bj, At, Bt) do { __builtin_amdgcn_s_setprio(1); _Pragma("unroll") for (int m = 0; m < 4; ++m) _Pragma("unroll") for (int n = 0; n < 2; ++n) _Pragma("unroll") for (int k = 0; k < 2; ++k) \
;         acc[ai][bj][m][n] = __builtin_amdgcn_mfma_f32_16x16x32_bf16(Bt[n][k], At[m][k], acc[ai][bj][m][n], 0, 0, 0); __builtin_amdgcn_s_setprio(0); } while (0)
; #define PG8_WAIT_V(n) asm volatile("s_waitcnt vmcnt(" #n ")" ::: "memory")
; #define PG8_WAIT_L(n) asm volatile("s_waitcnt lgkmcnt(" #n ")" ::: "memory")
; #define PG8_BAR __builtin_amdgcn_s_barrier()
; #define PG8_SCHED __builtin_amdgcn_sched_barrier(0)
; template <class Epi, class Sched, bool ALIGN_EPI = false, bool SP2 = false>
; __device__ __forceinline__ void gemm_phase(PG8_LAS unsigned char* lds, const Gemm g, const Sched& S, const Epi& E, int tid_in) {
;     ...
;             PG8_LDA(At, 1, 1); PG8_STAGE(PG8_SB(1, 0), b3, voffB); PG8_STAGE(PG8_SB(1, 1), b3 + hstep, voffB); PG8_STAGE(PG8_SA(1, 0), a3, voffA);
;             PG8_WAIT_V(8); PG8_WAIT_L(0); PG8_BAR; PG8_MMA(1, 0, At, B0); PG8_MMA(1, 1, At, B1); PG8_BAR; PG8_SCHED;
	s_add_i32 s28, s45, s31
	v_lshl_add_u64 v[222:223], v[222:223], 0, s[90:91]
	s_mov_b32 m0, s28
	ds_read_b128 v[190:193], v153 offset:49152
	ds_read_b128 v[194:197], v153 offset:50176
	ds_read_b128 v[198:201], v153 offset:51200
	ds_read_b128 v[202:205], v153 offset:52224
	ds_read_b128 v[206:209], v153 offset:53248
	ds_read_b128 v[210:213], v153 offset:54272
	ds_read_b128 v[214:217], v153 offset:55296
	ds_read_b128 v[218:221], v153 offset:56320
	global_load_lds_dwordx4 v[222:223], off
	s_add_i32 m0, s28, 0x2000
	s_add_u32 s26, s26, 0x80080
	v_lshl_add_u64 v[222:223], v[224:225], 0, s[90:91]
	s_addc_u32 s27, s27, 0
	s_add_i32 s28, s46, s31
	global_load_lds_dwordx4 v[222:223], off
	s_mov_b32 m0, s28
	v_lshl_add_u64 v[222:223], s[26:27], 0, v[0:1]
	global_load_lds_dwordx4 v[222:223], off
	s_add_i32 m0, s28, 0x2000
	v_lshl_add_u64 v[222:223], s[26:27], 0, v[130:131]
	global_load_lds_dwordx4 v[222:223], off
	s_mov_b32 m0, s39
	v_lshl_add_u64 v[222:223], v[226:227], 0, s[90:91]
	global_load_lds_dwordx4 v[222:223], off
	s_mov_b32 m0, s40
	v_lshl_add_u64 v[222:223], v[228:229], 0, s[90:91]
	global_load_lds_dwordx4 v[222:223], off
	s_add_i32 s23, s23, 2
	s_add_u32 s24, s24, 0x100
	s_addc_u32 s25, s25, 0
	s_add_u32 s15, s15, 0x100
	s_addc_u32 s17, s17, 0
	s_cmp_gt_u32 s23, 29
	s_waitcnt vmcnt(8)
	s_waitcnt lgkmcnt(0)
	s_barrier
	s_setprio 1
	s_waitcnt lgkmcnt(0)
	v_mfma_f32_16x16x32_bf16 v[62:65], v[142:145], v[190:193], v[62:65]
	v_mfma_f32_16x16x32_bf16 v[54:57], v[154:157], v[190:193], v[54:57]
	v_mfma_f32_16x16x32_bf16 v[46:49], v[142:145], v[198:201], v[46:49]
	v_mfma_f32_16x16x32_bf16 v[38:41], v[154:157], v[198:201], v[38:41]
	v_mfma_f32_16x16x32_bf16 v[30:33], v[142:145], v[206:209], v[30:33]
	v_mfma_f32_16x16x32_bf16 v[22:25], v[154:157], v[206:209], v[22:25]
	v_mfma_f32_16x16x32_bf16 v[14:17], v[142:145], v[214:217], v[14:17]
	v_mfma_f32_16x16x32_bf16 v[6:9], v[154:157], v[214:217], v[6:9]
	v_mfma_f32_16x16x32_bf16 v[62:65], v[146:149], v[194:197], v[62:65]
	v_mfma_f32_16x16x32_bf16 v[54:57], v[158:161], v[194:197], v[54:57]
	v_mfma_f32_16x16x32_bf16 v[46:49], v[146:149], v[202:205], v[46:49]
	v_mfma_f32_16x16x32_bf16 v[38:41], v[158:161], v[202:205], v[38:41]
	v_mfma_f32_16x16x32_bf16 v[30:33], v[146:149], v[210:213], v[30:33]
	v_mfma_f32_16x16x32_bf16 v[22:25], v[158:161], v[210:213], v[22:25]
	v_mfma_f32_16x16x32_bf16 v[14:17], v[146:149], v[218:221], v[14:17]
	v_mfma_f32_16x16x32_bf16 v[6:9], v[158:161], v[218:221], v[6:9]
	s_setprio 0
	s_setprio 1
	v_mfma_f32_16x16x32_bf16 v[58:61], v[162:165], v[190:193], v[58:61]
	v_mfma_f32_16x16x32_bf16 v[50:53], v[182:185], v[190:193], v[50:53]
	v_mfma_f32_16x16x32_bf16 v[42:45], v[162:165], v[198:201], v[42:45]
	v_mfma_f32_16x16x32_bf16 v[34:37], v[182:185], v[198:201], v[34:37]
	v_mfma_f32_16x16x32_bf16 v[26:29], v[162:165], v[206:209], v[26:29]
	v_mfma_f32_16x16x32_bf16 v[18:21], v[182:185], v[206:209], v[18:21]
	v_mfma_f32_16x16x32_bf16 v[10:13], v[162:165], v[214:217], v[10:13]
	v_mfma_f32_16x16x32_bf16 v[2:5], v[182:185], v[214:217], v[2:5]
	v_mfma_f32_16x16x32_bf16 v[58:61], v[166:169], v[194:197], v[58:61]
	v_mfma_f32_16x16x32_bf16 v[50:53], v[186:189], v[194:197], v[50:53]
	v_mfma_f32_16x16x32_bf16 v[42:45], v[166:169], v[202:205], v[42:45]
	v_mfma_f32_16x16x32_bf16 v[34:37], v[186:189], v[202:205], v[34:37]
	v_mfma_f32_16x16x32_bf16 v[26:29], v[166:169], v[210:213], v[26:29]
	v_mfma_f32_16x16x32_bf16 v[18:21], v[186:189], v[210:213], v[18:21]
	v_mfma_f32_16x16x32_bf16 v[10:13], v[166:169], v[218:221], v[10:13]
	v_mfma_f32_16x16x32_bf16 v[2:5], v[186:189], v[218:221], v[2:5]
	s_setprio 0
	s_barrier
	s_cbranch_scc0 .LBB0_282
	s_and_b64 vcc, exec, s[12:13]
	s_cbranch_vccz .LBB0_285
	s_barrier

; #define PG8_STAGE(bufoff, gbase, voff) do { _Pragma("unroll") for (int _i = 0; _i < 2; ++_i) \
;         __builtin_amdgcn_global_load_lds((const unsigned*)((const char*)(gbase) + (voff)[_i]), (PG8_LAS unsigned*)(lds + (bufoff) + ldsw + _i * 8192), 16, 0, 0); } while (0)
; #define PG8_LDA(dst, b, h) do { _Pragma("unroll") for (int m = 0; m < 4; ++m) _Pragma("unroll") for (int k = 0; k < 2; ++k) dst[m][k] = *(const PG8_LAS bf16x8*)(lds + PG8_SA(b, h) + aoff + m * 2048 + k * 1024); } while (0)
; #define PG8_LDB(dst, b, h) do { _Pragma("unroll") for (int n = 0; n < 2; ++n) _Pragma("unroll") for (int k = 0; k < 2; ++k) dst[n][k] = *(const PG8_LAS bf16x8*)(lds + PG8_SB(b, h) + boff + n * 2048 + k * 1024); } while (0)
; #define PG8_MMA(ai, bj, At, Bt) do { __builtin_amdgcn_s_setprio(1); _Pragma("unroll") for (int m = 0; m < 4; ++m) _Pragma("unroll") for (int n = 0; n < 2; ++n) _Pragma("unroll") for (int k = 0; k < 2; ++k) \
;         acc[ai][bj][m][n] = __builtin_amdgcn_mfma_f32_16x16x32_bf16(Bt[n][k], At[m][k], acc[ai][bj][m][n], 0, 0, 0); __builtin_amdgcn_s_setprio(0); } while (0)
; #define PG8_WAIT_V(n) asm volatile("s_waitcnt vmcnt(" #n ")" ::: "memory")
; #define PG8_BAR __builtin_amdgcn_s_barrier()
; template <class Epi, class Sched, bool ALIGN_EPI = false, bool SP2 = false>
; __device__ __forceinline__ void gemm_phase(PG8_LAS unsigned char* lds, const Gemm g, const Sched& S, const Epi& E, int tid_in) {
;     ...
;         for (int t = 0; t < nt; t += 2) {
;             const bool last = (t == nt - 2);
;             const char* a1 = cA + (size_t)(t + 1) * kstep;
;             const char* a2 = last ? nA : cA + (size_t)(t + 2) * kstep; const char* b2 = last ? nB : cB + (size_t)(t + 2) * kstep;
;             const char* a3 = a2 + kstep; const char* b3 = b2 + kstep;
;             if (last && has_next) S.a_ready(nxt);
;             if constexpr (SP2) {
;             PG8_LDB(B0, 0, 0); PG8_LDB(B1, 0, 1); PG8_SCHED; PG8_LDA(At, 0, 0); PG8_STAGE(PG8_SA(1, 1), a1 + hstepA, voffA);
;             PG8_WAIT_V(8); PG8_WAIT_L(0); PG8_BAR; PG8_MMA(0, 0, At, B0); PG8_MMA(0, 1, At, B1); PG8_BAR; PG8_SCHED;
;             PG8_LDA(At, 0, 1); PG8_STAGE(PG8_SB(0, 0), b2, voffB); PG8_STAGE(PG8_SB(0, 1), b2 + hstep, voffB); PG8_STAGE(PG8_SA(0, 0), a2, voffA);
;             PG8_WAIT_V(8); PG8_WAIT_L(0); PG8_BAR; PG8_MMA(1, 0, At, B0); PG8_MMA(1, 1, At, B1); PG8_BAR; PG8_SCHED;
.LBB0_352:
	s_add_i32 s82, s28, 2
	s_add_u32 s26, s8, 0x100
	s_addc_u32 s27, s9, 0
	s_add_i32 s4, 0, 0x10000
	s_cmp_eq_u32 s70, s28
	s_cselect_b32 s31, s46, s27
	s_cselect_b32 s30, s47, s26
	s_cselect_b32 s29, s67, s79
	s_cselect_b32 s28, s68, s76
	s_add_i32 s5, 0, 0x14000
	v_add_u32_e32 v152, s4, v146
	v_add_u32_e32 v168, s5, v146
	ds_read_b128 v[136:139], v152
	ds_read_b128 v[140:143], v152 offset:1024
	ds_read_b128 v[148:151], v152 offset:2048
	ds_read_b128 v[152:155], v152 offset:3072
	ds_read_b128 v[156:159], v168
	ds_read_b128 v[160:163], v168 offset:1024
	ds_read_b128 v[164:167], v168 offset:2048
	ds_read_b128 v[182:185], v168 offset:3072
	v_lshl_add_u64 v[168:169], s[8:9], 0, v[132:133]
	s_add_i32 m0, s34, 0xc000
	ds_read_b128 v[186:189], v147
	ds_read_b128 v[190:193], v147 offset:1024
	ds_read_b128 v[194:197], v147 offset:2048
	ds_read_b128 v[198:201], v147 offset:3072
	ds_read_b128 v[202:205], v147 offset:4096
	ds_read_b128 v[206:209], v147 offset:5120
	ds_read_b128 v[210:213], v147 offset:6144
	ds_read_b128 v[214:217], v147 offset:7168
	global_load_lds_dwordx4 v[168:169], off
	s_add_i32 m0, s34, 0xe000
	v_lshl_add_u64 v[168:169], s[8:9], 0, v[134:135]
	global_load_lds_dwordx4 v[168:169], off
	s_waitcnt vmcnt(8)
	s_waitcnt lgkmcnt(0)
	s_barrier
	s_setprio 1
	s_waitcnt lgkmcnt(0)
	v_mfma_f32_16x16x32_bf16 v[126:129], v[136:139], v[186:189], v[126:129]
	v_mfma_f32_16x16x32_bf16 v[122:125], v[148:151], v[186:189], v[122:125]
	v_mfma_f32_16x16x32_bf16 v[118:121], v[136:139], v[194:197], v[118:121]
	v_mfma_f32_16x16x32_bf16 v[114:117], v[148:151], v[194:197], v[114:117]
	v_mfma_f32_16x16x32_bf16 v[110:113], v[136:139], v[202:205], v[110:113]
	v_mfma_f32_16x16x32_bf16 v[106:109], v[148:151], v[202:205], v[106:109]
	v_mfma_f32_16x16x32_bf16 v[102:105], v[136:139], v[210:213], v[102:105]
	v_mfma_f32_16x16x32_bf16 v[98:101], v[148:151], v[210:213], v[98:101]
	v_mfma_f32_16x16x32_bf16 v[126:129], v[140:143], v[190:193], v[126:129]
	v_mfma_f32_16x16x32_bf16 v[122:125], v[152:155], v[190:193], v[122:125]
	v_mfma_f32_16x16x32_bf16 v[118:121], v[140:143], v[198:201], v[118:121]
	v_mfma_f32_16x16x32_bf16 v[114:117], v[152:155], v[198:201], v[114:117]
	v_mfma_f32_16x16x32_bf16 v[110:113], v[140:143], v[206:209], v[110:113]
	v_mfma_f32_16x16x32_bf16 v[106:109], v[152:155], v[206:209], v[106:109]
	v_mfma_f32_16x16x32_bf16 v[102:105], v[140:143], v[214:217], v[102:105]
	v_mfma_f32_16x16x32_bf16 v[98:101], v[152:155], v[214:217], v[98:101]
	s_setprio 0
	s_setprio 1
	v_mfma_f32_16x16x32_bf16 v[94:97], v[156:159], v[186:189], v[94:97]
	v_mfma_f32_16x16x32_bf16 v[90:93], v[164:167], v[186:189], v[90:93]
	v_mfma_f32_16x16x32_bf16 v[86:89], v[156:159], v[194:197], v[86:89]
	v_mfma_f32_16x16x32_bf16 v[82:85], v[164:167], v[194:197], v[82:85]
	v_mfma_f32_16x16x32_bf16 v[78:81], v[156:159], v[202:205], v[78:81]
	v_mfma_f32_16x16x32_bf16 v[74:77], v[164:167], v[202:205], v[74:77]
	v_mfma_f32_16x16x32_bf16 v[70:73], v[156:159], v[210:213], v[70:73]
	v_mfma_f32_16x16x32_bf16 v[66:69], v[164:167], v[210:213], v[66:69]
	v_mfma_f32_16x16x32_bf16 v[94:97], v[160:163], v[190:193], v[94:97]
	v_mfma_f32_16x16x32_bf16 v[90:93], v[182:185], v[190:193], v[90:93]
	v_mfma_f32_16x16x32_bf16 v[86:89], v[160:163], v[198:201], v[86:89]
	v_mfma_f32_16x16x32_bf16 v[82:85], v[182:185], v[198:201], v[82:85]
	v_mfma_f32_16x16x32_bf16 v[78:81], v[160:163], v[206:209], v[78:81]
	v_mfma_f32_16x16x32_bf16 v[74:77], v[182:185], v[206:209], v[74:77]
	v_mfma_f32_16x16x32_bf16 v[70:73], v[160:163], v[214:217], v[70:73]
	v_mfma_f32_16x16x32_bf16 v[66:69], v[182:185], v[214:217], v[66:69]
	s_setprio 0
	s_barrier
	s_add_i32 s8, s4, s33
	v_lshl_add_u64 v[168:169], s[28:29], 0, v[0:1]
	s_mov_b32 m0, s8
	ds_read_b128 v[186:189], v147 offset:16384
	ds_read_b128 v[190:193], v147 offset:17408
	ds_read_b128 v[194:197], v147 offset:18432
	ds_read_b128 v[198:201], v147 offset:19456
	ds_read_b128 v[202:205], v147 offset:20480
	ds_read_b128 v[206:209], v147 offset:21504
	ds_read_b128 v[210:213], v147 offset:22528
	ds_read_b128 v[214:217], v147 offset:23552
	global_load_lds_dwordx4 v[168:169], off
	s_add_i32 m0, s8, 0x2000
	s_add_u32 s8, s28, 0x160000
	v_lshl_add_u64 v[218:219], s[28:29], 0, v[130:131]
	s_addc_u32 s9, s29, 0
	s_add_i32 s55, s5, s33
	global_load_lds_dwordx4 v[218:219], off
	v_lshl_add_u64 v[220:221], s[8:9], 0, v[0:1]
	s_mov_b32 m0, s55
	v_lshl_add_u64 v[222:223], s[30:31], 0, v[130:131]
	global_load_lds_dwordx4 v[220:221], off
	s_add_i32 m0, s55, 0x2000
	v_lshl_add_u64 v[220:221], s[8:9], 0, v[130:131]
	global_load_lds_dwordx4 v[220:221], off
	s_waitcnt vmcnt(6)
	s_waitcnt lgkmcnt(0)
	s_barrier
; #define PG8_STAGE(bufoff, gbase, voff) do { _Pragma("unroll") for (int _i = 0; _i < 2; ++_i) \
;         __builtin_amdgcn_global_load_lds((const unsigned*)((const char*)(gbase) + (voff)[_i]), (PG8_LAS unsigned*)(lds + (bufoff) + ldsw + _i * 8192), 16, 0, 0); } while (0)
; #define PG8_LDA(dst, b, h) do { _Pragma("unroll") for (int m = 0; m < 4; ++m) _Pragma("unroll") for (int k = 0; k < 2; ++k) dst[m][k] = *(const PG8_LAS bf16x8*)(lds + PG8_SA(b, h) + aoff + m * 2048 + k * 1024); } while (0)
; #define PG8_LDB(dst, b, h) do { _Pragma("unroll") for (int n = 0; n < 2; ++n) _Pragma("unroll") for (int k = 0; k < 2; ++k) dst[n][k] = *(const PG8_LAS bf16x8*)(lds + PG8_SB(b, h) + boff + n * 2048 + k * 1024); } while (0)
; #define PG8_MMA(ai, bj, At, Bt) do { __builtin_amdgcn_s_setprio(1); _Pragma("unroll") for (int m = 0; m < 4; ++m) _Pragma("unroll") for (int n = 0; n < 2; ++n) _Pragma("unroll") for (int k = 0; k < 2; ++k) \
;         acc[ai][bj][m][n] = __builtin_amdgcn_mfma_f32_16x16x32_bf16(Bt[n][k], At[m][k], acc[ai][bj][m][n], 0, 0, 0); __builtin_amdgcn_s_setprio(0); } while (0)
; #define PG8_WAIT_V(n) asm volatile("s_waitcnt vmcnt(" #n ")" ::: "memory")
; #define PG8_WAIT_L(n) asm volatile("s_waitcnt lgkmcnt(" #n ")" ::: "memory")
; #define PG8_BAR __builtin_amdgcn_s_barrier()
; #define PG8_SCHED __builtin_amdgcn_sched_barrier(0)
; template <class Epi, class Sched, bool ALIGN_EPI = false, bool SP2 = false>
; __device__ __forceinline__ void gemm_phase(PG8_LAS unsigned char* lds, const Gemm g, const Sched& S, const Epi& E, int tid_in) {
;     ...
;             PG8_WAIT_V(8); PG8_WAIT_L(0); PG8_BAR; PG8_MMA(1, 0, At, B0); PG8_MMA(1, 1, At, B1); PG8_BAR; PG8_SCHED;
;             PG8_LDB(B0, 1, 0); PG8_LDB(B1, 1, 1); PG8_SCHED; PG8_LDA(At, 1, 0); PG8_STAGE(PG8_SA(0, 1), a2 + hstepA, voffA);
;             PG8_WAIT_V(8); PG8_WAIT_L(0); PG8_BAR; PG8_MMA(0, 0, At, B0); PG8_MMA(0, 1, At, B1); PG8_BAR; PG8_SCHED;
	s_setprio 1
	s_waitcnt lgkmcnt(0)
	v_mfma_f32_16x16x32_bf16 v[62:65], v[136:139], v[186:189], v[62:65]
	v_mfma_f32_16x16x32_bf16 v[58:61], v[148:151], v[186:189], v[58:61]
	v_mfma_f32_16x16x32_bf16 v[54:57], v[136:139], v[194:197], v[54:57]
	v_mfma_f32_16x16x32_bf16 v[50:53], v[148:151], v[194:197], v[50:53]
	v_mfma_f32_16x16x32_bf16 v[46:49], v[136:139], v[202:205], v[46:49]
	v_mfma_f32_16x16x32_bf16 v[42:45], v[148:151], v[202:205], v[42:45]
	v_mfma_f32_16x16x32_bf16 v[38:41], v[136:139], v[210:213], v[38:41]
	v_mfma_f32_16x16x32_bf16 v[34:37], v[148:151], v[210:213], v[34:37]
	v_mfma_f32_16x16x32_bf16 v[62:65], v[140:143], v[190:193], v[62:65]
	v_mfma_f32_16x16x32_bf16 v[58:61], v[152:155], v[190:193], v[58:61]
	v_mfma_f32_16x16x32_bf16 v[54:57], v[140:143], v[198:201], v[54:57]
	v_mfma_f32_16x16x32_bf16 v[50:53], v[152:155], v[198:201], v[50:53]
	v_mfma_f32_16x16x32_bf16 v[46:49], v[140:143], v[206:209], v[46:49]
	v_mfma_f32_16x16x32_bf16 v[42:45], v[152:155], v[206:209], v[42:45]
	v_mfma_f32_16x16x32_bf16 v[38:41], v[140:143], v[214:217], v[38:41]
	v_mfma_f32_16x16x32_bf16 v[34:37], v[152:155], v[214:217], v[34:37]
	s_setprio 0
	s_setprio 1
	v_mfma_f32_16x16x32_bf16 v[30:33], v[156:159], v[186:189], v[30:33]
	v_mfma_f32_16x16x32_bf16 v[26:29], v[164:167], v[186:189], v[26:29]
	v_mfma_f32_16x16x32_bf16 v[22:25], v[156:159], v[194:197], v[22:25]
	v_mfma_f32_16x16x32_bf16 v[18:21], v[164:167], v[194:197], v[18:21]
	v_mfma_f32_16x16x32_bf16 v[14:17], v[156:159], v[202:205], v[14:17]
	v_mfma_f32_16x16x32_bf16 v[10:13], v[164:167], v[202:205], v[10:13]
	v_mfma_f32_16x16x32_bf16 v[6:9], v[156:159], v[210:213], v[6:9]
	v_mfma_f32_16x16x32_bf16 v[2:5], v[164:167], v[210:213], v[2:5]
	v_mfma_f32_16x16x32_bf16 v[30:33], v[160:163], v[190:193], v[30:33]
	v_mfma_f32_16x16x32_bf16 v[26:29], v[182:185], v[190:193], v[26:29]
	v_mfma_f32_16x16x32_bf16 v[22:25], v[160:163], v[198:201], v[22:25]
	v_mfma_f32_16x16x32_bf16 v[18:21], v[182:185], v[198:201], v[18:21]
	v_mfma_f32_16x16x32_bf16 v[14:17], v[160:163], v[206:209], v[14:17]
	v_mfma_f32_16x16x32_bf16 v[10:13], v[182:185], v[206:209], v[10:13]
	v_mfma_f32_16x16x32_bf16 v[6:9], v[160:163], v[214:217], v[6:9]
	v_mfma_f32_16x16x32_bf16 v[2:5], v[182:185], v[214:217], v[2:5]
	s_setprio 0
	s_barrier
	s_mov_b32 m0, s34
	v_lshl_add_u64 v[220:221], s[30:31], 0, v[0:1]
	global_load_lds_dwordx4 v[220:221], off
	s_mov_b32 m0, s35
	s_nop 0
	global_load_lds_dwordx4 v[222:223], off
	s_add_i32 s63, 0, 0x18000
	s_add_i32 s55, 0, 0x1c000
	v_add_u32_e32 v152, s63, v146
	v_add_u32_e32 v182, s55, v146
	ds_read_b128 v[136:139], v152
	ds_read_b128 v[140:143], v152 offset:1024
	ds_read_b128 v[148:151], v152 offset:2048
	ds_read_b128 v[152:155], v152 offset:3072
	ds_read_b128 v[156:159], v182
	ds_read_b128 v[160:163], v182 offset:1024
	ds_read_b128 v[164:167], v182 offset:2048
	ds_read_b128 v[182:185], v182 offset:3072
	s_add_u32 s8, s30, 0x160000
	s_addc_u32 s9, s31, 0
	s_mov_b32 m0, s36
	v_lshl_add_u64 v[224:225], s[8:9], 0, v[0:1]
	ds_read_b128 v[186:189], v147 offset:32768
	ds_read_b128 v[190:193], v147 offset:33792
	ds_read_b128 v[194:197], v147 offset:34816
	ds_read_b128 v[198:201], v147 offset:35840
	ds_read_b128 v[202:205], v147 offset:36864
	ds_read_b128 v[206:209], v147 offset:37888
	ds_read_b128 v[210:213], v147 offset:38912
	ds_read_b128 v[214:217], v147 offset:39936
	global_load_lds_dwordx4 v[224:225], off
	s_mov_b32 m0, s37
	v_lshl_add_u64 v[224:225], s[8:9], 0, v[130:131]
	global_load_lds_dwordx4 v[224:225], off
	s_waitcnt vmcnt(8)
	s_waitcnt lgkmcnt(0)
	s_barrier
	s_setprio 1
	s_waitcnt lgkmcnt(0)
	v_mfma_f32_16x16x32_bf16 v[126:129], v[136:139], v[186:189], v[126:129]
	v_mfma_f32_16x16x32_bf16 v[122:125], v[148:151], v[186:189], v[122:125]
	v_mfma_f32_16x16x32_bf16 v[118:121], v[136:139], v[194:197], v[118:121]
	v_mfma_f32_16x16x32_bf16 v[114:117], v[148:151], v[194:197], v[114:117]
	v_mfma_f32_16x16x32_bf16 v[110:113], v[136:139], v[202:205], v[110:113]
	v_mfma_f32_16x16x32_bf16 v[106:109], v[148:151], v[202:205], v[106:109]
	v_mfma_f32_16x16x32_bf16 v[102:105], v[136:139], v[210:213], v[102:105]
	v_mfma_f32_16x16x32_bf16 v[98:101], v[148:151], v[210:213], v[98:101]
	v_mfma_f32_16x16x32_bf16 v[126:129], v[140:143], v[190:193], v[126:129]
	v_mfma_f32_16x16x32_bf16 v[122:125], v[152:155], v[190:193], v[122:125]
	v_mfma_f32_16x16x32_bf16 v[118:121], v[140:143], v[198:201], v[118:121]
	v_mfma_f32_16x16x32_bf16 v[114:117], v[152:155], v[198:201], v[114:117]
	v_mfma_f32_16x16x32_bf16 v[110:113], v[140:143], v[206:209], v[110:113]
	v_mfma_f32_16x16x32_bf16 v[106:109], v[152:155], v[206:209], v[106:109]
	v_mfma_f32_16x16x32_bf16 v[102:105], v[140:143], v[214:217], v[102:105]
	v_mfma_f32_16x16x32_bf16 v[98:101], v[152:155], v[214:217], v[98:101]
	s_setprio 0
	s_setprio 1
	v_mfma_f32_16x16x32_bf16 v[94:97], v[156:159], v[186:189], v[94:97]
	v_mfma_f32_16x16x32_bf16 v[90:93], v[164:167], v[186:189], v[90:93]
	v_mfma_f32_16x16x32_bf16 v[86:89], v[156:159], v[194:197], v[86:89]
	v_mfma_f32_16x16x32_bf16 v[82:85], v[164:167], v[194:197], v[82:85]
	v_mfma_f32_16x16x32_bf16 v[78:81], v[156:159], v[202:205], v[78:81]
	v_mfma_f32_16x16x32_bf16 v[74:77], v[164:167], v[202:205], v[74:77]
	v_mfma_f32_16x16x32_bf16 v[70:73], v[156:159], v[210:213], v[70:73]
	v_mfma_f32_16x16x32_bf16 v[66:69], v[164:167], v[210:213], v[66:69]
	v_mfma_f32_16x16x32_bf16 v[94:97], v[160:163], v[190:193], v[94:97]
	v_mfma_f32_16x16x32_bf16 v[90:93], v[182:185], v[190:193], v[90:93]
	v_mfma_f32_16x16x32_bf16 v[86:89], v[160:163], v[198:201], v[86:89]
	v_mfma_f32_16x16x32_bf16 v[82:85], v[182:185], v[198:201], v[82:85]
	v_mfma_f32_16x16x32_bf16 v[78:81], v[160:163], v[206:209], v[78:81]
	v_mfma_f32_16x16x32_bf16 v[74:77], v[182:185], v[206:209], v[74:77]
	v_mfma_f32_16x16x32_bf16 v[70:73], v[160:163], v[214:217], v[70:73]
	v_mfma_f32_16x16x32_bf16 v[66:69], v[182:185], v[214:217], v[66:69]
	s_setprio 0
	s_barrier
; #define PG8_STAGE(bufoff, gbase, voff) do { _Pragma("unroll") for (int _i = 0; _i < 2; ++_i) \
;         __builtin_amdgcn_global_load_lds((const unsigned*)((const char*)(gbase) + (voff)[_i]), (PG8_LAS unsigned*)(lds + (bufoff) + ldsw + _i * 8192), 16, 0, 0); } while (0)
; #define PG8_LDA(dst, b, h) do { _Pragma("unroll") for (int m = 0; m < 4; ++m) _Pragma("unroll") for (int k = 0; k < 2; ++k) dst[m][k] = *(const PG8_LAS bf16x8*)(lds + PG8_SA(b, h) + aoff + m * 2048 + k * 1024); } while (0)
; #define PG8_MMA(ai, bj, At, Bt) do { __builtin_amdgcn_s_setprio(1); _Pragma("unroll") for (int m = 0; m < 4; ++m) _Pragma("unroll") for (int n = 0; n < 2; ++n) _Pragma("unroll") for (int k = 0; k < 2; ++k) \
;         acc[ai][bj][m][n] = __builtin_amdgcn_mfma_f32_16x16x32_bf16(Bt[n][k], At[m][k], acc[ai][bj][m][n], 0, 0, 0); __builtin_amdgcn_s_setprio(0); } while (0)
; #define PG8_WAIT_V(n) asm volatile("s_waitcnt vmcnt(" #n ")" ::: "memory")
; #define PG8_WAIT_L(n) asm volatile("s_waitcnt lgkmcnt(" #n ")" ::: "memory")
; #define PG8_BAR __builtin_amdgcn_s_barrier()
; #define PG8_SCHED __builtin_amdgcn_sched_barrier(0)
; template <class Epi, class Sched, bool ALIGN_EPI = false, bool SP2 = false>
; __device__ __forceinline__ void gemm_phase(PG8_LAS unsigned char* lds, const Gemm g, const Sched& S, const Epi& E, int tid_in) {
;     ...
;             PG8_LDA(At, 1, 1); PG8_STAGE(PG8_SB(1, 0), b3, voffB); PG8_STAGE(PG8_SB(1, 1), b3 + hstep, voffB); PG8_STAGE(PG8_SA(1, 0), a3, voffA);
;             PG8_WAIT_V(8); PG8_WAIT_L(0); PG8_BAR; PG8_MMA(1, 0, At, B0); PG8_MMA(1, 1, At, B1); PG8_BAR; PG8_SCHED;
;     ...
;         if constexpr (ALIGN_EPI) { if (wr == 0) PG8_BAR; }
	s_add_i32 s8, s63, s33
	v_lshl_add_u64 v[168:169], v[168:169], 0, s[90:91]
	s_mov_b32 m0, s8
	ds_read_b128 v[186:189], v147 offset:49152
	ds_read_b128 v[190:193], v147 offset:50176
	ds_read_b128 v[194:197], v147 offset:51200
	ds_read_b128 v[198:201], v147 offset:52224
	ds_read_b128 v[202:205], v147 offset:53248
	ds_read_b128 v[206:209], v147 offset:54272
	ds_read_b128 v[210:213], v147 offset:55296
	ds_read_b128 v[214:217], v147 offset:56320
	global_load_lds_dwordx4 v[168:169], off
	s_add_i32 m0, s8, 0x2000
	s_add_u32 s8, s28, 0x160080
	v_lshl_add_u64 v[168:169], v[218:219], 0, s[90:91]
	s_addc_u32 s9, s29, 0
	s_add_i32 s28, s55, s33
	global_load_lds_dwordx4 v[168:169], off
	s_mov_b32 m0, s28
	v_lshl_add_u64 v[168:169], s[8:9], 0, v[0:1]
	global_load_lds_dwordx4 v[168:169], off
	s_add_i32 m0, s28, 0x2000
	v_lshl_add_u64 v[168:169], s[8:9], 0, v[130:131]
	global_load_lds_dwordx4 v[168:169], off
	s_mov_b32 m0, s43
	v_lshl_add_u64 v[168:169], v[220:221], 0, s[90:91]
	global_load_lds_dwordx4 v[168:169], off
	s_mov_b32 m0, s44
	v_lshl_add_u64 v[168:169], v[222:223], 0, s[90:91]
	global_load_lds_dwordx4 v[168:169], off
	s_add_u32 s76, s76, 0x100
	s_addc_u32 s79, s79, 0
	s_cmp_ge_u32 s82, s66
	s_mov_b64 s[8:9], s[26:27]
	s_mov_b32 s28, s82
	s_waitcnt vmcnt(8)
	s_waitcnt lgkmcnt(0)
	s_barrier
	s_setprio 1
	s_waitcnt lgkmcnt(0)
	v_mfma_f32_16x16x32_bf16 v[62:65], v[136:139], v[186:189], v[62:65]
	v_mfma_f32_16x16x32_bf16 v[58:61], v[148:151], v[186:189], v[58:61]
	v_mfma_f32_16x16x32_bf16 v[54:57], v[136:139], v[194:197], v[54:57]
	v_mfma_f32_16x16x32_bf16 v[50:53], v[148:151], v[194:197], v[50:53]
	v_mfma_f32_16x16x32_bf16 v[46:49], v[136:139], v[202:205], v[46:49]
	v_mfma_f32_16x16x32_bf16 v[42:45], v[148:151], v[202:205], v[42:45]
	v_mfma_f32_16x16x32_bf16 v[38:41], v[136:139], v[210:213], v[38:41]
	v_mfma_f32_16x16x32_bf16 v[34:37], v[148:151], v[210:213], v[34:37]
	v_mfma_f32_16x16x32_bf16 v[62:65], v[140:143], v[190:193], v[62:65]
	v_mfma_f32_16x16x32_bf16 v[58:61], v[152:155], v[190:193], v[58:61]
	v_mfma_f32_16x16x32_bf16 v[54:57], v[140:143], v[198:201], v[54:57]
	v_mfma_f32_16x16x32_bf16 v[50:53], v[152:155], v[198:201], v[50:53]
	v_mfma_f32_16x16x32_bf16 v[46:49], v[140:143], v[206:209], v[46:49]
	v_mfma_f32_16x16x32_bf16 v[42:45], v[152:155], v[206:209], v[42:45]
	v_mfma_f32_16x16x32_bf16 v[38:41], v[140:143], v[214:217], v[38:41]
	v_mfma_f32_16x16x32_bf16 v[34:37], v[152:155], v[214:217], v[34:37]
	s_setprio 0
	s_setprio 1
	v_mfma_f32_16x16x32_bf16 v[30:33], v[156:159], v[186:189], v[30:33]
	v_mfma_f32_16x16x32_bf16 v[26:29], v[164:167], v[186:189], v[26:29]
	v_mfma_f32_16x16x32_bf16 v[22:25], v[156:159], v[194:197], v[22:25]
	v_mfma_f32_16x16x32_bf16 v[18:21], v[164:167], v[194:197], v[18:21]
	v_mfma_f32_16x16x32_bf16 v[14:17], v[156:159], v[202:205], v[14:17]
	v_mfma_f32_16x16x32_bf16 v[10:13], v[164:167], v[202:205], v[10:13]
	v_mfma_f32_16x16x32_bf16 v[6:9], v[156:159], v[210:213], v[6:9]
	v_mfma_f32_16x16x32_bf16 v[2:5], v[164:167], v[210:213], v[2:5]
	v_mfma_f32_16x16x32_bf16 v[30:33], v[160:163], v[190:193], v[30:33]
	v_mfma_f32_16x16x32_bf16 v[26:29], v[182:185], v[190:193], v[26:29]
	v_mfma_f32_16x16x32_bf16 v[22:25], v[160:163], v[198:201], v[22:25]
	v_mfma_f32_16x16x32_bf16 v[18:21], v[182:185], v[198:201], v[18:21]
	v_mfma_f32_16x16x32_bf16 v[14:17], v[160:163], v[206:209], v[14:17]
	v_mfma_f32_16x16x32_bf16 v[10:13], v[182:185], v[206:209], v[10:13]
	v_mfma_f32_16x16x32_bf16 v[6:9], v[160:163], v[214:217], v[6:9]
	v_mfma_f32_16x16x32_bf16 v[2:5], v[182:185], v[214:217], v[2:5]
	s_setprio 0
	s_barrier
	s_cbranch_scc0 .LBB0_352
	s_and_b64 vcc, exec, s[18:19]
	s_cbranch_vccz .LBB0_355
	s_barrier

; #define PG8_STAGE(bufoff, gbase, voff) do { _Pragma("unroll") for (int _i = 0; _i < 2; ++_i) \
;         __builtin_amdgcn_global_load_lds((const unsigned*)((const char*)(gbase) + (voff)[_i]), (PG8_LAS unsigned*)(lds + (bufoff) + ldsw + _i * 8192), 16, 0, 0); } while (0)
; #define PG8_LDA(dst, b, h) do { _Pragma("unroll") for (int m = 0; m < 4; ++m) _Pragma("unroll") for (int k = 0; k < 2; ++k) dst[m][k] = *(const PG8_LAS bf16x8*)(lds + PG8_SA(b, h) + aoff + m * 2048 + k * 1024); } while (0)
; #define PG8_LDB(dst, b, h) do { _Pragma("unroll") for (int n = 0; n < 2; ++n) _Pragma("unroll") for (int k = 0; k < 2; ++k) dst[n][k] = *(const PG8_LAS bf16x8*)(lds + PG8_SB(b, h) + boff + n * 2048 + k * 1024); } while (0)
; #define PG8_MMA(ai, bj, At, Bt) do { __builtin_amdgcn_s_setprio(1); _Pragma("unroll") for (int m = 0; m < 4; ++m) _Pragma("unroll") for (int n = 0; n < 2; ++n) _Pragma("unroll") for (int k = 0; k < 2; ++k) \
;         acc[ai][bj][m][n] = __builtin_amdgcn_mfma_f32_16x16x32_bf16(Bt[n][k], At[m][k], acc[ai][bj][m][n], 0, 0, 0); __builtin_amdgcn_s_setprio(0); } while (0)
; #define PG8_WAIT_V(n) asm volatile("s_waitcnt vmcnt(" #n ")" ::: "memory")
; #define PG8_WAIT_L(n) asm volatile("s_waitcnt lgkmcnt(" #n ")" ::: "memory")
; template <class Epi, class Sched, bool ALIGN_EPI = false, bool SP2 = false>
; __device__ __forceinline__ void gemm_phase(PG8_LAS unsigned char* lds, const Gemm g, const Sched& S, const Epi& E, int tid_in) {
;     ...
;             const bool last = (t == nt - 2);
;             const char* a1 = cA + (size_t)(t + 1) * kstep;
;             const char* a2 = last ? nA : cA + (size_t)(t + 2) * kstep; const char* b2 = last ? nB : cB + (size_t)(t + 2) * kstep;
;             const char* a3 = a2 + kstep; const char* b3 = b2 + kstep;
;             if (last && has_next) S.a_ready(nxt);
;             if constexpr (SP2) {
;             PG8_LDB(B0, 0, 0); PG8_LDB(B1, 0, 1); PG8_SCHED; PG8_LDA(At, 0, 0); PG8_STAGE(PG8_SA(1, 1), a1 + hstepA, voffA);
;             PG8_WAIT_V(8); PG8_WAIT_L(0); PG8_BAR; PG8_MMA(0, 0, At, B0); PG8_MMA(0, 1, At, B1); PG8_BAR; PG8_SCHED;
;             PG8_LDA(At, 0, 1); PG8_STAGE(PG8_SB(0, 0), b2, voffB); PG8_STAGE(PG8_SB(0, 1), b2 + hstep, voffB); PG8_STAGE(PG8_SA(0, 0), a2, voffA);
;             PG8_WAIT_V(8); PG8_WAIT_L(0); PG8_BAR; PG8_MMA(1, 0, At, B0); PG8_MMA(1, 1, At, B1); PG8_BAR; PG8_SCHED;
.LBB0_513:
	v_add_u32_e32 v150, s4, v157
	ds_read_b128 v[142:145], v150
	ds_read_b128 v[146:149], v150 offset:1024
	ds_read_b128 v[152:155], v150 offset:2048
	ds_read_b128 v[160:163], v150 offset:3072
	v_add_u32_e32 v150, s5, v157
	ds_read_b128 v[164:167], v150
	ds_read_b128 v[182:185], v150 offset:1024
	ds_read_b128 v[186:189], v150 offset:2048
	ds_read_b128 v[190:193], v150 offset:3072
	s_add_u32 s28, s14, 0xfff80080
	s_addc_u32 s29, s15, -1
	s_cmp_eq_u32 s23, 28
	s_cselect_b32 s31, s25, s29
	s_cselect_b32 s30, s24, s28
	s_cselect_b32 s29, s27, s21
	s_cselect_b32 s28, s26, s13
	v_lshl_add_u64 v[168:169], s[14:15], 0, v[138:139]
	s_add_i32 m0, s38, 0xc000
	ds_read_b128 v[194:197], v158
	ds_read_b128 v[198:201], v158 offset:1024
	ds_read_b128 v[202:205], v158 offset:2048
	ds_read_b128 v[206:209], v158 offset:3072
	ds_read_b128 v[210:213], v158 offset:4096
	ds_read_b128 v[214:217], v158 offset:5120
	ds_read_b128 v[218:221], v158 offset:6144
	ds_read_b128 v[222:225], v158 offset:7168
	global_load_lds_dwordx4 v[168:169], off
	s_add_i32 m0, s38, 0xe000
	v_lshl_add_u64 v[168:169], s[14:15], 0, v[140:141]
	global_load_lds_dwordx4 v[168:169], off
	s_waitcnt vmcnt(8)
	s_waitcnt lgkmcnt(0)
	s_barrier
	s_setprio 1
	s_waitcnt lgkmcnt(0)
	v_mfma_f32_16x16x32_bf16 v[126:129], v[142:145], v[194:197], v[126:129]
	v_mfma_f32_16x16x32_bf16 v[122:125], v[152:155], v[194:197], v[122:125]
	v_mfma_f32_16x16x32_bf16 v[110:113], v[142:145], v[202:205], v[110:113]
	v_mfma_f32_16x16x32_bf16 v[106:109], v[152:155], v[202:205], v[106:109]
	v_mfma_f32_16x16x32_bf16 v[94:97], v[142:145], v[210:213], v[94:97]
	v_mfma_f32_16x16x32_bf16 v[90:93], v[152:155], v[210:213], v[90:93]
	v_mfma_f32_16x16x32_bf16 v[78:81], v[142:145], v[218:221], v[78:81]
	v_mfma_f32_16x16x32_bf16 v[74:77], v[152:155], v[218:221], v[74:77]
	v_mfma_f32_16x16x32_bf16 v[126:129], v[146:149], v[198:201], v[126:129]
	v_mfma_f32_16x16x32_bf16 v[122:125], v[160:163], v[198:201], v[122:125]
	v_mfma_f32_16x16x32_bf16 v[110:113], v[146:149], v[206:209], v[110:113]
	v_mfma_f32_16x16x32_bf16 v[106:109], v[160:163], v[206:209], v[106:109]
	v_mfma_f32_16x16x32_bf16 v[94:97], v[146:149], v[214:217], v[94:97]
	v_mfma_f32_16x16x32_bf16 v[90:93], v[160:163], v[214:217], v[90:93]
	v_mfma_f32_16x16x32_bf16 v[78:81], v[146:149], v[222:225], v[78:81]
	v_mfma_f32_16x16x32_bf16 v[74:77], v[160:163], v[222:225], v[74:77]
	s_setprio 0
	s_setprio 1
	v_mfma_f32_16x16x32_bf16 v[118:121], v[164:167], v[194:197], v[118:121]
	v_mfma_f32_16x16x32_bf16 v[114:117], v[186:189], v[194:197], v[114:117]
	v_mfma_f32_16x16x32_bf16 v[102:105], v[164:167], v[202:205], v[102:105]
	v_mfma_f32_16x16x32_bf16 v[98:101], v[186:189], v[202:205], v[98:101]
	v_mfma_f32_16x16x32_bf16 v[86:89], v[164:167], v[210:213], v[86:89]
	v_mfma_f32_16x16x32_bf16 v[82:85], v[186:189], v[210:213], v[82:85]
	v_mfma_f32_16x16x32_bf16 v[70:73], v[164:167], v[218:221], v[70:73]
	v_mfma_f32_16x16x32_bf16 v[66:69], v[186:189], v[218:221], v[66:69]
	v_mfma_f32_16x16x32_bf16 v[118:121], v[182:185], v[198:201], v[118:121]
	v_mfma_f32_16x16x32_bf16 v[114:117], v[190:193], v[198:201], v[114:117]
	v_mfma_f32_16x16x32_bf16 v[102:105], v[182:185], v[206:209], v[102:105]
	v_mfma_f32_16x16x32_bf16 v[98:101], v[190:193], v[206:209], v[98:101]
	v_mfma_f32_16x16x32_bf16 v[86:89], v[182:185], v[214:217], v[86:89]
	v_mfma_f32_16x16x32_bf16 v[82:85], v[190:193], v[214:217], v[82:85]
	v_mfma_f32_16x16x32_bf16 v[70:73], v[182:185], v[222:225], v[70:73]
	v_mfma_f32_16x16x32_bf16 v[66:69], v[190:193], v[222:225], v[66:69]
	s_setprio 0
	s_barrier
	s_add_i32 s46, s4, s37
	v_lshl_add_u64 v[168:169], s[28:29], 0, v[0:1]
	s_mov_b32 m0, s46
	ds_read_b128 v[194:197], v158 offset:16384
	ds_read_b128 v[198:201], v158 offset:17408
	ds_read_b128 v[202:205], v158 offset:18432
	ds_read_b128 v[206:209], v158 offset:19456
	ds_read_b128 v[210:213], v158 offset:20480
	ds_read_b128 v[214:217], v158 offset:21504
	ds_read_b128 v[218:221], v158 offset:22528
	ds_read_b128 v[222:225], v158 offset:23552
	global_load_lds_dwordx4 v[168:169], off
	s_add_i32 m0, s46, 0x2000
	s_add_u32 s46, s28, 0x80000
	v_lshl_add_u64 v[226:227], s[28:29], 0, v[134:135]
	s_addc_u32 s47, s29, 0
	s_add_i32 s64, s5, s37
	global_load_lds_dwordx4 v[226:227], off
	v_lshl_add_u64 v[228:229], s[46:47], 0, v[0:1]
	s_mov_b32 m0, s64
	v_lshl_add_u64 v[240:241], s[30:31], 0, v[132:133]
	global_load_lds_dwordx4 v[228:229], off
	s_add_i32 m0, s64, 0x2000
	v_lshl_add_u64 v[228:229], s[46:47], 0, v[134:135]
	global_load_lds_dwordx4 v[228:229], off
	s_waitcnt vmcnt(6)
	s_waitcnt lgkmcnt(0)
	s_barrier
; #define PG8_STAGE(bufoff, gbase, voff) do { _Pragma("unroll") for (int _i = 0; _i < 2; ++_i) \
;         __builtin_amdgcn_global_load_lds((const unsigned*)((const char*)(gbase) + (voff)[_i]), (PG8_LAS unsigned*)(lds + (bufoff) + ldsw + _i * 8192), 16, 0, 0); } while (0)
; #define PG8_LDA(dst, b, h) do { _Pragma("unroll") for (int m = 0; m < 4; ++m) _Pragma("unroll") for (int k = 0; k < 2; ++k) dst[m][k] = *(const PG8_LAS bf16x8*)(lds + PG8_SA(b, h) + aoff + m * 2048 + k * 1024); } while (0)
; #define PG8_LDB(dst, b, h) do { _Pragma("unroll") for (int n = 0; n < 2; ++n) _Pragma("unroll") for (int k = 0; k < 2; ++k) dst[n][k] = *(const PG8_LAS bf16x8*)(lds + PG8_SB(b, h) + boff + n * 2048 + k * 1024); } while (0)
; #define PG8_MMA(ai, bj, At, Bt) do { __builtin_amdgcn_s_setprio(1); _Pragma("unroll") for (int m = 0; m < 4; ++m) _Pragma("unroll") for (int n = 0; n < 2; ++n) _Pragma("unroll") for (int k = 0; k < 2; ++k) \
;         acc[ai][bj][m][n] = __builtin_amdgcn_mfma_f32_16x16x32_bf16(Bt[n][k], At[m][k], acc[ai][bj][m][n], 0, 0, 0); __builtin_amdgcn_s_setprio(0); } while (0)
; #define PG8_WAIT_V(n) asm volatile("s_waitcnt vmcnt(" #n ")" ::: "memory")
; #define PG8_WAIT_L(n) asm volatile("s_waitcnt lgkmcnt(" #n ")" ::: "memory")
; #define PG8_BAR __builtin_amdgcn_s_barrier()
; #define PG8_SCHED __builtin_amdgcn_sched_barrier(0)
; template <class Epi, class Sched, bool ALIGN_EPI = false, bool SP2 = false>
; __device__ __forceinline__ void gemm_phase(PG8_LAS unsigned char* lds, const Gemm g, const Sched& S, const Epi& E, int tid_in) {
;     ...
;             PG8_WAIT_V(8); PG8_WAIT_L(0); PG8_BAR; PG8_MMA(1, 0, At, B0); PG8_MMA(1, 1, At, B1); PG8_BAR; PG8_SCHED;
;             PG8_LDB(B0, 1, 0); PG8_LDB(B1, 1, 1); PG8_SCHED; PG8_LDA(At, 1, 0); PG8_STAGE(PG8_SA(0, 1), a2 + hstepA, voffA);
;             PG8_WAIT_V(8); PG8_WAIT_L(0); PG8_BAR; PG8_MMA(0, 0, At, B0); PG8_MMA(0, 1, At, B1); PG8_BAR; PG8_SCHED;
;             PG8_LDA(At, 1, 1); PG8_STAGE(PG8_SB(1, 0), b3, voffB); PG8_STAGE(PG8_SB(1, 1), b3 + hstep, voffB); PG8_STAGE(PG8_SA(1, 0), a3, voffA);
;             PG8_WAIT_V(8); PG8_WAIT_L(0); PG8_BAR; PG8_MMA(1, 0, At, B0); PG8_MMA(1, 1, At, B1); PG8_BAR; PG8_SCHED;
	s_setprio 1
	s_waitcnt lgkmcnt(0)
	v_mfma_f32_16x16x32_bf16 v[62:65], v[142:145], v[194:197], v[62:65]
	v_mfma_f32_16x16x32_bf16 v[58:61], v[152:155], v[194:197], v[58:61]
	v_mfma_f32_16x16x32_bf16 v[46:49], v[142:145], v[202:205], v[46:49]
	v_mfma_f32_16x16x32_bf16 v[42:45], v[152:155], v[202:205], v[42:45]
	v_mfma_f32_16x16x32_bf16 v[30:33], v[142:145], v[210:213], v[30:33]
	v_mfma_f32_16x16x32_bf16 v[26:29], v[152:155], v[210:213], v[26:29]
	v_mfma_f32_16x16x32_bf16 v[14:17], v[142:145], v[218:221], v[14:17]
	v_mfma_f32_16x16x32_bf16 v[10:13], v[152:155], v[218:221], v[10:13]
	v_mfma_f32_16x16x32_bf16 v[62:65], v[146:149], v[198:201], v[62:65]
	v_mfma_f32_16x16x32_bf16 v[58:61], v[160:163], v[198:201], v[58:61]
	v_mfma_f32_16x16x32_bf16 v[46:49], v[146:149], v[206:209], v[46:49]
	v_mfma_f32_16x16x32_bf16 v[42:45], v[160:163], v[206:209], v[42:45]
	v_mfma_f32_16x16x32_bf16 v[30:33], v[146:149], v[214:217], v[30:33]
	v_mfma_f32_16x16x32_bf16 v[26:29], v[160:163], v[214:217], v[26:29]
	v_mfma_f32_16x16x32_bf16 v[14:17], v[146:149], v[222:225], v[14:17]
	v_mfma_f32_16x16x32_bf16 v[10:13], v[160:163], v[222:225], v[10:13]
	s_setprio 0
	s_setprio 1
	v_mfma_f32_16x16x32_bf16 v[54:57], v[164:167], v[194:197], v[54:57]
	v_mfma_f32_16x16x32_bf16 v[50:53], v[186:189], v[194:197], v[50:53]
	v_mfma_f32_16x16x32_bf16 v[38:41], v[164:167], v[202:205], v[38:41]
	v_mfma_f32_16x16x32_bf16 v[34:37], v[186:189], v[202:205], v[34:37]
	v_mfma_f32_16x16x32_bf16 v[22:25], v[164:167], v[210:213], v[22:25]
	v_mfma_f32_16x16x32_bf16 v[18:21], v[186:189], v[210:213], v[18:21]
	v_mfma_f32_16x16x32_bf16 v[6:9], v[164:167], v[218:221], v[6:9]
	v_mfma_f32_16x16x32_bf16 v[2:5], v[186:189], v[218:221], v[2:5]
	v_mfma_f32_16x16x32_bf16 v[54:57], v[182:185], v[198:201], v[54:57]
	v_mfma_f32_16x16x32_bf16 v[50:53], v[190:193], v[198:201], v[50:53]
	v_mfma_f32_16x16x32_bf16 v[38:41], v[182:185], v[206:209], v[38:41]
	v_mfma_f32_16x16x32_bf16 v[34:37], v[190:193], v[206:209], v[34:37]
	v_mfma_f32_16x16x32_bf16 v[22:25], v[182:185], v[214:217], v[22:25]
	v_mfma_f32_16x16x32_bf16 v[18:21], v[190:193], v[214:217], v[18:21]
	v_mfma_f32_16x16x32_bf16 v[6:9], v[182:185], v[222:225], v[6:9]
	v_mfma_f32_16x16x32_bf16 v[2:5], v[190:193], v[222:225], v[2:5]
	s_setprio 0
	s_barrier
	s_mov_b32 m0, s38
	v_lshl_add_u64 v[228:229], s[30:31], 0, v[130:131]
	global_load_lds_dwordx4 v[228:229], off
	s_mov_b32 m0, s39
	s_nop 0
	global_load_lds_dwordx4 v[240:241], off
	v_add_u32_e32 v150, s63, v157
	ds_read_b128 v[142:145], v150
	ds_read_b128 v[146:149], v150 offset:1024
	ds_read_b128 v[152:155], v150 offset:2048
	ds_read_b128 v[160:163], v150 offset:3072
	v_add_u32_e32 v150, s55, v157
	ds_read_b128 v[164:167], v150
	ds_read_b128 v[182:185], v150 offset:1024
	ds_read_b128 v[186:189], v150 offset:2048
	ds_read_b128 v[190:193], v150 offset:3072
	s_add_u32 s30, s30, 0x80000
	s_addc_u32 s31, s31, 0
	s_mov_b32 m0, s40
	v_lshl_add_u64 v[242:243], s[30:31], 0, v[130:131]
	ds_read_b128 v[194:197], v158 offset:32768
	ds_read_b128 v[198:201], v158 offset:33792
	ds_read_b128 v[202:205], v158 offset:34816
	ds_read_b128 v[206:209], v158 offset:35840
	ds_read_b128 v[210:213], v158 offset:36864
	ds_read_b128 v[214:217], v158 offset:37888
	ds_read_b128 v[218:221], v158 offset:38912
	ds_read_b128 v[222:225], v158 offset:39936
	global_load_lds_dwordx4 v[242:243], off
	s_mov_b32 m0, s41
	v_lshl_add_u64 v[242:243], s[30:31], 0, v[132:133]
	global_load_lds_dwordx4 v[242:243], off
	s_waitcnt vmcnt(8)
	s_waitcnt lgkmcnt(0)
	s_barrier
	s_setprio 1
	s_waitcnt lgkmcnt(0)
	v_mfma_f32_16x16x32_bf16 v[126:129], v[142:145], v[194:197], v[126:129]
	v_mfma_f32_16x16x32_bf16 v[122:125], v[152:155], v[194:197], v[122:125]
	v_mfma_f32_16x16x32_bf16 v[110:113], v[142:145], v[202:205], v[110:113]
	v_mfma_f32_16x16x32_bf16 v[106:109], v[152:155], v[202:205], v[106:109]
	v_mfma_f32_16x16x32_bf16 v[94:97], v[142:145], v[210:213], v[94:97]
	v_mfma_f32_16x16x32_bf16 v[90:93], v[152:155], v[210:213], v[90:93]
	v_mfma_f32_16x16x32_bf16 v[78:81], v[142:145], v[218:221], v[78:81]
	v_mfma_f32_16x16x32_bf16 v[74:77], v[152:155], v[218:221], v[74:77]
	v_mfma_f32_16x16x32_bf16 v[126:129], v[146:149], v[198:201], v[126:129]
	v_mfma_f32_16x16x32_bf16 v[122:125], v[160:163], v[198:201], v[122:125]
	v_mfma_f32_16x16x32_bf16 v[110:113], v[146:149], v[206:209], v[110:113]
	v_mfma_f32_16x16x32_bf16 v[106:109], v[160:163], v[206:209], v[106:109]
	v_mfma_f32_16x16x32_bf16 v[94:97], v[146:149], v[214:217], v[94:97]
	v_mfma_f32_16x16x32_bf16 v[90:93], v[160:163], v[214:217], v[90:93]
	v_mfma_f32_16x16x32_bf16 v[78:81], v[146:149], v[222:225], v[78:81]
	v_mfma_f32_16x16x32_bf16 v[74:77], v[160:163], v[222:225], v[74:77]
	s_setprio 0
	s_setprio 1
	v_mfma_f32_16x16x32_bf16 v[118:121], v[164:167], v[194:197], v[118:121]
	v_mfma_f32_16x16x32_bf16 v[114:117], v[186:189], v[194:197], v[114:117]
	v_mfma_f32_16x16x32_bf16 v[102:105], v[164:167], v[202:205], v[102:105]
	v_mfma_f32_16x16x32_bf16 v[98:101], v[186:189], v[202:205], v[98:101]
	v_mfma_f32_16x16x32_bf16 v[86:89], v[164:167], v[210:213], v[86:89]
	v_mfma_f32_16x16x32_bf16 v[82:85], v[186:189], v[210:213], v[82:85]
	v_mfma_f32_16x16x32_bf16 v[70:73], v[164:167], v[218:221], v[70:73]
	v_mfma_f32_16x16x32_bf16 v[66:69], v[186:189], v[218:221], v[66:69]
	v_mfma_f32_16x16x32_bf16 v[118:121], v[182:185], v[198:201], v[118:121]
	v_mfma_f32_16x16x32_bf16 v[114:117], v[190:193], v[198:201], v[114:117]
	v_mfma_f32_16x16x32_bf16 v[102:105], v[182:185], v[206:209], v[102:105]
	v_mfma_f32_16x16x32_bf16 v[98:101], v[190:193], v[206:209], v[98:101]
	v_mfma_f32_16x16x32_bf16 v[86:89], v[182:185], v[214:217], v[86:89]
	v_mfma_f32_16x16x32_bf16 v[82:85], v[190:193], v[214:217], v[82:85]
	v_mfma_f32_16x16x32_bf16 v[70:73], v[182:185], v[222:225], v[70:73]
	v_mfma_f32_16x16x32_bf16 v[66:69], v[190:193], v[222:225], v[66:69]
	s_setprio 0
	s_barrier
; #define PG8_STAGE(bufoff, gbase, voff) do { _Pragma("unroll") for (int _i = 0; _i < 2; ++_i) \
;         __builtin_amdgcn_global_load_lds((const unsigned*)((const char*)(gbase) + (voff)[_i]), (PG8_LAS unsigned*)(lds + (bufoff) + ldsw + _i * 8192), 16, 0, 0); } while (0)
; #define PG8_LDA(dst, b, h) do { _Pragma("unroll") for (int m = 0; m < 4; ++m) _Pragma("unroll") for (int k = 0; k < 2; ++k) dst[m][k] = *(const PG8_LAS bf16x8*)(lds + PG8_SA(b, h) + aoff + m * 2048 + k * 1024); } while (0)
; #define PG8_MMA(ai, bj, At, Bt) do { __builtin_amdgcn_s_setprio(1); _Pragma("unroll") for (int m = 0; m < 4; ++m) _Pragma("unroll") for (int n = 0; n < 2; ++n) _Pragma("unroll") for (int k = 0; k < 2; ++k) \
;         acc[ai][bj][m][n] = __builtin_amdgcn_mfma_f32_16x16x32_bf16(Bt[n][k], At[m][k], acc[ai][bj][m][n], 0, 0, 0); __builtin_amdgcn_s_setprio(0); } while (0)
; #define PG8_WAIT_V(n) asm volatile("s_waitcnt vmcnt(" #n ")" ::: "memory")
; #define PG8_WAIT_L(n) asm volatile("s_waitcnt lgkmcnt(" #n ")" ::: "memory")
; #define PG8_BAR __builtin_amdgcn_s_barrier()
; #define PG8_SCHED __builtin_amdgcn_sched_barrier(0)
; template <class Epi, class Sched, bool ALIGN_EPI = false, bool SP2 = false>
; __device__ __forceinline__ void gemm_phase(PG8_LAS unsigned char* lds, const Gemm g, const Sched& S, const Epi& E, int tid_in) {
;     ...
;             PG8_LDA(At, 1, 1); PG8_STAGE(PG8_SB(1, 0), b3, voffB); PG8_STAGE(PG8_SB(1, 1), b3 + hstep, voffB); PG8_STAGE(PG8_SA(1, 0), a3, voffA);
;             PG8_WAIT_V(8); PG8_WAIT_L(0); PG8_BAR; PG8_MMA(1, 0, At, B0); PG8_MMA(1, 1, At, B1); PG8_BAR; PG8_SCHED;
;     ...
;         if constexpr (ALIGN_EPI) { if (wr == 0) PG8_BAR; }
	s_add_i32 s30, s63, s37
	v_lshl_add_u64 v[168:169], v[168:169], 0, s[90:91]
	s_mov_b32 m0, s30
	ds_read_b128 v[194:197], v158 offset:49152
	ds_read_b128 v[198:201], v158 offset:50176
	ds_read_b128 v[202:205], v158 offset:51200
	ds_read_b128 v[206:209], v158 offset:52224
	ds_read_b128 v[210:213], v158 offset:53248
	ds_read_b128 v[214:217], v158 offset:54272
	ds_read_b128 v[218:221], v158 offset:55296
	ds_read_b128 v[222:225], v158 offset:56320
	global_load_lds_dwordx4 v[168:169], off
	s_add_i32 m0, s30, 0x2000
	s_add_u32 s28, s28, 0x80080
	v_lshl_add_u64 v[168:169], v[226:227], 0, s[90:91]
	s_addc_u32 s29, s29, 0
	s_add_i32 s30, s55, s37
	global_load_lds_dwordx4 v[168:169], off
	s_mov_b32 m0, s30
	v_lshl_add_u64 v[168:169], s[28:29], 0, v[0:1]
	global_load_lds_dwordx4 v[168:169], off
	s_add_i32 m0, s30, 0x2000
	v_lshl_add_u64 v[168:169], s[28:29], 0, v[134:135]
	global_load_lds_dwordx4 v[168:169], off
	s_mov_b32 m0, s45
	v_lshl_add_u64 v[168:169], v[228:229], 0, s[90:91]
	global_load_lds_dwordx4 v[168:169], off
	s_mov_b32 m0, s48
	v_lshl_add_u64 v[168:169], v[240:241], 0, s[90:91]
	global_load_lds_dwordx4 v[168:169], off
	s_add_i32 s23, s23, 2
	s_add_u32 s14, s14, 0x100
	s_addc_u32 s15, s15, 0
	s_add_u32 s13, s13, 0x100
	s_addc_u32 s21, s21, 0
	s_cmp_gt_u32 s23, 29
	s_waitcnt vmcnt(8)
	s_waitcnt lgkmcnt(0)
	s_barrier
	s_setprio 1
	s_waitcnt lgkmcnt(0)
	v_mfma_f32_16x16x32_bf16 v[62:65], v[142:145], v[194:197], v[62:65]
	v_mfma_f32_16x16x32_bf16 v[58:61], v[152:155], v[194:197], v[58:61]
	v_mfma_f32_16x16x32_bf16 v[46:49], v[142:145], v[202:205], v[46:49]
	v_mfma_f32_16x16x32_bf16 v[42:45], v[152:155], v[202:205], v[42:45]
	v_mfma_f32_16x16x32_bf16 v[30:33], v[142:145], v[210:213], v[30:33]
	v_mfma_f32_16x16x32_bf16 v[26:29], v[152:155], v[210:213], v[26:29]
	v_mfma_f32_16x16x32_bf16 v[14:17], v[142:145], v[218:221], v[14:17]
	v_mfma_f32_16x16x32_bf16 v[10:13], v[152:155], v[218:221], v[10:13]
	v_mfma_f32_16x16x32_bf16 v[62:65], v[146:149], v[198:201], v[62:65]
	v_mfma_f32_16x16x32_bf16 v[58:61], v[160:163], v[198:201], v[58:61]
	v_mfma_f32_16x16x32_bf16 v[46:49], v[146:149], v[206:209], v[46:49]
	v_mfma_f32_16x16x32_bf16 v[42:45], v[160:163], v[206:209], v[42:45]
	v_mfma_f32_16x16x32_bf16 v[30:33], v[146:149], v[214:217], v[30:33]
	v_mfma_f32_16x16x32_bf16 v[26:29], v[160:163], v[214:217], v[26:29]
	v_mfma_f32_16x16x32_bf16 v[14:17], v[146:149], v[222:225], v[14:17]
	v_mfma_f32_16x16x32_bf16 v[10:13], v[160:163], v[222:225], v[10:13]
	s_setprio 0
	s_setprio 1
	v_mfma_f32_16x16x32_bf16 v[54:57], v[164:167], v[194:197], v[54:57]
	v_mfma_f32_16x16x32_bf16 v[50:53], v[186:189], v[194:197], v[50:53]
	v_mfma_f32_16x16x32_bf16 v[38:41], v[164:167], v[202:205], v[38:41]
	v_mfma_f32_16x16x32_bf16 v[34:37], v[186:189], v[202:205], v[34:37]
	v_mfma_f32_16x16x32_bf16 v[22:25], v[164:167], v[210:213], v[22:25]
	v_mfma_f32_16x16x32_bf16 v[18:21], v[186:189], v[210:213], v[18:21]
	v_mfma_f32_16x16x32_bf16 v[6:9], v[164:167], v[218:221], v[6:9]
	v_mfma_f32_16x16x32_bf16 v[2:5], v[186:189], v[218:221], v[2:5]
	v_mfma_f32_16x16x32_bf16 v[54:57], v[182:185], v[198:201], v[54:57]
	v_mfma_f32_16x16x32_bf16 v[50:53], v[190:193], v[198:201], v[50:53]
	v_mfma_f32_16x16x32_bf16 v[38:41], v[182:185], v[206:209], v[38:41]
	v_mfma_f32_16x16x32_bf16 v[34:37], v[190:193], v[206:209], v[34:37]
	v_mfma_f32_16x16x32_bf16 v[22:25], v[182:185], v[214:217], v[22:25]
	v_mfma_f32_16x16x32_bf16 v[18:21], v[190:193], v[214:217], v[18:21]
	v_mfma_f32_16x16x32_bf16 v[6:9], v[182:185], v[222:225], v[6:9]
	v_mfma_f32_16x16x32_bf16 v[2:5], v[190:193], v[222:225], v[2:5]
	s_setprio 0
	s_barrier
	s_cbranch_scc0 .LBB0_513
	s_and_b64 vcc, exec, s[18:19]
	s_cbranch_vccz .LBB0_516
	s_barrier

; #define PG8_STAGE(bufoff, gbase, voff) do { _Pragma("unroll") for (int _i = 0; _i < 2; ++_i) \
;         __builtin_amdgcn_global_load_lds((const unsigned*)((const char*)(gbase) + (voff)[_i]), (PG8_LAS unsigned*)(lds + (bufoff) + ldsw + _i * 8192), 16, 0, 0); } while (0)
; #define PG8_LDA(dst, b, h) do { _Pragma("unroll") for (int m = 0; m < 4; ++m) _Pragma("unroll") for (int k = 0; k < 2; ++k) dst[m][k] = *(const PG8_LAS bf16x8*)(lds + PG8_SA(b, h) + aoff + m * 2048 + k * 1024); } while (0)
; #define PG8_LDB(dst, b, h) do { _Pragma("unroll") for (int n = 0; n < 2; ++n) _Pragma("unroll") for (int k = 0; k < 2; ++k) dst[n][k] = *(const PG8_LAS bf16x8*)(lds + PG8_SB(b, h) + boff + n * 2048 + k * 1024); } while (0)
; #define PG8_MMA(ai, bj, At, Bt) do { __builtin_amdgcn_s_setprio(1); _Pragma("unroll") for (int m = 0; m < 4; ++m) _Pragma("unroll") for (int n = 0; n < 2; ++n) _Pragma("unroll") for (int k = 0; k < 2; ++k) \
;         acc[ai][bj][m][n] = __builtin_amdgcn_mfma_f32_16x16x32_bf16(Bt[n][k], At[m][k], acc[ai][bj][m][n], 0, 0, 0); __builtin_amdgcn_s_setprio(0); } while (0)
; #define PG8_WAIT_V(n) asm volatile("s_waitcnt vmcnt(" #n ")" ::: "memory")
; #define PG8_WAIT_L(n) asm volatile("s_waitcnt lgkmcnt(" #n ")" ::: "memory")
; template <class Epi, class Sched, bool ALIGN_EPI = false, bool SP2 = false>
; __device__ __forceinline__ void gemm_phase(PG8_LAS unsigned char* lds, const Gemm g, const Sched& S, const Epi& E, int tid_in) {
;     ...
;             const bool last = (t == nt - 2);
;             const char* a1 = cA + (size_t)(t + 1) * kstep;
;             const char* a2 = last ? nA : cA + (size_t)(t + 2) * kstep; const char* b2 = last ? nB : cB + (size_t)(t + 2) * kstep;
;             const char* a3 = a2 + kstep; const char* b3 = b2 + kstep;
;             if (last && has_next) S.a_ready(nxt);
;             if constexpr (SP2) {
;             PG8_LDB(B0, 0, 0); PG8_LDB(B1, 0, 1); PG8_SCHED; PG8_LDA(At, 0, 0); PG8_STAGE(PG8_SA(1, 1), a1 + hstepA, voffA);
;             PG8_WAIT_V(8); PG8_WAIT_L(0); PG8_BAR; PG8_MMA(0, 0, At, B0); PG8_MMA(0, 1, At, B1); PG8_BAR; PG8_SCHED;
;             PG8_LDA(At, 0, 1); PG8_STAGE(PG8_SB(0, 0), b2, voffB); PG8_STAGE(PG8_SB(0, 1), b2 + hstep, voffB); PG8_STAGE(PG8_SA(0, 0), a2, voffA);
;             PG8_WAIT_V(8); PG8_WAIT_L(0); PG8_BAR; PG8_MMA(1, 0, At, B0); PG8_MMA(1, 1, At, B1); PG8_BAR; PG8_SCHED;
.LBB0_627:
	v_add_u32_e32 v140, s4, v145
	ds_read_b128 v[148:151], v140
	ds_read_b128 v[152:155], v140 offset:1024
	ds_read_b128 v[156:159], v140 offset:2048
	ds_read_b128 v[160:163], v140 offset:3072
	v_add_u32_e32 v140, s5, v145
	ds_read_b128 v[164:167], v140
	ds_read_b128 v[182:185], v140 offset:1024
	ds_read_b128 v[186:189], v140 offset:2048
	ds_read_b128 v[190:193], v140 offset:3072
	s_add_u32 s22, s20, 0x100
	s_addc_u32 s23, s21, 0
	s_cmp_eq_u32 s48, 4
	s_cselect_b32 s27, s17, s23
	s_cselect_b32 s26, s16, s22
	s_cselect_b32 s25, s19, s15
	s_cselect_b32 s24, s18, s0
	v_lshl_add_u64 v[168:169], s[20:21], 0, v[136:137]
	s_add_i32 m0, s34, 0xc000
	ds_read_b128 v[194:197], v147
	ds_read_b128 v[198:201], v147 offset:1024
	ds_read_b128 v[202:205], v147 offset:2048
	ds_read_b128 v[206:209], v147 offset:3072
	ds_read_b128 v[210:213], v147 offset:4096
	ds_read_b128 v[214:217], v147 offset:5120
	ds_read_b128 v[218:221], v147 offset:6144
	ds_read_b128 v[222:225], v147 offset:7168
	global_load_lds_dwordx4 v[168:169], off
	s_add_i32 m0, s34, 0xe000
	v_lshl_add_u64 v[168:169], s[20:21], 0, v[138:139]
	global_load_lds_dwordx4 v[168:169], off
	s_waitcnt vmcnt(8)
	s_waitcnt lgkmcnt(0)
	s_barrier
	s_setprio 1
	s_waitcnt lgkmcnt(0)
	v_mfma_f32_16x16x32_bf16 v[126:129], v[148:151], v[194:197], v[126:129]
	v_mfma_f32_16x16x32_bf16 v[122:125], v[156:159], v[194:197], v[122:125]
	v_mfma_f32_16x16x32_bf16 v[114:117], v[148:151], v[202:205], v[114:117]
	v_mfma_f32_16x16x32_bf16 v[106:109], v[156:159], v[202:205], v[106:109]
	v_mfma_f32_16x16x32_bf16 v[98:101], v[148:151], v[210:213], v[98:101]
	v_mfma_f32_16x16x32_bf16 v[90:93], v[156:159], v[210:213], v[90:93]
	v_mfma_f32_16x16x32_bf16 v[82:85], v[148:151], v[218:221], v[82:85]
	v_mfma_f32_16x16x32_bf16 v[74:77], v[156:159], v[218:221], v[74:77]
	v_mfma_f32_16x16x32_bf16 v[126:129], v[152:155], v[198:201], v[126:129]
	v_mfma_f32_16x16x32_bf16 v[122:125], v[160:163], v[198:201], v[122:125]
	v_mfma_f32_16x16x32_bf16 v[114:117], v[152:155], v[206:209], v[114:117]
	v_mfma_f32_16x16x32_bf16 v[106:109], v[160:163], v[206:209], v[106:109]
	v_mfma_f32_16x16x32_bf16 v[98:101], v[152:155], v[214:217], v[98:101]
	v_mfma_f32_16x16x32_bf16 v[90:93], v[160:163], v[214:217], v[90:93]
	v_mfma_f32_16x16x32_bf16 v[82:85], v[152:155], v[222:225], v[82:85]
	v_mfma_f32_16x16x32_bf16 v[74:77], v[160:163], v[222:225], v[74:77]
	s_setprio 0
	s_setprio 1
	v_mfma_f32_16x16x32_bf16 v[118:121], v[164:167], v[194:197], v[118:121]
	v_mfma_f32_16x16x32_bf16 v[110:113], v[186:189], v[194:197], v[110:113]
	v_mfma_f32_16x16x32_bf16 v[102:105], v[164:167], v[202:205], v[102:105]
	v_mfma_f32_16x16x32_bf16 v[94:97], v[186:189], v[202:205], v[94:97]
	v_mfma_f32_16x16x32_bf16 v[86:89], v[164:167], v[210:213], v[86:89]
	v_mfma_f32_16x16x32_bf16 v[78:81], v[186:189], v[210:213], v[78:81]
	v_mfma_f32_16x16x32_bf16 v[70:73], v[164:167], v[218:221], v[70:73]
	v_mfma_f32_16x16x32_bf16 v[66:69], v[186:189], v[218:221], v[66:69]
	v_mfma_f32_16x16x32_bf16 v[118:121], v[182:185], v[198:201], v[118:121]
	v_mfma_f32_16x16x32_bf16 v[110:113], v[190:193], v[198:201], v[110:113]
	v_mfma_f32_16x16x32_bf16 v[102:105], v[182:185], v[206:209], v[102:105]
	v_mfma_f32_16x16x32_bf16 v[94:97], v[190:193], v[206:209], v[94:97]
	v_mfma_f32_16x16x32_bf16 v[86:89], v[182:185], v[214:217], v[86:89]
	v_mfma_f32_16x16x32_bf16 v[78:81], v[190:193], v[214:217], v[78:81]
	v_mfma_f32_16x16x32_bf16 v[70:73], v[182:185], v[222:225], v[70:73]
	v_mfma_f32_16x16x32_bf16 v[66:69], v[190:193], v[222:225], v[66:69]
	s_setprio 0
	s_barrier
	s_add_i32 s20, s4, s33
	v_lshl_add_u64 v[168:169], s[24:25], 0, v[0:1]
	s_mov_b32 m0, s20
	ds_read_b128 v[194:197], v147 offset:16384
	ds_read_b128 v[198:201], v147 offset:17408
	ds_read_b128 v[202:205], v147 offset:18432
	ds_read_b128 v[206:209], v147 offset:19456
	ds_read_b128 v[210:213], v147 offset:20480
	ds_read_b128 v[214:217], v147 offset:21504
	ds_read_b128 v[218:221], v147 offset:22528
	ds_read_b128 v[222:225], v147 offset:23552
	global_load_lds_dwordx4 v[168:169], off
	s_add_i32 m0, s20, 0x2000
	s_add_u32 s20, s24, 0x20000
	v_lshl_add_u64 v[226:227], s[24:25], 0, v[134:135]
	s_addc_u32 s21, s25, 0
	s_add_i32 s49, s5, s33
	global_load_lds_dwordx4 v[226:227], off
	v_lshl_add_u64 v[228:229], s[20:21], 0, v[0:1]
	s_mov_b32 m0, s49
	v_lshl_add_u64 v[240:241], s[26:27], 0, v[132:133]
	global_load_lds_dwordx4 v[228:229], off
	s_add_i32 m0, s49, 0x2000
	v_lshl_add_u64 v[228:229], s[20:21], 0, v[134:135]
	global_load_lds_dwordx4 v[228:229], off
	s_waitcnt vmcnt(6)
	s_waitcnt lgkmcnt(0)
	s_barrier
; #define PG8_STAGE(bufoff, gbase, voff) do { _Pragma("unroll") for (int _i = 0; _i < 2; ++_i) \
;         __builtin_amdgcn_global_load_lds((const unsigned*)((const char*)(gbase) + (voff)[_i]), (PG8_LAS unsigned*)(lds + (bufoff) + ldsw + _i * 8192), 16, 0, 0); } while (0)
; #define PG8_LDA(dst, b, h) do { _Pragma("unroll") for (int m = 0; m < 4; ++m) _Pragma("unroll") for (int k = 0; k < 2; ++k) dst[m][k] = *(const PG8_LAS bf16x8*)(lds + PG8_SA(b, h) + aoff + m * 2048 + k * 1024); } while (0)
; #define PG8_LDB(dst, b, h) do { _Pragma("unroll") for (int n = 0; n < 2; ++n) _Pragma("unroll") for (int k = 0; k < 2; ++k) dst[n][k] = *(const PG8_LAS bf16x8*)(lds + PG8_SB(b, h) + boff + n * 2048 + k * 1024); } while (0)
; #define PG8_MMA(ai, bj, At, Bt) do { __builtin_amdgcn_s_setprio(1); _Pragma("unroll") for (int m = 0; m < 4; ++m) _Pragma("unroll") for (int n = 0; n < 2; ++n) _Pragma("unroll") for (int k = 0; k < 2; ++k) \
;         acc[ai][bj][m][n] = __builtin_amdgcn_mfma_f32_16x16x32_bf16(Bt[n][k], At[m][k], acc[ai][bj][m][n], 0, 0, 0); __builtin_amdgcn_s_setprio(0); } while (0)
; #define PG8_WAIT_V(n) asm volatile("s_waitcnt vmcnt(" #n ")" ::: "memory")
; #define PG8_WAIT_L(n) asm volatile("s_waitcnt lgkmcnt(" #n ")" ::: "memory")
; #define PG8_BAR __builtin_amdgcn_s_barrier()
; #define PG8_SCHED __builtin_amdgcn_sched_barrier(0)
; template <class Epi, class Sched, bool ALIGN_EPI = false, bool SP2 = false>
; __device__ __forceinline__ void gemm_phase(PG8_LAS unsigned char* lds, const Gemm g, const Sched& S, const Epi& E, int tid_in) {
;     ...
;             PG8_WAIT_V(8); PG8_WAIT_L(0); PG8_BAR; PG8_MMA(1, 0, At, B0); PG8_MMA(1, 1, At, B1); PG8_BAR; PG8_SCHED;
;             PG8_LDB(B0, 1, 0); PG8_LDB(B1, 1, 1); PG8_SCHED; PG8_LDA(At, 1, 0); PG8_STAGE(PG8_SA(0, 1), a2 + hstepA, voffA);
;             PG8_WAIT_V(8); PG8_WAIT_L(0); PG8_BAR; PG8_MMA(0, 0, At, B0); PG8_MMA(0, 1, At, B1); PG8_BAR; PG8_SCHED;
;             PG8_LDA(At, 1, 1); PG8_STAGE(PG8_SB(1, 0), b3, voffB); PG8_STAGE(PG8_SB(1, 1), b3 + hstep, voffB); PG8_STAGE(PG8_SA(1, 0), a3, voffA);
;             PG8_WAIT_V(8); PG8_WAIT_L(0); PG8_BAR; PG8_MMA(1, 0, At, B0); PG8_MMA(1, 1, At, B1); PG8_BAR; PG8_SCHED;
	s_setprio 1
	s_waitcnt lgkmcnt(0)
	v_mfma_f32_16x16x32_bf16 v[62:65], v[148:151], v[194:197], v[62:65]
	v_mfma_f32_16x16x32_bf16 v[58:61], v[156:159], v[194:197], v[58:61]
	v_mfma_f32_16x16x32_bf16 v[50:53], v[148:151], v[202:205], v[50:53]
	v_mfma_f32_16x16x32_bf16 v[42:45], v[156:159], v[202:205], v[42:45]
	v_mfma_f32_16x16x32_bf16 v[34:37], v[148:151], v[210:213], v[34:37]
	v_mfma_f32_16x16x32_bf16 v[26:29], v[156:159], v[210:213], v[26:29]
	v_mfma_f32_16x16x32_bf16 v[18:21], v[148:151], v[218:221], v[18:21]
	v_mfma_f32_16x16x32_bf16 v[10:13], v[156:159], v[218:221], v[10:13]
	v_mfma_f32_16x16x32_bf16 v[62:65], v[152:155], v[198:201], v[62:65]
	v_mfma_f32_16x16x32_bf16 v[58:61], v[160:163], v[198:201], v[58:61]
	v_mfma_f32_16x16x32_bf16 v[50:53], v[152:155], v[206:209], v[50:53]
	v_mfma_f32_16x16x32_bf16 v[42:45], v[160:163], v[206:209], v[42:45]
	v_mfma_f32_16x16x32_bf16 v[34:37], v[152:155], v[214:217], v[34:37]
	v_mfma_f32_16x16x32_bf16 v[26:29], v[160:163], v[214:217], v[26:29]
	v_mfma_f32_16x16x32_bf16 v[18:21], v[152:155], v[222:225], v[18:21]
	v_mfma_f32_16x16x32_bf16 v[10:13], v[160:163], v[222:225], v[10:13]
	s_setprio 0
	s_setprio 1
	v_mfma_f32_16x16x32_bf16 v[54:57], v[164:167], v[194:197], v[54:57]
	v_mfma_f32_16x16x32_bf16 v[46:49], v[186:189], v[194:197], v[46:49]
	v_mfma_f32_16x16x32_bf16 v[38:41], v[164:167], v[202:205], v[38:41]
	v_mfma_f32_16x16x32_bf16 v[30:33], v[186:189], v[202:205], v[30:33]
	v_mfma_f32_16x16x32_bf16 v[22:25], v[164:167], v[210:213], v[22:25]
	v_mfma_f32_16x16x32_bf16 v[14:17], v[186:189], v[210:213], v[14:17]
	v_mfma_f32_16x16x32_bf16 v[6:9], v[164:167], v[218:221], v[6:9]
	v_mfma_f32_16x16x32_bf16 v[2:5], v[186:189], v[218:221], v[2:5]
	v_mfma_f32_16x16x32_bf16 v[54:57], v[182:185], v[198:201], v[54:57]
	v_mfma_f32_16x16x32_bf16 v[46:49], v[190:193], v[198:201], v[46:49]
	v_mfma_f32_16x16x32_bf16 v[38:41], v[182:185], v[206:209], v[38:41]
	v_mfma_f32_16x16x32_bf16 v[30:33], v[190:193], v[206:209], v[30:33]
	v_mfma_f32_16x16x32_bf16 v[22:25], v[182:185], v[214:217], v[22:25]
	v_mfma_f32_16x16x32_bf16 v[14:17], v[190:193], v[214:217], v[14:17]
	v_mfma_f32_16x16x32_bf16 v[6:9], v[182:185], v[222:225], v[6:9]
	v_mfma_f32_16x16x32_bf16 v[2:5], v[190:193], v[222:225], v[2:5]
	s_setprio 0
	s_barrier
	s_mov_b32 m0, s34
	v_lshl_add_u64 v[228:229], s[26:27], 0, v[130:131]
	global_load_lds_dwordx4 v[228:229], off
	s_mov_b32 m0, s35
	s_nop 0
	global_load_lds_dwordx4 v[240:241], off
	v_add_u32_e32 v140, s63, v145
	ds_read_b128 v[148:151], v140
	ds_read_b128 v[152:155], v140 offset:1024
	ds_read_b128 v[156:159], v140 offset:2048
	ds_read_b128 v[160:163], v140 offset:3072
	v_add_u32_e32 v140, s55, v145
	ds_read_b128 v[164:167], v140
	ds_read_b128 v[182:185], v140 offset:1024
	ds_read_b128 v[186:189], v140 offset:2048
	ds_read_b128 v[190:193], v140 offset:3072
	s_add_u32 s20, s26, 0x2e0000
	s_addc_u32 s21, s27, 0
	s_mov_b32 m0, s36
	v_lshl_add_u64 v[242:243], s[20:21], 0, v[130:131]
	ds_read_b128 v[194:197], v147 offset:32768
	ds_read_b128 v[198:201], v147 offset:33792
	ds_read_b128 v[202:205], v147 offset:34816
	ds_read_b128 v[206:209], v147 offset:35840
	ds_read_b128 v[210:213], v147 offset:36864
	ds_read_b128 v[214:217], v147 offset:37888
	ds_read_b128 v[218:221], v147 offset:38912
	ds_read_b128 v[222:225], v147 offset:39936
	global_load_lds_dwordx4 v[242:243], off
	s_mov_b32 m0, s37
	v_lshl_add_u64 v[242:243], s[20:21], 0, v[132:133]
	global_load_lds_dwordx4 v[242:243], off
	s_waitcnt vmcnt(8)
	s_waitcnt lgkmcnt(0)
	s_barrier
	s_setprio 1
	s_waitcnt lgkmcnt(0)
	v_mfma_f32_16x16x32_bf16 v[126:129], v[148:151], v[194:197], v[126:129]
	v_mfma_f32_16x16x32_bf16 v[122:125], v[156:159], v[194:197], v[122:125]
	v_mfma_f32_16x16x32_bf16 v[114:117], v[148:151], v[202:205], v[114:117]
	v_mfma_f32_16x16x32_bf16 v[106:109], v[156:159], v[202:205], v[106:109]
	v_mfma_f32_16x16x32_bf16 v[98:101], v[148:151], v[210:213], v[98:101]
	v_mfma_f32_16x16x32_bf16 v[90:93], v[156:159], v[210:213], v[90:93]
	v_mfma_f32_16x16x32_bf16 v[82:85], v[148:151], v[218:221], v[82:85]
	v_mfma_f32_16x16x32_bf16 v[74:77], v[156:159], v[218:221], v[74:77]
	v_mfma_f32_16x16x32_bf16 v[126:129], v[152:155], v[198:201], v[126:129]
	v_mfma_f32_16x16x32_bf16 v[122:125], v[160:163], v[198:201], v[122:125]
	v_mfma_f32_16x16x32_bf16 v[114:117], v[152:155], v[206:209], v[114:117]
	v_mfma_f32_16x16x32_bf16 v[106:109], v[160:163], v[206:209], v[106:109]
	v_mfma_f32_16x16x32_bf16 v[98:101], v[152:155], v[214:217], v[98:101]
	v_mfma_f32_16x16x32_bf16 v[90:93], v[160:163], v[214:217], v[90:93]
	v_mfma_f32_16x16x32_bf16 v[82:85], v[152:155], v[222:225], v[82:85]
	v_mfma_f32_16x16x32_bf16 v[74:77], v[160:163], v[222:225], v[74:77]
	s_setprio 0
	s_setprio 1
	v_mfma_f32_16x16x32_bf16 v[118:121], v[164:167], v[194:197], v[118:121]
	v_mfma_f32_16x16x32_bf16 v[110:113], v[186:189], v[194:197], v[110:113]
	v_mfma_f32_16x16x32_bf16 v[102:105], v[164:167], v[202:205], v[102:105]
	v_mfma_f32_16x16x32_bf16 v[94:97], v[186:189], v[202:205], v[94:97]
	v_mfma_f32_16x16x32_bf16 v[86:89], v[164:167], v[210:213], v[86:89]
	v_mfma_f32_16x16x32_bf16 v[78:81], v[186:189], v[210:213], v[78:81]
	v_mfma_f32_16x16x32_bf16 v[70:73], v[164:167], v[218:221], v[70:73]
	v_mfma_f32_16x16x32_bf16 v[66:69], v[186:189], v[218:221], v[66:69]
	v_mfma_f32_16x16x32_bf16 v[118:121], v[182:185], v[198:201], v[118:121]
	v_mfma_f32_16x16x32_bf16 v[110:113], v[190:193], v[198:201], v[110:113]
	v_mfma_f32_16x16x32_bf16 v[102:105], v[182:185], v[206:209], v[102:105]
	v_mfma_f32_16x16x32_bf16 v[94:97], v[190:193], v[206:209], v[94:97]
	v_mfma_f32_16x16x32_bf16 v[86:89], v[182:185], v[214:217], v[86:89]
	v_mfma_f32_16x16x32_bf16 v[78:81], v[190:193], v[214:217], v[78:81]
	v_mfma_f32_16x16x32_bf16 v[70:73], v[182:185], v[222:225], v[70:73]
	v_mfma_f32_16x16x32_bf16 v[66:69], v[190:193], v[222:225], v[66:69]
	s_setprio 0
	s_barrier
; #define PG8_STAGE(bufoff, gbase, voff) do { _Pragma("unroll") for (int _i = 0; _i < 2; ++_i) \
;         __builtin_amdgcn_global_load_lds((const unsigned*)((const char*)(gbase) + (voff)[_i]), (PG8_LAS unsigned*)(lds + (bufoff) + ldsw + _i * 8192), 16, 0, 0); } while (0)
; #define PG8_LDA(dst, b, h) do { _Pragma("unroll") for (int m = 0; m < 4; ++m) _Pragma("unroll") for (int k = 0; k < 2; ++k) dst[m][k] = *(const PG8_LAS bf16x8*)(lds + PG8_SA(b, h) + aoff + m * 2048 + k * 1024); } while (0)
; #define PG8_MMA(ai, bj, At, Bt) do { __builtin_amdgcn_s_setprio(1); _Pragma("unroll") for (int m = 0; m < 4; ++m) _Pragma("unroll") for (int n = 0; n < 2; ++n) _Pragma("unroll") for (int k = 0; k < 2; ++k) \
;         acc[ai][bj][m][n] = __builtin_amdgcn_mfma_f32_16x16x32_bf16(Bt[n][k], At[m][k], acc[ai][bj][m][n], 0, 0, 0); __builtin_amdgcn_s_setprio(0); } while (0)
; #define PG8_WAIT_V(n) asm volatile("s_waitcnt vmcnt(" #n ")" ::: "memory")
; #define PG8_WAIT_L(n) asm volatile("s_waitcnt lgkmcnt(" #n ")" ::: "memory")
; #define PG8_BAR __builtin_amdgcn_s_barrier()
; #define PG8_SCHED __builtin_amdgcn_sched_barrier(0)
; template <class Epi, class Sched, bool ALIGN_EPI = false, bool SP2 = false>
; __device__ __forceinline__ void gemm_phase(PG8_LAS unsigned char* lds, const Gemm g, const Sched& S, const Epi& E, int tid_in) {
;     ...
;             PG8_LDA(At, 1, 1); PG8_STAGE(PG8_SB(1, 0), b3, voffB); PG8_STAGE(PG8_SB(1, 1), b3 + hstep, voffB); PG8_STAGE(PG8_SA(1, 0), a3, voffA);
;             PG8_WAIT_V(8); PG8_WAIT_L(0); PG8_BAR; PG8_MMA(1, 0, At, B0); PG8_MMA(1, 1, At, B1); PG8_BAR; PG8_SCHED;
;     ...
;         if constexpr (ALIGN_EPI) { if (wr == 0) PG8_BAR; }
	s_add_i32 s20, s63, s33
	v_lshl_add_u64 v[168:169], v[168:169], 0, s[90:91]
	s_mov_b32 m0, s20
	ds_read_b128 v[194:197], v147 offset:49152
	ds_read_b128 v[198:201], v147 offset:50176
	ds_read_b128 v[202:205], v147 offset:51200
	ds_read_b128 v[206:209], v147 offset:52224
	ds_read_b128 v[210:213], v147 offset:53248
	ds_read_b128 v[214:217], v147 offset:54272
	ds_read_b128 v[218:221], v147 offset:55296
	ds_read_b128 v[222:225], v147 offset:56320
	global_load_lds_dwordx4 v[168:169], off
	s_add_i32 m0, s20, 0x2000
	s_add_u32 s20, s24, 0x20080
	v_lshl_add_u64 v[168:169], v[226:227], 0, s[90:91]
	s_addc_u32 s21, s25, 0
	s_add_i32 s24, s55, s33
	global_load_lds_dwordx4 v[168:169], off
	s_mov_b32 m0, s24
	v_lshl_add_u64 v[168:169], s[20:21], 0, v[0:1]
	global_load_lds_dwordx4 v[168:169], off
	s_add_i32 m0, s24, 0x2000
	v_lshl_add_u64 v[168:169], s[20:21], 0, v[134:135]
	global_load_lds_dwordx4 v[168:169], off
	s_mov_b32 m0, s42
	v_lshl_add_u64 v[168:169], v[228:229], 0, s[90:91]
	global_load_lds_dwordx4 v[168:169], off
	s_mov_b32 m0, s43
	v_lshl_add_u64 v[168:169], v[240:241], 0, s[90:91]
	global_load_lds_dwordx4 v[168:169], off
	s_add_i32 s48, s48, 2
	s_add_u32 s0, s0, 0x100
	s_addc_u32 s15, s15, 0
	s_cmp_gt_u32 s48, 5
	s_mov_b64 s[20:21], s[22:23]
	s_waitcnt vmcnt(8)
	s_waitcnt lgkmcnt(0)
	s_barrier
	s_setprio 1
	s_waitcnt lgkmcnt(0)
	v_mfma_f32_16x16x32_bf16 v[62:65], v[148:151], v[194:197], v[62:65]
	v_mfma_f32_16x16x32_bf16 v[58:61], v[156:159], v[194:197], v[58:61]
	v_mfma_f32_16x16x32_bf16 v[50:53], v[148:151], v[202:205], v[50:53]
	v_mfma_f32_16x16x32_bf16 v[42:45], v[156:159], v[202:205], v[42:45]
	v_mfma_f32_16x16x32_bf16 v[34:37], v[148:151], v[210:213], v[34:37]
	v_mfma_f32_16x16x32_bf16 v[26:29], v[156:159], v[210:213], v[26:29]
	v_mfma_f32_16x16x32_bf16 v[18:21], v[148:151], v[218:221], v[18:21]
	v_mfma_f32_16x16x32_bf16 v[10:13], v[156:159], v[218:221], v[10:13]
	v_mfma_f32_16x16x32_bf16 v[62:65], v[152:155], v[198:201], v[62:65]
	v_mfma_f32_16x16x32_bf16 v[58:61], v[160:163], v[198:201], v[58:61]
	v_mfma_f32_16x16x32_bf16 v[50:53], v[152:155], v[206:209], v[50:53]
	v_mfma_f32_16x16x32_bf16 v[42:45], v[160:163], v[206:209], v[42:45]
	v_mfma_f32_16x16x32_bf16 v[34:37], v[152:155], v[214:217], v[34:37]
	v_mfma_f32_16x16x32_bf16 v[26:29], v[160:163], v[214:217], v[26:29]
	v_mfma_f32_16x16x32_bf16 v[18:21], v[152:155], v[222:225], v[18:21]
	v_mfma_f32_16x16x32_bf16 v[10:13], v[160:163], v[222:225], v[10:13]
	s_setprio 0
	s_setprio 1
	v_mfma_f32_16x16x32_bf16 v[54:57], v[164:167], v[194:197], v[54:57]
	v_mfma_f32_16x16x32_bf16 v[46:49], v[186:189], v[194:197], v[46:49]
	v_mfma_f32_16x16x32_bf16 v[38:41], v[164:167], v[202:205], v[38:41]
	v_mfma_f32_16x16x32_bf16 v[30:33], v[186:189], v[202:205], v[30:33]
	v_mfma_f32_16x16x32_bf16 v[22:25], v[164:167], v[210:213], v[22:25]
	v_mfma_f32_16x16x32_bf16 v[14:17], v[186:189], v[210:213], v[14:17]
	v_mfma_f32_16x16x32_bf16 v[6:9], v[164:167], v[218:221], v[6:9]
	v_mfma_f32_16x16x32_bf16 v[2:5], v[186:189], v[218:221], v[2:5]
	v_mfma_f32_16x16x32_bf16 v[54:57], v[182:185], v[198:201], v[54:57]
	v_mfma_f32_16x16x32_bf16 v[46:49], v[190:193], v[198:201], v[46:49]
	v_mfma_f32_16x16x32_bf16 v[38:41], v[182:185], v[206:209], v[38:41]
	v_mfma_f32_16x16x32_bf16 v[30:33], v[190:193], v[206:209], v[30:33]
	v_mfma_f32_16x16x32_bf16 v[22:25], v[182:185], v[214:217], v[22:25]
	v_mfma_f32_16x16x32_bf16 v[14:17], v[190:193], v[214:217], v[14:17]
	v_mfma_f32_16x16x32_bf16 v[6:9], v[182:185], v[222:225], v[6:9]
	v_mfma_f32_16x16x32_bf16 v[2:5], v[190:193], v[222:225], v[2:5]
	s_setprio 0
	s_barrier
	s_cbranch_scc0 .LBB0_627
	s_and_b64 vcc, exec, s[12:13]
	s_cbranch_vccz .LBB0_630
	s_barrier

; #define PG8_STAGE(bufoff, gbase, voff) do { _Pragma("unroll") for (int _i = 0; _i < 2; ++_i) \
;         __builtin_amdgcn_global_load_lds((const unsigned*)((const char*)(gbase) + (voff)[_i]), (PG8_LAS unsigned*)(lds + (bufoff) + ldsw + _i * 8192), 16, 0, 0); } while (0)
; #define PG8_LDA(dst, b, h) do { _Pragma("unroll") for (int m = 0; m < 4; ++m) _Pragma("unroll") for (int k = 0; k < 2; ++k) dst[m][k] = *(const PG8_LAS bf16x8*)(lds + PG8_SA(b, h) + aoff + m * 2048 + k * 1024); } while (0)
; #define PG8_LDB(dst, b, h) do { _Pragma("unroll") for (int n = 0; n < 2; ++n) _Pragma("unroll") for (int k = 0; k < 2; ++k) dst[n][k] = *(const PG8_LAS bf16x8*)(lds + PG8_SB(b, h) + boff + n * 2048 + k * 1024); } while (0)
; #define PG8_MMA(ai, bj, At, Bt) do { __builtin_amdgcn_s_setprio(1); _Pragma("unroll") for (int m = 0; m < 4; ++m) _Pragma("unroll") for (int n = 0; n < 2; ++n) _Pragma("unroll") for (int k = 0; k < 2; ++k) \
;         acc[ai][bj][m][n] = __builtin_amdgcn_mfma_f32_16x16x32_bf16(Bt[n][k], At[m][k], acc[ai][bj][m][n], 0, 0, 0); __builtin_amdgcn_s_setprio(0); } while (0)
; #define PG8_WAIT_V(n) asm volatile("s_waitcnt vmcnt(" #n ")" ::: "memory")
; #define PG8_WAIT_L(n) asm volatile("s_waitcnt lgkmcnt(" #n ")" ::: "memory")
; template <class Epi, class Sched, bool ALIGN_EPI = false, bool SP2 = false>
; __device__ __forceinline__ void gemm_phase(PG8_LAS unsigned char* lds, const Gemm g, const Sched& S, const Epi& E, int tid_in) {
;     ...
;             const bool last = (t == nt - 2);
;             const char* a1 = cA + (size_t)(t + 1) * kstep;
;             const char* a2 = last ? nA : cA + (size_t)(t + 2) * kstep; const char* b2 = last ? nB : cB + (size_t)(t + 2) * kstep;
;             const char* a3 = a2 + kstep; const char* b3 = b2 + kstep;
;             if (last && has_next) S.a_ready(nxt);
;             if constexpr (SP2) {
;             PG8_LDB(B0, 0, 0); PG8_LDB(B1, 0, 1); PG8_SCHED; PG8_LDA(At, 0, 0); PG8_STAGE(PG8_SA(1, 1), a1 + hstepA, voffA);
;             PG8_WAIT_V(8); PG8_WAIT_L(0); PG8_BAR; PG8_MMA(0, 0, At, B0); PG8_MMA(0, 1, At, B1); PG8_BAR; PG8_SCHED;
;             PG8_LDA(At, 0, 1); PG8_STAGE(PG8_SB(0, 0), b2, voffB); PG8_STAGE(PG8_SB(0, 1), b2 + hstep, voffB); PG8_STAGE(PG8_SA(0, 0), a2, voffA);
;             PG8_WAIT_V(8); PG8_WAIT_L(0); PG8_BAR; PG8_MMA(1, 0, At, B0); PG8_MMA(1, 1, At, B1); PG8_BAR; PG8_SCHED;
.LBB0_900:
	v_add_u32_e32 v0, s4, v242
	ds_read_b128 v[132:135], v0
	ds_read_b128 v[144:147], v0 offset:1024
	ds_read_b128 v[148:151], v0 offset:2048
	ds_read_b128 v[152:155], v0 offset:3072
	v_add_u32_e32 v0, s5, v242
	ds_read_b128 v[156:159], v0
	ds_read_b128 v[160:163], v0 offset:1024
	ds_read_b128 v[164:167], v0 offset:2048
	ds_read_b128 v[182:185], v0 offset:3072
	s_add_i32 vcc_hi, s10, 2
	s_add_u32 s11, s8, 0xfffc0080
	s_addc_u32 s12, s9, -1
	s_cmp_eq_u32 s68, s10
	s_cselect_b32 s10, s47, s76
	s_cselect_b32 s13, s30, s12
	s_cselect_b32 s12, s31, s11
	s_cselect_b32 s11, s46, vcc_lo
	v_lshl_add_u64 v[2:3], s[8:9], 0, v[140:141]
	s_add_i32 m0, s37, 0xc000
	ds_read_b128 v[186:189], v243
	ds_read_b128 v[190:193], v243 offset:1024
	ds_read_b128 v[194:197], v243 offset:2048
	ds_read_b128 v[198:201], v243 offset:3072
	ds_read_b128 v[202:205], v243 offset:4096
	ds_read_b128 v[206:209], v243 offset:5120
	ds_read_b128 v[210:213], v243 offset:6144
	ds_read_b128 v[214:217], v243 offset:7168
	global_load_lds_dwordx4 v[2:3], off
	s_add_i32 m0, s37, 0xe000
	v_lshl_add_u64 v[2:3], s[8:9], 0, v[142:143]
	global_load_lds_dwordx4 v[2:3], off
	s_waitcnt vmcnt(8)
	s_waitcnt lgkmcnt(0)
	s_barrier
	s_setprio 1
	s_waitcnt lgkmcnt(0)
	v_mfma_f32_16x16x32_bf16 v[128:131], v[132:135], v[186:189], v[128:131]
	v_mfma_f32_16x16x32_bf16 v[124:127], v[148:151], v[186:189], v[124:127]
	v_mfma_f32_16x16x32_bf16 v[120:123], v[132:135], v[194:197], v[120:123]
	v_mfma_f32_16x16x32_bf16 v[116:119], v[148:151], v[194:197], v[116:119]
	v_mfma_f32_16x16x32_bf16 v[112:115], v[132:135], v[202:205], v[112:115]
	v_mfma_f32_16x16x32_bf16 v[108:111], v[148:151], v[202:205], v[108:111]
	v_mfma_f32_16x16x32_bf16 v[104:107], v[132:135], v[210:213], v[104:107]
	v_mfma_f32_16x16x32_bf16 v[100:103], v[148:151], v[210:213], v[100:103]
	v_mfma_f32_16x16x32_bf16 v[128:131], v[144:147], v[190:193], v[128:131]
	v_mfma_f32_16x16x32_bf16 v[124:127], v[152:155], v[190:193], v[124:127]
	v_mfma_f32_16x16x32_bf16 v[120:123], v[144:147], v[198:201], v[120:123]
	v_mfma_f32_16x16x32_bf16 v[116:119], v[152:155], v[198:201], v[116:119]
	v_mfma_f32_16x16x32_bf16 v[112:115], v[144:147], v[206:209], v[112:115]
	v_mfma_f32_16x16x32_bf16 v[108:111], v[152:155], v[206:209], v[108:111]
	v_mfma_f32_16x16x32_bf16 v[104:107], v[144:147], v[214:217], v[104:107]
	v_mfma_f32_16x16x32_bf16 v[100:103], v[152:155], v[214:217], v[100:103]
	s_setprio 0
	s_setprio 1
	v_mfma_f32_16x16x32_bf16 v[96:99], v[156:159], v[186:189], v[96:99]
	v_mfma_f32_16x16x32_bf16 v[92:95], v[164:167], v[186:189], v[92:95]
	v_mfma_f32_16x16x32_bf16 v[88:91], v[156:159], v[194:197], v[88:91]
	v_mfma_f32_16x16x32_bf16 v[84:87], v[164:167], v[194:197], v[84:87]
	v_mfma_f32_16x16x32_bf16 v[80:83], v[156:159], v[202:205], v[80:83]
	v_mfma_f32_16x16x32_bf16 v[76:79], v[164:167], v[202:205], v[76:79]
	v_mfma_f32_16x16x32_bf16 v[72:75], v[156:159], v[210:213], v[72:75]
	v_mfma_f32_16x16x32_bf16 v[68:71], v[164:167], v[210:213], v[68:71]
	v_mfma_f32_16x16x32_bf16 v[96:99], v[160:163], v[190:193], v[96:99]
	v_mfma_f32_16x16x32_bf16 v[92:95], v[182:185], v[190:193], v[92:95]
	v_mfma_f32_16x16x32_bf16 v[88:91], v[160:163], v[198:201], v[88:91]
	v_mfma_f32_16x16x32_bf16 v[84:87], v[182:185], v[198:201], v[84:87]
	v_mfma_f32_16x16x32_bf16 v[80:83], v[160:163], v[206:209], v[80:83]
	v_mfma_f32_16x16x32_bf16 v[76:79], v[182:185], v[206:209], v[76:79]
	v_mfma_f32_16x16x32_bf16 v[72:75], v[160:163], v[214:217], v[72:75]
	v_mfma_f32_16x16x32_bf16 v[68:71], v[182:185], v[214:217], v[68:71]
	s_setprio 0
	s_barrier
	s_add_i32 s64, s4, s36
	v_lshl_add_u64 v[168:169], s[10:11], 0, v[136:137]
	s_mov_b32 m0, s64
	ds_read_b128 v[186:189], v243 offset:16384
	ds_read_b128 v[190:193], v243 offset:17408
	ds_read_b128 v[194:197], v243 offset:18432
	ds_read_b128 v[198:201], v243 offset:19456
	ds_read_b128 v[202:205], v243 offset:20480
	ds_read_b128 v[206:209], v243 offset:21504
	ds_read_b128 v[210:213], v243 offset:22528
	ds_read_b128 v[214:217], v243 offset:23552
	global_load_lds_dwordx4 v[168:169], off
	s_add_i32 m0, s64, 0x2000
	s_add_u32 s64, s10, 0x40000
	v_lshl_add_u64 v[218:219], s[10:11], 0, v[138:139]
	s_addc_u32 s65, s11, 0
	s_add_i32 s95, s5, s36
	global_load_lds_dwordx4 v[218:219], off
	v_lshl_add_u64 v[2:3], s[64:65], 0, v[136:137]
	s_mov_b32 m0, s95
	v_lshl_add_u64 v[220:221], s[12:13], 0, v[136:137]
	global_load_lds_dwordx4 v[2:3], off
	v_lshl_add_u64 v[2:3], s[64:65], 0, v[138:139]
	s_add_i32 m0, s95, 0x2000
	v_lshl_add_u64 v[222:223], s[12:13], 0, v[138:139]
	global_load_lds_dwordx4 v[2:3], off
	s_waitcnt vmcnt(6)
	s_waitcnt lgkmcnt(0)
	s_barrier
; #define PG8_STAGE(bufoff, gbase, voff) do { _Pragma("unroll") for (int _i = 0; _i < 2; ++_i) \
;         __builtin_amdgcn_global_load_lds((const unsigned*)((const char*)(gbase) + (voff)[_i]), (PG8_LAS unsigned*)(lds + (bufoff) + ldsw + _i * 8192), 16, 0, 0); } while (0)
; #define PG8_LDA(dst, b, h) do { _Pragma("unroll") for (int m = 0; m < 4; ++m) _Pragma("unroll") for (int k = 0; k < 2; ++k) dst[m][k] = *(const PG8_LAS bf16x8*)(lds + PG8_SA(b, h) + aoff + m * 2048 + k * 1024); } while (0)
; #define PG8_LDB(dst, b, h) do { _Pragma("unroll") for (int n = 0; n < 2; ++n) _Pragma("unroll") for (int k = 0; k < 2; ++k) dst[n][k] = *(const PG8_LAS bf16x8*)(lds + PG8_SB(b, h) + boff + n * 2048 + k * 1024); } while (0)
; #define PG8_MMA(ai, bj, At, Bt) do { __builtin_amdgcn_s_setprio(1); _Pragma("unroll") for (int m = 0; m < 4; ++m) _Pragma("unroll") for (int n = 0; n < 2; ++n) _Pragma("unroll") for (int k = 0; k < 2; ++k) \
;         acc[ai][bj][m][n] = __builtin_amdgcn_mfma_f32_16x16x32_bf16(Bt[n][k], At[m][k], acc[ai][bj][m][n], 0, 0, 0); __builtin_amdgcn_s_setprio(0); } while (0)
; #define PG8_WAIT_V(n) asm volatile("s_waitcnt vmcnt(" #n ")" ::: "memory")
; #define PG8_WAIT_L(n) asm volatile("s_waitcnt lgkmcnt(" #n ")" ::: "memory")
; #define PG8_BAR __builtin_amdgcn_s_barrier()
; #define PG8_SCHED __builtin_amdgcn_sched_barrier(0)
; template <class Epi, class Sched, bool ALIGN_EPI = false, bool SP2 = false>
; __device__ __forceinline__ void gemm_phase(PG8_LAS unsigned char* lds, const Gemm g, const Sched& S, const Epi& E, int tid_in) {
;     ...
;             PG8_WAIT_V(8); PG8_WAIT_L(0); PG8_BAR; PG8_MMA(1, 0, At, B0); PG8_MMA(1, 1, At, B1); PG8_BAR; PG8_SCHED;
;             PG8_LDB(B0, 1, 0); PG8_LDB(B1, 1, 1); PG8_SCHED; PG8_LDA(At, 1, 0); PG8_STAGE(PG8_SA(0, 1), a2 + hstepA, voffA);
;             PG8_WAIT_V(8); PG8_WAIT_L(0); PG8_BAR; PG8_MMA(0, 0, At, B0); PG8_MMA(0, 1, At, B1); PG8_BAR; PG8_SCHED;
;             PG8_LDA(At, 1, 1); PG8_STAGE(PG8_SB(1, 0), b3, voffB); PG8_STAGE(PG8_SB(1, 1), b3 + hstep, voffB); PG8_STAGE(PG8_SA(1, 0), a3, voffA);
;             PG8_WAIT_V(8); PG8_WAIT_L(0); PG8_BAR; PG8_MMA(1, 0, At, B0); PG8_MMA(1, 1, At, B1); PG8_BAR; PG8_SCHED;
	s_setprio 1
	s_waitcnt lgkmcnt(0)
	v_mfma_f32_16x16x32_bf16 v[64:67], v[132:135], v[186:189], v[64:67]
	v_mfma_f32_16x16x32_bf16 v[60:63], v[148:151], v[186:189], v[60:63]
	v_mfma_f32_16x16x32_bf16 v[56:59], v[132:135], v[194:197], v[56:59]
	v_mfma_f32_16x16x32_bf16 v[52:55], v[148:151], v[194:197], v[52:55]
	v_mfma_f32_16x16x32_bf16 v[48:51], v[132:135], v[202:205], v[48:51]
	v_mfma_f32_16x16x32_bf16 v[44:47], v[148:151], v[202:205], v[44:47]
	v_mfma_f32_16x16x32_bf16 v[40:43], v[132:135], v[210:213], v[40:43]
	v_mfma_f32_16x16x32_bf16 v[36:39], v[148:151], v[210:213], v[36:39]
	v_mfma_f32_16x16x32_bf16 v[64:67], v[144:147], v[190:193], v[64:67]
	v_mfma_f32_16x16x32_bf16 v[60:63], v[152:155], v[190:193], v[60:63]
	v_mfma_f32_16x16x32_bf16 v[56:59], v[144:147], v[198:201], v[56:59]
	v_mfma_f32_16x16x32_bf16 v[52:55], v[152:155], v[198:201], v[52:55]
	v_mfma_f32_16x16x32_bf16 v[48:51], v[144:147], v[206:209], v[48:51]
	v_mfma_f32_16x16x32_bf16 v[44:47], v[152:155], v[206:209], v[44:47]
	v_mfma_f32_16x16x32_bf16 v[40:43], v[144:147], v[214:217], v[40:43]
	v_mfma_f32_16x16x32_bf16 v[36:39], v[152:155], v[214:217], v[36:39]
	s_setprio 0
	s_setprio 1
	v_mfma_f32_16x16x32_bf16 v[32:35], v[156:159], v[186:189], v[32:35]
	v_mfma_f32_16x16x32_bf16 v[28:31], v[164:167], v[186:189], v[28:31]
	v_mfma_f32_16x16x32_bf16 v[24:27], v[156:159], v[194:197], v[24:27]
	v_mfma_f32_16x16x32_bf16 v[20:23], v[164:167], v[194:197], v[20:23]
	v_mfma_f32_16x16x32_bf16 v[16:19], v[156:159], v[202:205], v[16:19]
	v_mfma_f32_16x16x32_bf16 v[12:15], v[164:167], v[202:205], v[12:15]
	v_mfma_f32_16x16x32_bf16 v[8:11], v[156:159], v[210:213], v[8:11]
	v_mfma_f32_16x16x32_bf16 v[2:5], v[164:167], v[210:213], v[4:7]
	v_mfma_f32_16x16x32_bf16 v[32:35], v[160:163], v[190:193], v[32:35]
	v_mfma_f32_16x16x32_bf16 v[28:31], v[182:185], v[190:193], v[28:31]
	v_mfma_f32_16x16x32_bf16 v[24:27], v[160:163], v[198:201], v[24:27]
	v_mfma_f32_16x16x32_bf16 v[20:23], v[182:185], v[198:201], v[20:23]
	v_mfma_f32_16x16x32_bf16 v[16:19], v[160:163], v[206:209], v[16:19]
	v_mfma_f32_16x16x32_bf16 v[12:15], v[182:185], v[206:209], v[12:15]
	v_mfma_f32_16x16x32_bf16 v[8:11], v[160:163], v[214:217], v[8:11]
	v_mfma_f32_16x16x32_bf16 v[2:5], v[182:185], v[214:217], v[2:5]
	s_setprio 0
	s_barrier
	s_mov_b32 m0, s37
	s_nop 0
	global_load_lds_dwordx4 v[220:221], off
	s_mov_b32 m0, s38
	s_nop 0
	global_load_lds_dwordx4 v[222:223], off
	v_add_u32_e32 v0, s63, v242
	ds_read_b128 v[132:135], v0
	ds_read_b128 v[144:147], v0 offset:1024
	ds_read_b128 v[148:151], v0 offset:2048
	ds_read_b128 v[152:155], v0 offset:3072
	v_add_u32_e32 v0, s55, v242
	ds_read_b128 v[156:159], v0
	ds_read_b128 v[160:163], v0 offset:1024
	ds_read_b128 v[164:167], v0 offset:2048
	ds_read_b128 v[182:185], v0 offset:3072
	s_add_u32 s12, s12, 0x40000
	s_addc_u32 s13, s13, 0
	s_mov_b32 m0, s39
	v_lshl_add_u64 v[6:7], s[12:13], 0, v[136:137]
	ds_read_b128 v[186:189], v243 offset:32768
	ds_read_b128 v[190:193], v243 offset:33792
	ds_read_b128 v[194:197], v243 offset:34816
	ds_read_b128 v[198:201], v243 offset:35840
	ds_read_b128 v[202:205], v243 offset:36864
	ds_read_b128 v[206:209], v243 offset:37888
	ds_read_b128 v[210:213], v243 offset:38912
	ds_read_b128 v[214:217], v243 offset:39936
	global_load_lds_dwordx4 v[6:7], off
	s_mov_b32 m0, s40
	v_lshl_add_u64 v[6:7], s[12:13], 0, v[138:139]
	global_load_lds_dwordx4 v[6:7], off
	s_waitcnt vmcnt(8)
	s_waitcnt lgkmcnt(0)
	s_barrier
	s_setprio 1
	s_waitcnt lgkmcnt(0)
	v_mfma_f32_16x16x32_bf16 v[128:131], v[132:135], v[186:189], v[128:131]
	v_mfma_f32_16x16x32_bf16 v[124:127], v[148:151], v[186:189], v[124:127]
	v_mfma_f32_16x16x32_bf16 v[120:123], v[132:135], v[194:197], v[120:123]
	v_mfma_f32_16x16x32_bf16 v[116:119], v[148:151], v[194:197], v[116:119]
	v_mfma_f32_16x16x32_bf16 v[112:115], v[132:135], v[202:205], v[112:115]
	v_mfma_f32_16x16x32_bf16 v[108:111], v[148:151], v[202:205], v[108:111]
	v_mfma_f32_16x16x32_bf16 v[104:107], v[132:135], v[210:213], v[104:107]
	v_mfma_f32_16x16x32_bf16 v[100:103], v[148:151], v[210:213], v[100:103]
	v_mfma_f32_16x16x32_bf16 v[128:131], v[144:147], v[190:193], v[128:131]
	v_mfma_f32_16x16x32_bf16 v[124:127], v[152:155], v[190:193], v[124:127]
	v_mfma_f32_16x16x32_bf16 v[120:123], v[144:147], v[198:201], v[120:123]
	v_mfma_f32_16x16x32_bf16 v[116:119], v[152:155], v[198:201], v[116:119]
	v_mfma_f32_16x16x32_bf16 v[112:115], v[144:147], v[206:209], v[112:115]
	v_mfma_f32_16x16x32_bf16 v[108:111], v[152:155], v[206:209], v[108:111]
	v_mfma_f32_16x16x32_bf16 v[104:107], v[144:147], v[214:217], v[104:107]
	v_mfma_f32_16x16x32_bf16 v[100:103], v[152:155], v[214:217], v[100:103]
	s_setprio 0
	s_setprio 1
	v_mfma_f32_16x16x32_bf16 v[96:99], v[156:159], v[186:189], v[96:99]
	v_mfma_f32_16x16x32_bf16 v[92:95], v[164:167], v[186:189], v[92:95]
	v_mfma_f32_16x16x32_bf16 v[88:91], v[156:159], v[194:197], v[88:91]
	v_mfma_f32_16x16x32_bf16 v[84:87], v[164:167], v[194:197], v[84:87]
	v_mfma_f32_16x16x32_bf16 v[80:83], v[156:159], v[202:205], v[80:83]
	v_mfma_f32_16x16x32_bf16 v[76:79], v[164:167], v[202:205], v[76:79]
	v_mfma_f32_16x16x32_bf16 v[72:75], v[156:159], v[210:213], v[72:75]
	v_mfma_f32_16x16x32_bf16 v[68:71], v[164:167], v[210:213], v[68:71]
	v_mfma_f32_16x16x32_bf16 v[96:99], v[160:163], v[190:193], v[96:99]
	v_mfma_f32_16x16x32_bf16 v[92:95], v[182:185], v[190:193], v[92:95]
	v_mfma_f32_16x16x32_bf16 v[88:91], v[160:163], v[198:201], v[88:91]
	v_mfma_f32_16x16x32_bf16 v[84:87], v[182:185], v[198:201], v[84:87]
	v_mfma_f32_16x16x32_bf16 v[80:83], v[160:163], v[206:209], v[80:83]
	v_mfma_f32_16x16x32_bf16 v[76:79], v[182:185], v[206:209], v[76:79]
	v_mfma_f32_16x16x32_bf16 v[72:75], v[160:163], v[214:217], v[72:75]
	v_mfma_f32_16x16x32_bf16 v[68:71], v[182:185], v[214:217], v[68:71]
	s_setprio 0
	s_barrier
; #define PG8_STAGE(bufoff, gbase, voff) do { _Pragma("unroll") for (int _i = 0; _i < 2; ++_i) \
;         __builtin_amdgcn_global_load_lds((const unsigned*)((const char*)(gbase) + (voff)[_i]), (PG8_LAS unsigned*)(lds + (bufoff) + ldsw + _i * 8192), 16, 0, 0); } while (0)
; #define PG8_LDA(dst, b, h) do { _Pragma("unroll") for (int m = 0; m < 4; ++m) _Pragma("unroll") for (int k = 0; k < 2; ++k) dst[m][k] = *(const PG8_LAS bf16x8*)(lds + PG8_SA(b, h) + aoff + m * 2048 + k * 1024); } while (0)
; #define PG8_MMA(ai, bj, At, Bt) do { __builtin_amdgcn_s_setprio(1); _Pragma("unroll") for (int m = 0; m < 4; ++m) _Pragma("unroll") for (int n = 0; n < 2; ++n) _Pragma("unroll") for (int k = 0; k < 2; ++k) \
;         acc[ai][bj][m][n] = __builtin_amdgcn_mfma_f32_16x16x32_bf16(Bt[n][k], At[m][k], acc[ai][bj][m][n], 0, 0, 0); __builtin_amdgcn_s_setprio(0); } while (0)
; #define PG8_WAIT_V(n) asm volatile("s_waitcnt vmcnt(" #n ")" ::: "memory")
; #define PG8_WAIT_L(n) asm volatile("s_waitcnt lgkmcnt(" #n ")" ::: "memory")
; #define PG8_BAR __builtin_amdgcn_s_barrier()
; #define PG8_SCHED __builtin_amdgcn_sched_barrier(0)
; template <class Epi, class Sched, bool ALIGN_EPI = false, bool SP2 = false>
; __device__ __forceinline__ void gemm_phase(PG8_LAS unsigned char* lds, const Gemm g, const Sched& S, const Epi& E, int tid_in) {
;     ...
;             PG8_LDA(At, 1, 1); PG8_STAGE(PG8_SB(1, 0), b3, voffB); PG8_STAGE(PG8_SB(1, 1), b3 + hstep, voffB); PG8_STAGE(PG8_SA(1, 0), a3, voffA);
;             PG8_WAIT_V(8); PG8_WAIT_L(0); PG8_BAR; PG8_MMA(1, 0, At, B0); PG8_MMA(1, 1, At, B1); PG8_BAR; PG8_SCHED;
;     ...
;         if constexpr (ALIGN_EPI) { if (wr == 0) PG8_BAR; }
	s_add_i32 s12, s63, s36
	v_lshl_add_u64 v[6:7], v[168:169], 0, s[90:91]
	s_mov_b32 m0, s12
	ds_read_b128 v[186:189], v243 offset:49152
	ds_read_b128 v[190:193], v243 offset:50176
	ds_read_b128 v[194:197], v243 offset:51200
	ds_read_b128 v[198:201], v243 offset:52224
	ds_read_b128 v[202:205], v243 offset:53248
	ds_read_b128 v[206:209], v243 offset:54272
	ds_read_b128 v[210:213], v243 offset:55296
	ds_read_b128 v[214:217], v243 offset:56320
	global_load_lds_dwordx4 v[6:7], off
	s_add_i32 m0, s12, 0x2000
	s_add_u32 s10, s10, 0x40080
	v_lshl_add_u64 v[6:7], v[218:219], 0, s[90:91]
	s_addc_u32 s11, s11, 0
	s_add_i32 s12, s55, s36
	global_load_lds_dwordx4 v[6:7], off
	s_mov_b32 m0, s12
	v_lshl_add_u64 v[6:7], s[10:11], 0, v[136:137]
	global_load_lds_dwordx4 v[6:7], off
	s_add_i32 m0, s12, 0x2000
	v_lshl_add_u64 v[6:7], s[10:11], 0, v[138:139]
	global_load_lds_dwordx4 v[6:7], off
	s_mov_b32 m0, s49
	v_lshl_add_u64 v[6:7], v[220:221], 0, s[90:91]
	global_load_lds_dwordx4 v[6:7], off
	s_mov_b32 m0, s79
	v_lshl_add_u64 v[6:7], v[222:223], 0, s[90:91]
	global_load_lds_dwordx4 v[6:7], off
	s_add_u32 s8, s8, 0x100
	s_addc_u32 s9, s9, 0
	s_add_u32 s76, s76, 0x100
	s_addc_u32 vcc_lo, vcc_lo, 0
	s_cmp_ge_i32 vcc_hi, s14
	s_mov_b32 s10, vcc_hi
	s_waitcnt vmcnt(8)
	s_waitcnt lgkmcnt(0)
	s_barrier
	s_setprio 1
	s_waitcnt lgkmcnt(0)
	v_mfma_f32_16x16x32_bf16 v[64:67], v[132:135], v[186:189], v[64:67]
	v_mfma_f32_16x16x32_bf16 v[60:63], v[148:151], v[186:189], v[60:63]
	v_mfma_f32_16x16x32_bf16 v[56:59], v[132:135], v[194:197], v[56:59]
	v_mfma_f32_16x16x32_bf16 v[52:55], v[148:151], v[194:197], v[52:55]
	v_mfma_f32_16x16x32_bf16 v[48:51], v[132:135], v[202:205], v[48:51]
	v_mfma_f32_16x16x32_bf16 v[44:47], v[148:151], v[202:205], v[44:47]
	v_mfma_f32_16x16x32_bf16 v[40:43], v[132:135], v[210:213], v[40:43]
	v_mfma_f32_16x16x32_bf16 v[36:39], v[148:151], v[210:213], v[36:39]
	v_mfma_f32_16x16x32_bf16 v[64:67], v[144:147], v[190:193], v[64:67]
	v_mfma_f32_16x16x32_bf16 v[60:63], v[152:155], v[190:193], v[60:63]
	v_mfma_f32_16x16x32_bf16 v[56:59], v[144:147], v[198:201], v[56:59]
	v_mfma_f32_16x16x32_bf16 v[52:55], v[152:155], v[198:201], v[52:55]
	v_mfma_f32_16x16x32_bf16 v[48:51], v[144:147], v[206:209], v[48:51]
	v_mfma_f32_16x16x32_bf16 v[44:47], v[152:155], v[206:209], v[44:47]
	v_mfma_f32_16x16x32_bf16 v[40:43], v[144:147], v[214:217], v[40:43]
	v_mfma_f32_16x16x32_bf16 v[36:39], v[152:155], v[214:217], v[36:39]
	s_setprio 0
	s_setprio 1
	v_mfma_f32_16x16x32_bf16 v[32:35], v[156:159], v[186:189], v[32:35]
	v_mfma_f32_16x16x32_bf16 v[28:31], v[164:167], v[186:189], v[28:31]
	v_mfma_f32_16x16x32_bf16 v[24:27], v[156:159], v[194:197], v[24:27]
	v_mfma_f32_16x16x32_bf16 v[20:23], v[164:167], v[194:197], v[20:23]
	v_mfma_f32_16x16x32_bf16 v[16:19], v[156:159], v[202:205], v[16:19]
	v_mfma_f32_16x16x32_bf16 v[12:15], v[164:167], v[202:205], v[12:15]
	v_mfma_f32_16x16x32_bf16 v[6:9], v[156:159], v[210:213], v[8:11]
	v_mfma_f32_16x16x32_bf16 v[2:5], v[164:167], v[210:213], v[2:5]
	v_mfma_f32_16x16x32_bf16 v[32:35], v[160:163], v[190:193], v[32:35]
	v_mfma_f32_16x16x32_bf16 v[28:31], v[182:185], v[190:193], v[28:31]
	v_mfma_f32_16x16x32_bf16 v[24:27], v[160:163], v[198:201], v[24:27]
	v_mfma_f32_16x16x32_bf16 v[20:23], v[182:185], v[198:201], v[20:23]
	v_mfma_f32_16x16x32_bf16 v[16:19], v[160:163], v[206:209], v[16:19]
	v_mfma_f32_16x16x32_bf16 v[12:15], v[182:185], v[206:209], v[12:15]
	v_mfma_f32_16x16x32_bf16 v[8:11], v[160:163], v[214:217], v[6:9]
	v_mfma_f32_16x16x32_bf16 v[4:7], v[182:185], v[214:217], v[2:5]
	s_setprio 0
	s_barrier
	s_cbranch_scc0 .LBB0_900
	s_and_b64 vcc, exec, s[18:19]
	s_cbranch_vccz .LBB0_903
	s_barrier

; #define PG8_STAGE(bufoff, gbase, voff) do { _Pragma("unroll") for (int _i = 0; _i < 2; ++_i) \
;         __builtin_amdgcn_global_load_lds((const unsigned*)((const char*)(gbase) + (voff)[_i]), (PG8_LAS unsigned*)(lds + (bufoff) + ldsw + _i * 8192), 16, 0, 0); } while (0)
; #define PG8_LDA(dst, b, h) do { _Pragma("unroll") for (int m = 0; m < 4; ++m) _Pragma("unroll") for (int k = 0; k < 2; ++k) dst[m][k] = *(const PG8_LAS bf16x8*)(lds + PG8_SA(b, h) + aoff + m * 2048 + k * 1024); } while (0)
; #define PG8_LDB(dst, b, h) do { _Pragma("unroll") for (int n = 0; n < 2; ++n) _Pragma("unroll") for (int k = 0; k < 2; ++k) dst[n][k] = *(const PG8_LAS bf16x8*)(lds + PG8_SB(b, h) + boff + n * 2048 + k * 1024); } while (0)
; #define PG8_MMA(ai, bj, At, Bt) do { __builtin_amdgcn_s_setprio(1); _Pragma("unroll") for (int m = 0; m < 4; ++m) _Pragma("unroll") for (int n = 0; n < 2; ++n) _Pragma("unroll") for (int k = 0; k < 2; ++k) \
;         acc[ai][bj][m][n] = __builtin_amdgcn_mfma_f32_16x16x32_bf16(Bt[n][k], At[m][k], acc[ai][bj][m][n], 0, 0, 0); __builtin_amdgcn_s_setprio(0); } while (0)
; #define PG8_WAIT_V(n) asm volatile("s_waitcnt vmcnt(" #n ")" ::: "memory")
; #define PG8_WAIT_L(n) asm volatile("s_waitcnt lgkmcnt(" #n ")" ::: "memory")
; template <class Epi, class Sched, bool ALIGN_EPI = false, bool SP2 = false>
; __device__ __forceinline__ void gemm_phase(PG8_LAS unsigned char* lds, const Gemm g, const Sched& S, const Epi& E, int tid_in) {
;     ...
;             const bool last = (t == nt - 2);
;             const char* a1 = cA + (size_t)(t + 1) * kstep;
;             const char* a2 = last ? nA : cA + (size_t)(t + 2) * kstep; const char* b2 = last ? nB : cB + (size_t)(t + 2) * kstep;
;             const char* a3 = a2 + kstep; const char* b3 = b2 + kstep;
;             if (last && has_next) S.a_ready(nxt);
;             if constexpr (SP2) {
;             PG8_LDB(B0, 0, 0); PG8_LDB(B1, 0, 1); PG8_SCHED; PG8_LDA(At, 0, 0); PG8_STAGE(PG8_SA(1, 1), a1 + hstepA, voffA);
;             PG8_WAIT_V(8); PG8_WAIT_L(0); PG8_BAR; PG8_MMA(0, 0, At, B0); PG8_MMA(0, 1, At, B1); PG8_BAR; PG8_SCHED;
;             PG8_LDA(At, 0, 1); PG8_STAGE(PG8_SB(0, 0), b2, voffB); PG8_STAGE(PG8_SB(0, 1), b2 + hstep, voffB); PG8_STAGE(PG8_SA(0, 0), a2, voffA);
;             PG8_WAIT_V(8); PG8_WAIT_L(0); PG8_BAR; PG8_MMA(1, 0, At, B0); PG8_MMA(1, 1, At, B1); PG8_BAR; PG8_SCHED;
.LBB0_1348:
	v_add_u32_e32 v152, s4, v146
	v_add_u32_e32 v168, s5, v146
	ds_read_b128 v[136:139], v152
	ds_read_b128 v[140:143], v152 offset:1024
	ds_read_b128 v[148:151], v152 offset:2048
	ds_read_b128 v[152:155], v152 offset:3072
	ds_read_b128 v[156:159], v168
	ds_read_b128 v[160:163], v168 offset:1024
	ds_read_b128 v[164:167], v168 offset:2048
	ds_read_b128 v[182:185], v168 offset:3072
	s_add_i32 s76, s26, 2
	s_add_u32 s27, s24, 0xfff80080
	s_addc_u32 s28, s25, -1
	s_cmp_eq_u32 s67, s26
	s_cselect_b32 s26, s66, s68
	s_cselect_b32 s29, s46, s28
	s_cselect_b32 s28, s47, s27
	s_cselect_b32 s27, s49, s70
	v_lshl_add_u64 v[168:169], s[24:25], 0, v[132:133]
	s_add_i32 m0, s31, 0xc000
	ds_read_b128 v[186:189], v147
	ds_read_b128 v[190:193], v147 offset:1024
	ds_read_b128 v[194:197], v147 offset:2048
	ds_read_b128 v[198:201], v147 offset:3072
	ds_read_b128 v[202:205], v147 offset:4096
	ds_read_b128 v[206:209], v147 offset:5120
	ds_read_b128 v[210:213], v147 offset:6144
	ds_read_b128 v[214:217], v147 offset:7168
	global_load_lds_dwordx4 v[168:169], off
	s_add_i32 m0, s31, 0xe000
	v_lshl_add_u64 v[168:169], s[24:25], 0, v[134:135]
	global_load_lds_dwordx4 v[168:169], off
	s_waitcnt vmcnt(8)
	s_waitcnt lgkmcnt(0)
	s_barrier
	s_setprio 1
	s_waitcnt lgkmcnt(0)
	v_mfma_f32_16x16x32_bf16 v[126:129], v[136:139], v[186:189], v[126:129]
	v_mfma_f32_16x16x32_bf16 v[122:125], v[148:151], v[186:189], v[122:125]
	v_mfma_f32_16x16x32_bf16 v[118:121], v[136:139], v[194:197], v[118:121]
	v_mfma_f32_16x16x32_bf16 v[114:117], v[148:151], v[194:197], v[114:117]
	v_mfma_f32_16x16x32_bf16 v[110:113], v[136:139], v[202:205], v[110:113]
	v_mfma_f32_16x16x32_bf16 v[106:109], v[148:151], v[202:205], v[106:109]
	v_mfma_f32_16x16x32_bf16 v[102:105], v[136:139], v[210:213], v[102:105]
	v_mfma_f32_16x16x32_bf16 v[98:101], v[148:151], v[210:213], v[98:101]
	v_mfma_f32_16x16x32_bf16 v[126:129], v[140:143], v[190:193], v[126:129]
	v_mfma_f32_16x16x32_bf16 v[122:125], v[152:155], v[190:193], v[122:125]
	v_mfma_f32_16x16x32_bf16 v[118:121], v[140:143], v[198:201], v[118:121]
	v_mfma_f32_16x16x32_bf16 v[114:117], v[152:155], v[198:201], v[114:117]
	v_mfma_f32_16x16x32_bf16 v[110:113], v[140:143], v[206:209], v[110:113]
	v_mfma_f32_16x16x32_bf16 v[106:109], v[152:155], v[206:209], v[106:109]
	v_mfma_f32_16x16x32_bf16 v[102:105], v[140:143], v[214:217], v[102:105]
	v_mfma_f32_16x16x32_bf16 v[98:101], v[152:155], v[214:217], v[98:101]
	s_setprio 0
	s_setprio 1
	v_mfma_f32_16x16x32_bf16 v[94:97], v[156:159], v[186:189], v[94:97]
	v_mfma_f32_16x16x32_bf16 v[90:93], v[164:167], v[186:189], v[90:93]
	v_mfma_f32_16x16x32_bf16 v[86:89], v[156:159], v[194:197], v[86:89]
	v_mfma_f32_16x16x32_bf16 v[82:85], v[164:167], v[194:197], v[82:85]
	v_mfma_f32_16x16x32_bf16 v[78:81], v[156:159], v[202:205], v[78:81]
	v_mfma_f32_16x16x32_bf16 v[74:77], v[164:167], v[202:205], v[74:77]
	v_mfma_f32_16x16x32_bf16 v[70:73], v[156:159], v[210:213], v[70:73]
	v_mfma_f32_16x16x32_bf16 v[66:69], v[164:167], v[210:213], v[66:69]
	v_mfma_f32_16x16x32_bf16 v[94:97], v[160:163], v[190:193], v[94:97]
	v_mfma_f32_16x16x32_bf16 v[90:93], v[182:185], v[190:193], v[90:93]
	v_mfma_f32_16x16x32_bf16 v[86:89], v[160:163], v[198:201], v[86:89]
	v_mfma_f32_16x16x32_bf16 v[82:85], v[182:185], v[198:201], v[82:85]
	v_mfma_f32_16x16x32_bf16 v[78:81], v[160:163], v[206:209], v[78:81]
	v_mfma_f32_16x16x32_bf16 v[74:77], v[182:185], v[206:209], v[74:77]
	v_mfma_f32_16x16x32_bf16 v[70:73], v[160:163], v[214:217], v[70:73]
	v_mfma_f32_16x16x32_bf16 v[66:69], v[182:185], v[214:217], v[66:69]
	s_setprio 0
	s_barrier
	s_add_i32 s64, s4, s30
	v_lshl_add_u64 v[168:169], s[26:27], 0, v[0:1]
	s_mov_b32 m0, s64
	ds_read_b128 v[186:189], v147 offset:16384
	ds_read_b128 v[190:193], v147 offset:17408
	ds_read_b128 v[194:197], v147 offset:18432
	ds_read_b128 v[198:201], v147 offset:19456
	ds_read_b128 v[202:205], v147 offset:20480
	ds_read_b128 v[206:209], v147 offset:21504
	ds_read_b128 v[210:213], v147 offset:22528
	ds_read_b128 v[214:217], v147 offset:23552
	global_load_lds_dwordx4 v[168:169], off
	s_add_i32 m0, s64, 0x2000
	s_add_u32 s64, s26, 0x80000
	v_lshl_add_u64 v[218:219], s[26:27], 0, v[130:131]
	s_addc_u32 s65, s27, 0
	s_add_i32 s79, s5, s30
	global_load_lds_dwordx4 v[218:219], off
	v_lshl_add_u64 v[220:221], s[64:65], 0, v[0:1]
	s_mov_b32 m0, s79
	v_lshl_add_u64 v[222:223], s[28:29], 0, v[130:131]
	global_load_lds_dwordx4 v[220:221], off
	s_add_i32 m0, s79, 0x2000
	v_lshl_add_u64 v[220:221], s[64:65], 0, v[130:131]
	global_load_lds_dwordx4 v[220:221], off
	s_waitcnt vmcnt(6)
	s_waitcnt lgkmcnt(0)
	s_barrier
; #define PG8_STAGE(bufoff, gbase, voff) do { _Pragma("unroll") for (int _i = 0; _i < 2; ++_i) \
;         __builtin_amdgcn_global_load_lds((const unsigned*)((const char*)(gbase) + (voff)[_i]), (PG8_LAS unsigned*)(lds + (bufoff) + ldsw + _i * 8192), 16, 0, 0); } while (0)
; #define PG8_LDA(dst, b, h) do { _Pragma("unroll") for (int m = 0; m < 4; ++m) _Pragma("unroll") for (int k = 0; k < 2; ++k) dst[m][k] = *(const PG8_LAS bf16x8*)(lds + PG8_SA(b, h) + aoff + m * 2048 + k * 1024); } while (0)
; #define PG8_LDB(dst, b, h) do { _Pragma("unroll") for (int n = 0; n < 2; ++n) _Pragma("unroll") for (int k = 0; k < 2; ++k) dst[n][k] = *(const PG8_LAS bf16x8*)(lds + PG8_SB(b, h) + boff + n * 2048 + k * 1024); } while (0)
; #define PG8_MMA(ai, bj, At, Bt) do { __builtin_amdgcn_s_setprio(1); _Pragma("unroll") for (int m = 0; m < 4; ++m) _Pragma("unroll") for (int n = 0; n < 2; ++n) _Pragma("unroll") for (int k = 0; k < 2; ++k) \
;         acc[ai][bj][m][n] = __builtin_amdgcn_mfma_f32_16x16x32_bf16(Bt[n][k], At[m][k], acc[ai][bj][m][n], 0, 0, 0); __builtin_amdgcn_s_setprio(0); } while (0)
; #define PG8_WAIT_V(n) asm volatile("s_waitcnt vmcnt(" #n ")" ::: "memory")
; #define PG8_WAIT_L(n) asm volatile("s_waitcnt lgkmcnt(" #n ")" ::: "memory")
; #define PG8_BAR __builtin_amdgcn_s_barrier()
; #define PG8_SCHED __builtin_amdgcn_sched_barrier(0)
; template <class Epi, class Sched, bool ALIGN_EPI = false, bool SP2 = false>
; __device__ __forceinline__ void gemm_phase(PG8_LAS unsigned char* lds, const Gemm g, const Sched& S, const Epi& E, int tid_in) {
;     ...
;             PG8_WAIT_V(8); PG8_WAIT_L(0); PG8_BAR; PG8_MMA(1, 0, At, B0); PG8_MMA(1, 1, At, B1); PG8_BAR; PG8_SCHED;
;             PG8_LDB(B0, 1, 0); PG8_LDB(B1, 1, 1); PG8_SCHED; PG8_LDA(At, 1, 0); PG8_STAGE(PG8_SA(0, 1), a2 + hstepA, voffA);
;             PG8_WAIT_V(8); PG8_WAIT_L(0); PG8_BAR; PG8_MMA(0, 0, At, B0); PG8_MMA(0, 1, At, B1); PG8_BAR; PG8_SCHED;
;             PG8_LDA(At, 1, 1); PG8_STAGE(PG8_SB(1, 0), b3, voffB); PG8_STAGE(PG8_SB(1, 1), b3 + hstep, voffB); PG8_STAGE(PG8_SA(1, 0), a3, voffA);
;             PG8_WAIT_V(8); PG8_WAIT_L(0); PG8_BAR; PG8_MMA(1, 0, At, B0); PG8_MMA(1, 1, At, B1); PG8_BAR; PG8_SCHED;
	s_setprio 1
	s_waitcnt lgkmcnt(0)
	v_mfma_f32_16x16x32_bf16 v[62:65], v[136:139], v[186:189], v[62:65]
	v_mfma_f32_16x16x32_bf16 v[58:61], v[148:151], v[186:189], v[58:61]
	v_mfma_f32_16x16x32_bf16 v[54:57], v[136:139], v[194:197], v[54:57]
	v_mfma_f32_16x16x32_bf16 v[50:53], v[148:151], v[194:197], v[50:53]
	v_mfma_f32_16x16x32_bf16 v[46:49], v[136:139], v[202:205], v[46:49]
	v_mfma_f32_16x16x32_bf16 v[42:45], v[148:151], v[202:205], v[42:45]
	v_mfma_f32_16x16x32_bf16 v[38:41], v[136:139], v[210:213], v[38:41]
	v_mfma_f32_16x16x32_bf16 v[34:37], v[148:151], v[210:213], v[34:37]
	v_mfma_f32_16x16x32_bf16 v[62:65], v[140:143], v[190:193], v[62:65]
	v_mfma_f32_16x16x32_bf16 v[58:61], v[152:155], v[190:193], v[58:61]
	v_mfma_f32_16x16x32_bf16 v[54:57], v[140:143], v[198:201], v[54:57]
	v_mfma_f32_16x16x32_bf16 v[50:53], v[152:155], v[198:201], v[50:53]
	v_mfma_f32_16x16x32_bf16 v[46:49], v[140:143], v[206:209], v[46:49]
	v_mfma_f32_16x16x32_bf16 v[42:45], v[152:155], v[206:209], v[42:45]
	v_mfma_f32_16x16x32_bf16 v[38:41], v[140:143], v[214:217], v[38:41]
	v_mfma_f32_16x16x32_bf16 v[34:37], v[152:155], v[214:217], v[34:37]
	s_setprio 0
	s_setprio 1
	v_mfma_f32_16x16x32_bf16 v[30:33], v[156:159], v[186:189], v[30:33]
	v_mfma_f32_16x16x32_bf16 v[26:29], v[164:167], v[186:189], v[26:29]
	v_mfma_f32_16x16x32_bf16 v[22:25], v[156:159], v[194:197], v[22:25]
	v_mfma_f32_16x16x32_bf16 v[18:21], v[164:167], v[194:197], v[18:21]
	v_mfma_f32_16x16x32_bf16 v[14:17], v[156:159], v[202:205], v[14:17]
	v_mfma_f32_16x16x32_bf16 v[10:13], v[164:167], v[202:205], v[10:13]
	v_mfma_f32_16x16x32_bf16 v[6:9], v[156:159], v[210:213], v[6:9]
	v_mfma_f32_16x16x32_bf16 v[2:5], v[164:167], v[210:213], v[2:5]
	v_mfma_f32_16x16x32_bf16 v[30:33], v[160:163], v[190:193], v[30:33]
	v_mfma_f32_16x16x32_bf16 v[26:29], v[182:185], v[190:193], v[26:29]
	v_mfma_f32_16x16x32_bf16 v[22:25], v[160:163], v[198:201], v[22:25]
	v_mfma_f32_16x16x32_bf16 v[18:21], v[182:185], v[198:201], v[18:21]
	v_mfma_f32_16x16x32_bf16 v[14:17], v[160:163], v[206:209], v[14:17]
	v_mfma_f32_16x16x32_bf16 v[10:13], v[182:185], v[206:209], v[10:13]
	v_mfma_f32_16x16x32_bf16 v[6:9], v[160:163], v[214:217], v[6:9]
	v_mfma_f32_16x16x32_bf16 v[2:5], v[182:185], v[214:217], v[2:5]
	s_setprio 0
	s_barrier
	s_mov_b32 m0, s31
	v_lshl_add_u64 v[220:221], s[28:29], 0, v[0:1]
	global_load_lds_dwordx4 v[220:221], off
	s_mov_b32 m0, s33
	s_nop 0
	global_load_lds_dwordx4 v[222:223], off
	v_add_u32_e32 v152, s63, v146
	v_add_u32_e32 v182, s55, v146
	ds_read_b128 v[136:139], v152
	ds_read_b128 v[140:143], v152 offset:1024
	ds_read_b128 v[148:151], v152 offset:2048
	ds_read_b128 v[152:155], v152 offset:3072
	ds_read_b128 v[156:159], v182
	ds_read_b128 v[160:163], v182 offset:1024
	ds_read_b128 v[164:167], v182 offset:2048
	ds_read_b128 v[182:185], v182 offset:3072
	s_add_u32 s28, s28, 0x80000
	s_addc_u32 s29, s29, 0
	s_mov_b32 m0, s34
	v_lshl_add_u64 v[224:225], s[28:29], 0, v[0:1]
	ds_read_b128 v[186:189], v147 offset:32768
	ds_read_b128 v[190:193], v147 offset:33792
	ds_read_b128 v[194:197], v147 offset:34816
	ds_read_b128 v[198:201], v147 offset:35840
	ds_read_b128 v[202:205], v147 offset:36864
	ds_read_b128 v[206:209], v147 offset:37888
	ds_read_b128 v[210:213], v147 offset:38912
	ds_read_b128 v[214:217], v147 offset:39936
	global_load_lds_dwordx4 v[224:225], off
	s_mov_b32 m0, s35
	v_lshl_add_u64 v[224:225], s[28:29], 0, v[130:131]
	global_load_lds_dwordx4 v[224:225], off
	s_waitcnt vmcnt(8)
	s_waitcnt lgkmcnt(0)
	s_barrier
	s_setprio 1
	s_waitcnt lgkmcnt(0)
	v_mfma_f32_16x16x32_bf16 v[126:129], v[136:139], v[186:189], v[126:129]
	v_mfma_f32_16x16x32_bf16 v[122:125], v[148:151], v[186:189], v[122:125]
	v_mfma_f32_16x16x32_bf16 v[118:121], v[136:139], v[194:197], v[118:121]
	v_mfma_f32_16x16x32_bf16 v[114:117], v[148:151], v[194:197], v[114:117]
	v_mfma_f32_16x16x32_bf16 v[110:113], v[136:139], v[202:205], v[110:113]
	v_mfma_f32_16x16x32_bf16 v[106:109], v[148:151], v[202:205], v[106:109]
	v_mfma_f32_16x16x32_bf16 v[102:105], v[136:139], v[210:213], v[102:105]
	v_mfma_f32_16x16x32_bf16 v[98:101], v[148:151], v[210:213], v[98:101]
	v_mfma_f32_16x16x32_bf16 v[126:129], v[140:143], v[190:193], v[126:129]
	v_mfma_f32_16x16x32_bf16 v[122:125], v[152:155], v[190:193], v[122:125]
	v_mfma_f32_16x16x32_bf16 v[118:121], v[140:143], v[198:201], v[118:121]
	v_mfma_f32_16x16x32_bf16 v[114:117], v[152:155], v[198:201], v[114:117]
	v_mfma_f32_16x16x32_bf16 v[110:113], v[140:143], v[206:209], v[110:113]
	v_mfma_f32_16x16x32_bf16 v[106:109], v[152:155], v[206:209], v[106:109]
	v_mfma_f32_16x16x32_bf16 v[102:105], v[140:143], v[214:217], v[102:105]
	v_mfma_f32_16x16x32_bf16 v[98:101], v[152:155], v[214:217], v[98:101]
	s_setprio 0
	s_setprio 1
	v_mfma_f32_16x16x32_bf16 v[94:97], v[156:159], v[186:189], v[94:97]
	v_mfma_f32_16x16x32_bf16 v[90:93], v[164:167], v[186:189], v[90:93]
	v_mfma_f32_16x16x32_bf16 v[86:89], v[156:159], v[194:197], v[86:89]
	v_mfma_f32_16x16x32_bf16 v[82:85], v[164:167], v[194:197], v[82:85]
	v_mfma_f32_16x16x32_bf16 v[78:81], v[156:159], v[202:205], v[78:81]
	v_mfma_f32_16x16x32_bf16 v[74:77], v[164:167], v[202:205], v[74:77]
	v_mfma_f32_16x16x32_bf16 v[70:73], v[156:159], v[210:213], v[70:73]
	v_mfma_f32_16x16x32_bf16 v[66:69], v[164:167], v[210:213], v[66:69]
	v_mfma_f32_16x16x32_bf16 v[94:97], v[160:163], v[190:193], v[94:97]
	v_mfma_f32_16x16x32_bf16 v[90:93], v[182:185], v[190:193], v[90:93]
	v_mfma_f32_16x16x32_bf16 v[86:89], v[160:163], v[198:201], v[86:89]
	v_mfma_f32_16x16x32_bf16 v[82:85], v[182:185], v[198:201], v[82:85]
	v_mfma_f32_16x16x32_bf16 v[78:81], v[160:163], v[206:209], v[78:81]
	v_mfma_f32_16x16x32_bf16 v[74:77], v[182:185], v[206:209], v[74:77]
	v_mfma_f32_16x16x32_bf16 v[70:73], v[160:163], v[214:217], v[70:73]
	v_mfma_f32_16x16x32_bf16 v[66:69], v[182:185], v[214:217], v[66:69]
	s_setprio 0
	s_barrier
; #define PG8_STAGE(bufoff, gbase, voff) do { _Pragma("unroll") for (int _i = 0; _i < 2; ++_i) \
;         __builtin_amdgcn_global_load_lds((const unsigned*)((const char*)(gbase) + (voff)[_i]), (PG8_LAS unsigned*)(lds + (bufoff) + ldsw + _i * 8192), 16, 0, 0); } while (0)
; #define PG8_LDA(dst, b, h) do { _Pragma("unroll") for (int m = 0; m < 4; ++m) _Pragma("unroll") for (int k = 0; k < 2; ++k) dst[m][k] = *(const PG8_LAS bf16x8*)(lds + PG8_SA(b, h) + aoff + m * 2048 + k * 1024); } while (0)
; #define PG8_MMA(ai, bj, At, Bt) do { __builtin_amdgcn_s_setprio(1); _Pragma("unroll") for (int m = 0; m < 4; ++m) _Pragma("unroll") for (int n = 0; n < 2; ++n) _Pragma("unroll") for (int k = 0; k < 2; ++k) \
;         acc[ai][bj][m][n] = __builtin_amdgcn_mfma_f32_16x16x32_bf16(Bt[n][k], At[m][k], acc[ai][bj][m][n], 0, 0, 0); __builtin_amdgcn_s_setprio(0); } while (0)
; #define PG8_WAIT_V(n) asm volatile("s_waitcnt vmcnt(" #n ")" ::: "memory")
; #define PG8_WAIT_L(n) asm volatile("s_waitcnt lgkmcnt(" #n ")" ::: "memory")
; #define PG8_BAR __builtin_amdgcn_s_barrier()
; #define PG8_SCHED __builtin_amdgcn_sched_barrier(0)
; template <class Epi, class Sched, bool ALIGN_EPI = false, bool SP2 = false>
; __device__ __forceinline__ void gemm_phase(PG8_LAS unsigned char* lds, const Gemm g, const Sched& S, const Epi& E, int tid_in) {
;     ...
;             PG8_LDA(At, 1, 1); PG8_STAGE(PG8_SB(1, 0), b3, voffB); PG8_STAGE(PG8_SB(1, 1), b3 + hstep, voffB); PG8_STAGE(PG8_SA(1, 0), a3, voffA);
;             PG8_WAIT_V(8); PG8_WAIT_L(0); PG8_BAR; PG8_MMA(1, 0, At, B0); PG8_MMA(1, 1, At, B1); PG8_BAR; PG8_SCHED;
;     ...
;         if constexpr (ALIGN_EPI) { if (wr == 0) PG8_BAR; }
	s_add_i32 s28, s63, s30
	v_lshl_add_u64 v[168:169], v[168:169], 0, s[90:91]
	s_mov_b32 m0, s28
	ds_read_b128 v[186:189], v147 offset:49152
	ds_read_b128 v[190:193], v147 offset:50176
	ds_read_b128 v[194:197], v147 offset:51200
	ds_read_b128 v[198:201], v147 offset:52224
	ds_read_b128 v[202:205], v147 offset:53248
	ds_read_b128 v[206:209], v147 offset:54272
	ds_read_b128 v[210:213], v147 offset:55296
	ds_read_b128 v[214:217], v147 offset:56320
	global_load_lds_dwordx4 v[168:169], off
	s_add_i32 m0, s28, 0x2000
	s_add_u32 s26, s26, 0x80080
	v_lshl_add_u64 v[168:169], v[218:219], 0, s[90:91]
	s_addc_u32 s27, s27, 0
	s_add_i32 s28, s55, s30
	global_load_lds_dwordx4 v[168:169], off
	s_mov_b32 m0, s28
	v_lshl_add_u64 v[168:169], s[26:27], 0, v[0:1]
	global_load_lds_dwordx4 v[168:169], off
	s_add_i32 m0, s28, 0x2000
	v_lshl_add_u64 v[168:169], s[26:27], 0, v[130:131]
	global_load_lds_dwordx4 v[168:169], off
	s_mov_b32 m0, s41
	v_lshl_add_u64 v[168:169], v[220:221], 0, s[90:91]
	global_load_lds_dwordx4 v[168:169], off
	s_mov_b32 m0, s42
	v_lshl_add_u64 v[168:169], v[222:223], 0, s[90:91]
	global_load_lds_dwordx4 v[168:169], off
	s_add_u32 s24, s24, 0x100
	s_addc_u32 s25, s25, 0
	s_add_u32 s68, s68, 0x100
	s_addc_u32 s70, s70, 0
	s_cmp_ge_u32 s76, s45
	s_mov_b32 s26, s76
	s_waitcnt vmcnt(8)
	s_waitcnt lgkmcnt(0)
	s_barrier
	s_setprio 1
	s_waitcnt lgkmcnt(0)
	v_mfma_f32_16x16x32_bf16 v[62:65], v[136:139], v[186:189], v[62:65]
	v_mfma_f32_16x16x32_bf16 v[58:61], v[148:151], v[186:189], v[58:61]
	v_mfma_f32_16x16x32_bf16 v[54:57], v[136:139], v[194:197], v[54:57]
	v_mfma_f32_16x16x32_bf16 v[50:53], v[148:151], v[194:197], v[50:53]
	v_mfma_f32_16x16x32_bf16 v[46:49], v[136:139], v[202:205], v[46:49]
	v_mfma_f32_16x16x32_bf16 v[42:45], v[148:151], v[202:205], v[42:45]
	v_mfma_f32_16x16x32_bf16 v[38:41], v[136:139], v[210:213], v[38:41]
	v_mfma_f32_16x16x32_bf16 v[34:37], v[148:151], v[210:213], v[34:37]
	v_mfma_f32_16x16x32_bf16 v[62:65], v[140:143], v[190:193], v[62:65]
	v_mfma_f32_16x16x32_bf16 v[58:61], v[152:155], v[190:193], v[58:61]
	v_mfma_f32_16x16x32_bf16 v[54:57], v[140:143], v[198:201], v[54:57]
	v_mfma_f32_16x16x32_bf16 v[50:53], v[152:155], v[198:201], v[50:53]
	v_mfma_f32_16x16x32_bf16 v[46:49], v[140:143], v[206:209], v[46:49]
	v_mfma_f32_16x16x32_bf16 v[42:45], v[152:155], v[206:209], v[42:45]
	v_mfma_f32_16x16x32_bf16 v[38:41], v[140:143], v[214:217], v[38:41]
	v_mfma_f32_16x16x32_bf16 v[34:37], v[152:155], v[214:217], v[34:37]
	s_setprio 0
	s_setprio 1
	v_mfma_f32_16x16x32_bf16 v[30:33], v[156:159], v[186:189], v[30:33]
	v_mfma_f32_16x16x32_bf16 v[26:29], v[164:167], v[186:189], v[26:29]
	v_mfma_f32_16x16x32_bf16 v[22:25], v[156:159], v[194:197], v[22:25]
	v_mfma_f32_16x16x32_bf16 v[18:21], v[164:167], v[194:197], v[18:21]
	v_mfma_f32_16x16x32_bf16 v[14:17], v[156:159], v[202:205], v[14:17]
	v_mfma_f32_16x16x32_bf16 v[10:13], v[164:167], v[202:205], v[10:13]
	v_mfma_f32_16x16x32_bf16 v[6:9], v[156:159], v[210:213], v[6:9]
	v_mfma_f32_16x16x32_bf16 v[2:5], v[164:167], v[210:213], v[2:5]
	v_mfma_f32_16x16x32_bf16 v[30:33], v[160:163], v[190:193], v[30:33]
	v_mfma_f32_16x16x32_bf16 v[26:29], v[182:185], v[190:193], v[26:29]
	v_mfma_f32_16x16x32_bf16 v[22:25], v[160:163], v[198:201], v[22:25]
	v_mfma_f32_16x16x32_bf16 v[18:21], v[182:185], v[198:201], v[18:21]
	v_mfma_f32_16x16x32_bf16 v[14:17], v[160:163], v[206:209], v[14:17]
	v_mfma_f32_16x16x32_bf16 v[10:13], v[182:185], v[206:209], v[10:13]
	v_mfma_f32_16x16x32_bf16 v[6:9], v[160:163], v[214:217], v[6:9]
	v_mfma_f32_16x16x32_bf16 v[2:5], v[182:185], v[214:217], v[2:5]
	s_setprio 0
	s_barrier
	s_cbranch_scc0 .LBB0_1348
	s_and_b64 vcc, exec, s[16:17]
	s_cbranch_vccz .LBB0_1351
	s_barrier

; #define PG8_STAGE(bufoff, gbase, voff) do { _Pragma("unroll") for (int _i = 0; _i < 2; ++_i) \
;         __builtin_amdgcn_global_load_lds((const unsigned*)((const char*)(gbase) + (voff)[_i]), (PG8_LAS unsigned*)(lds + (bufoff) + ldsw + _i * 8192), 16, 0, 0); } while (0)
; #define PG8_LDA(dst, b, h) do { _Pragma("unroll") for (int m = 0; m < 4; ++m) _Pragma("unroll") for (int k = 0; k < 2; ++k) dst[m][k] = *(const PG8_LAS bf16x8*)(lds + PG8_SA(b, h) + aoff + m * 2048 + k * 1024); } while (0)
; #define PG8_LDB(dst, b, h) do { _Pragma("unroll") for (int n = 0; n < 2; ++n) _Pragma("unroll") for (int k = 0; k < 2; ++k) dst[n][k] = *(const PG8_LAS bf16x8*)(lds + PG8_SB(b, h) + boff + n * 2048 + k * 1024); } while (0)
; #define PG8_MMA(ai, bj, At, Bt) do { __builtin_amdgcn_s_setprio(1); _Pragma("unroll") for (int m = 0; m < 4; ++m) _Pragma("unroll") for (int n = 0; n < 2; ++n) _Pragma("unroll") for (int k = 0; k < 2; ++k) \
;         acc[ai][bj][m][n] = __builtin_amdgcn_mfma_f32_16x16x32_bf16(Bt[n][k], At[m][k], acc[ai][bj][m][n], 0, 0, 0); __builtin_amdgcn_s_setprio(0); } while (0)
; #define PG8_WAIT_V(n) asm volatile("s_waitcnt vmcnt(" #n ")" ::: "memory")
; #define PG8_WAIT_L(n) asm volatile("s_waitcnt lgkmcnt(" #n ")" ::: "memory")
; template <class Epi, class Sched, bool ALIGN_EPI = false, bool SP2 = false>
; __device__ __forceinline__ void gemm_phase(PG8_LAS unsigned char* lds, const Gemm g, const Sched& S, const Epi& E, int tid_in) {
;     ...
;             const bool last = (t == nt - 2);
;             const char* a1 = cA + (size_t)(t + 1) * kstep;
;             const char* a2 = last ? nA : cA + (size_t)(t + 2) * kstep; const char* b2 = last ? nB : cB + (size_t)(t + 2) * kstep;
;             const char* a3 = a2 + kstep; const char* b3 = b2 + kstep;
;             if (last && has_next) S.a_ready(nxt);
;             if constexpr (SP2) {
;             PG8_LDB(B0, 0, 0); PG8_LDB(B1, 0, 1); PG8_SCHED; PG8_LDA(At, 0, 0); PG8_STAGE(PG8_SA(1, 1), a1 + hstepA, voffA);
;             PG8_WAIT_V(8); PG8_WAIT_L(0); PG8_BAR; PG8_MMA(0, 0, At, B0); PG8_MMA(0, 1, At, B1); PG8_BAR; PG8_SCHED;
;             PG8_LDA(At, 0, 1); PG8_STAGE(PG8_SB(0, 0), b2, voffB); PG8_STAGE(PG8_SB(0, 1), b2 + hstep, voffB); PG8_STAGE(PG8_SA(0, 0), a2, voffA);
;             PG8_WAIT_V(8); PG8_WAIT_L(0); PG8_BAR; PG8_MMA(1, 0, At, B0); PG8_MMA(1, 1, At, B1); PG8_BAR; PG8_SCHED;
.LBB0_1507:
	v_add_u32_e32 v158, s4, v152
	v_add_u32_e32 v186, s5, v152
	ds_read_b128 v[142:145], v158
	ds_read_b128 v[146:149], v158 offset:1024
	ds_read_b128 v[154:157], v158 offset:2048
	ds_read_b128 v[158:161], v158 offset:3072
	ds_read_b128 v[162:165], v186
	ds_read_b128 v[166:169], v186 offset:1024
	ds_read_b128 v[182:185], v186 offset:2048
	ds_read_b128 v[186:189], v186 offset:3072
	s_add_u32 s26, s24, 0xfff80080
	s_addc_u32 s27, s25, -1
	s_cmp_eq_u32 s23, 28
	s_cselect_b32 s29, s19, s27
	s_cselect_b32 s28, s18, s26
	s_cselect_b32 s27, s21, s17
	s_cselect_b32 s26, s20, s15
	v_lshl_add_u64 v[222:223], s[24:25], 0, v[138:139]
	s_add_i32 m0, s35, 0xc000
	ds_read_b128 v[190:193], v153
	ds_read_b128 v[194:197], v153 offset:1024
	ds_read_b128 v[198:201], v153 offset:2048
	ds_read_b128 v[202:205], v153 offset:3072
	ds_read_b128 v[206:209], v153 offset:4096
	ds_read_b128 v[210:213], v153 offset:5120
	ds_read_b128 v[214:217], v153 offset:6144
	ds_read_b128 v[218:221], v153 offset:7168
	global_load_lds_dwordx4 v[222:223], off
	s_add_i32 m0, s35, 0xe000
	v_lshl_add_u64 v[222:223], s[24:25], 0, v[140:141]
	global_load_lds_dwordx4 v[222:223], off
	s_waitcnt vmcnt(8)
	s_waitcnt lgkmcnt(0)
	s_barrier
	s_setprio 1
	s_waitcnt lgkmcnt(0)
	v_mfma_f32_16x16x32_bf16 v[126:129], v[142:145], v[190:193], v[126:129]
	v_mfma_f32_16x16x32_bf16 v[118:121], v[154:157], v[190:193], v[118:121]
	v_mfma_f32_16x16x32_bf16 v[110:113], v[142:145], v[198:201], v[110:113]
	v_mfma_f32_16x16x32_bf16 v[102:105], v[154:157], v[198:201], v[102:105]
	v_mfma_f32_16x16x32_bf16 v[94:97], v[142:145], v[206:209], v[94:97]
	v_mfma_f32_16x16x32_bf16 v[86:89], v[154:157], v[206:209], v[86:89]
	v_mfma_f32_16x16x32_bf16 v[78:81], v[142:145], v[214:217], v[78:81]
	v_mfma_f32_16x16x32_bf16 v[70:73], v[154:157], v[214:217], v[70:73]
	v_mfma_f32_16x16x32_bf16 v[126:129], v[146:149], v[194:197], v[126:129]
	v_mfma_f32_16x16x32_bf16 v[118:121], v[158:161], v[194:197], v[118:121]
	v_mfma_f32_16x16x32_bf16 v[110:113], v[146:149], v[202:205], v[110:113]
	v_mfma_f32_16x16x32_bf16 v[102:105], v[158:161], v[202:205], v[102:105]
	v_mfma_f32_16x16x32_bf16 v[94:97], v[146:149], v[210:213], v[94:97]
	v_mfma_f32_16x16x32_bf16 v[86:89], v[158:161], v[210:213], v[86:89]
	v_mfma_f32_16x16x32_bf16 v[78:81], v[146:149], v[218:221], v[78:81]
	v_mfma_f32_16x16x32_bf16 v[70:73], v[158:161], v[218:221], v[70:73]
	s_setprio 0
	s_setprio 1
	v_mfma_f32_16x16x32_bf16 v[122:125], v[162:165], v[190:193], v[122:125]
	v_mfma_f32_16x16x32_bf16 v[114:117], v[182:185], v[190:193], v[114:117]
	v_mfma_f32_16x16x32_bf16 v[106:109], v[162:165], v[198:201], v[106:109]
	v_mfma_f32_16x16x32_bf16 v[98:101], v[182:185], v[198:201], v[98:101]
	v_mfma_f32_16x16x32_bf16 v[90:93], v[162:165], v[206:209], v[90:93]
	v_mfma_f32_16x16x32_bf16 v[82:85], v[182:185], v[206:209], v[82:85]
	v_mfma_f32_16x16x32_bf16 v[74:77], v[162:165], v[214:217], v[74:77]
	v_mfma_f32_16x16x32_bf16 v[66:69], v[182:185], v[214:217], v[66:69]
	v_mfma_f32_16x16x32_bf16 v[122:125], v[166:169], v[194:197], v[122:125]
	v_mfma_f32_16x16x32_bf16 v[114:117], v[186:189], v[194:197], v[114:117]
	v_mfma_f32_16x16x32_bf16 v[106:109], v[166:169], v[202:205], v[106:109]
	v_mfma_f32_16x16x32_bf16 v[98:101], v[186:189], v[202:205], v[98:101]
	v_mfma_f32_16x16x32_bf16 v[90:93], v[166:169], v[210:213], v[90:93]
	v_mfma_f32_16x16x32_bf16 v[82:85], v[186:189], v[210:213], v[82:85]
	v_mfma_f32_16x16x32_bf16 v[74:77], v[166:169], v[218:221], v[74:77]
	v_mfma_f32_16x16x32_bf16 v[66:69], v[186:189], v[218:221], v[66:69]
	s_setprio 0
	s_barrier
	s_add_i32 s47, s4, s34
	v_lshl_add_u64 v[222:223], s[26:27], 0, v[0:1]
	s_mov_b32 m0, s47
	ds_read_b128 v[190:193], v153 offset:16384
	ds_read_b128 v[194:197], v153 offset:17408
	ds_read_b128 v[198:201], v153 offset:18432
	ds_read_b128 v[202:205], v153 offset:19456
	ds_read_b128 v[206:209], v153 offset:20480
	ds_read_b128 v[210:213], v153 offset:21504
	ds_read_b128 v[214:217], v153 offset:22528
	ds_read_b128 v[218:221], v153 offset:23552
	global_load_lds_dwordx4 v[222:223], off
	s_add_i32 m0, s47, 0x2000
	s_add_u32 s48, s26, 0x80000
	v_lshl_add_u64 v[224:225], s[26:27], 0, v[130:131]
	s_addc_u32 s49, s27, 0
	s_add_i32 s47, s5, s34
	global_load_lds_dwordx4 v[224:225], off
	v_lshl_add_u64 v[226:227], s[48:49], 0, v[0:1]
	s_mov_b32 m0, s47
	v_lshl_add_u64 v[228:229], s[28:29], 0, v[132:133]
	global_load_lds_dwordx4 v[226:227], off
	s_add_i32 m0, s47, 0x2000
	v_lshl_add_u64 v[226:227], s[48:49], 0, v[130:131]
	global_load_lds_dwordx4 v[226:227], off
	s_waitcnt vmcnt(6)
	s_waitcnt lgkmcnt(0)
	s_barrier
; #define PG8_STAGE(bufoff, gbase, voff) do { _Pragma("unroll") for (int _i = 0; _i < 2; ++_i) \
;         __builtin_amdgcn_global_load_lds((const unsigned*)((const char*)(gbase) + (voff)[_i]), (PG8_LAS unsigned*)(lds + (bufoff) + ldsw + _i * 8192), 16, 0, 0); } while (0)
; #define PG8_LDA(dst, b, h) do { _Pragma("unroll") for (int m = 0; m < 4; ++m) _Pragma("unroll") for (int k = 0; k < 2; ++k) dst[m][k] = *(const PG8_LAS bf16x8*)(lds + PG8_SA(b, h) + aoff + m * 2048 + k * 1024); } while (0)
; #define PG8_LDB(dst, b, h) do { _Pragma("unroll") for (int n = 0; n < 2; ++n) _Pragma("unroll") for (int k = 0; k < 2; ++k) dst[n][k] = *(const PG8_LAS bf16x8*)(lds + PG8_SB(b, h) + boff + n * 2048 + k * 1024); } while (0)
; #define PG8_MMA(ai, bj, At, Bt) do { __builtin_amdgcn_s_setprio(1); _Pragma("unroll") for (int m = 0; m < 4; ++m) _Pragma("unroll") for (int n = 0; n < 2; ++n) _Pragma("unroll") for (int k = 0; k < 2; ++k) \
;         acc[ai][bj][m][n] = __builtin_amdgcn_mfma_f32_16x16x32_bf16(Bt[n][k], At[m][k], acc[ai][bj][m][n], 0, 0, 0); __builtin_amdgcn_s_setprio(0); } while (0)
; #define PG8_WAIT_V(n) asm volatile("s_waitcnt vmcnt(" #n ")" ::: "memory")
; #define PG8_WAIT_L(n) asm volatile("s_waitcnt lgkmcnt(" #n ")" ::: "memory")
; #define PG8_BAR __builtin_amdgcn_s_barrier()
; #define PG8_SCHED __builtin_amdgcn_sched_barrier(0)
; template <class Epi, class Sched, bool ALIGN_EPI = false, bool SP2 = false>
; __device__ __forceinline__ void gemm_phase(PG8_LAS unsigned char* lds, const Gemm g, const Sched& S, const Epi& E, int tid_in) {
;     ...
;             PG8_WAIT_V(8); PG8_WAIT_L(0); PG8_BAR; PG8_MMA(1, 0, At, B0); PG8_MMA(1, 1, At, B1); PG8_BAR; PG8_SCHED;
;             PG8_LDB(B0, 1, 0); PG8_LDB(B1, 1, 1); PG8_SCHED; PG8_LDA(At, 1, 0); PG8_STAGE(PG8_SA(0, 1), a2 + hstepA, voffA);
;             PG8_WAIT_V(8); PG8_WAIT_L(0); PG8_BAR; PG8_MMA(0, 0, At, B0); PG8_MMA(0, 1, At, B1); PG8_BAR; PG8_SCHED;
;             PG8_LDA(At, 1, 1); PG8_STAGE(PG8_SB(1, 0), b3, voffB); PG8_STAGE(PG8_SB(1, 1), b3 + hstep, voffB); PG8_STAGE(PG8_SA(1, 0), a3, voffA);
;             PG8_WAIT_V(8); PG8_WAIT_L(0); PG8_BAR; PG8_MMA(1, 0, At, B0); PG8_MMA(1, 1, At, B1); PG8_BAR; PG8_SCHED;
	s_setprio 1
	s_waitcnt lgkmcnt(0)
	v_mfma_f32_16x16x32_bf16 v[62:65], v[142:145], v[190:193], v[62:65]
	v_mfma_f32_16x16x32_bf16 v[54:57], v[154:157], v[190:193], v[54:57]
	v_mfma_f32_16x16x32_bf16 v[46:49], v[142:145], v[198:201], v[46:49]
	v_mfma_f32_16x16x32_bf16 v[38:41], v[154:157], v[198:201], v[38:41]
	v_mfma_f32_16x16x32_bf16 v[30:33], v[142:145], v[206:209], v[30:33]
	v_mfma_f32_16x16x32_bf16 v[22:25], v[154:157], v[206:209], v[22:25]
	v_mfma_f32_16x16x32_bf16 v[14:17], v[142:145], v[214:217], v[14:17]
	v_mfma_f32_16x16x32_bf16 v[6:9], v[154:157], v[214:217], v[6:9]
	v_mfma_f32_16x16x32_bf16 v[62:65], v[146:149], v[194:197], v[62:65]
	v_mfma_f32_16x16x32_bf16 v[54:57], v[158:161], v[194:197], v[54:57]
	v_mfma_f32_16x16x32_bf16 v[46:49], v[146:149], v[202:205], v[46:49]
	v_mfma_f32_16x16x32_bf16 v[38:41], v[158:161], v[202:205], v[38:41]
	v_mfma_f32_16x16x32_bf16 v[30:33], v[146:149], v[210:213], v[30:33]
	v_mfma_f32_16x16x32_bf16 v[22:25], v[158:161], v[210:213], v[22:25]
	v_mfma_f32_16x16x32_bf16 v[14:17], v[146:149], v[218:221], v[14:17]
	v_mfma_f32_16x16x32_bf16 v[6:9], v[158:161], v[218:221], v[6:9]
	s_setprio 0
	s_setprio 1
	v_mfma_f32_16x16x32_bf16 v[58:61], v[162:165], v[190:193], v[58:61]
	v_mfma_f32_16x16x32_bf16 v[50:53], v[182:185], v[190:193], v[50:53]
	v_mfma_f32_16x16x32_bf16 v[42:45], v[162:165], v[198:201], v[42:45]
	v_mfma_f32_16x16x32_bf16 v[34:37], v[182:185], v[198:201], v[34:37]
	v_mfma_f32_16x16x32_bf16 v[26:29], v[162:165], v[206:209], v[26:29]
	v_mfma_f32_16x16x32_bf16 v[18:21], v[182:185], v[206:209], v[18:21]
	v_mfma_f32_16x16x32_bf16 v[10:13], v[162:165], v[214:217], v[10:13]
	v_mfma_f32_16x16x32_bf16 v[2:5], v[182:185], v[214:217], v[2:5]
	v_mfma_f32_16x16x32_bf16 v[58:61], v[166:169], v[194:197], v[58:61]
	v_mfma_f32_16x16x32_bf16 v[50:53], v[186:189], v[194:197], v[50:53]
	v_mfma_f32_16x16x32_bf16 v[42:45], v[166:169], v[202:205], v[42:45]
	v_mfma_f32_16x16x32_bf16 v[34:37], v[186:189], v[202:205], v[34:37]
	v_mfma_f32_16x16x32_bf16 v[26:29], v[166:169], v[210:213], v[26:29]
	v_mfma_f32_16x16x32_bf16 v[18:21], v[186:189], v[210:213], v[18:21]
	v_mfma_f32_16x16x32_bf16 v[10:13], v[166:169], v[218:221], v[10:13]
	v_mfma_f32_16x16x32_bf16 v[2:5], v[186:189], v[218:221], v[2:5]
	s_setprio 0
	s_barrier
	s_mov_b32 m0, s35
	v_lshl_add_u64 v[226:227], s[28:29], 0, v[134:135]
	global_load_lds_dwordx4 v[226:227], off
	s_mov_b32 m0, s36
	s_nop 0
	global_load_lds_dwordx4 v[228:229], off
	v_add_u32_e32 v158, s63, v152
	v_add_u32_e32 v186, s55, v152
	ds_read_b128 v[142:145], v158
	ds_read_b128 v[146:149], v158 offset:1024
	ds_read_b128 v[154:157], v158 offset:2048
	ds_read_b128 v[158:161], v158 offset:3072
	ds_read_b128 v[162:165], v186
	ds_read_b128 v[166:169], v186 offset:1024
	ds_read_b128 v[182:185], v186 offset:2048
	ds_read_b128 v[186:189], v186 offset:3072
	s_add_u32 s28, s28, 0x80000
	s_addc_u32 s29, s29, 0
	s_mov_b32 m0, s37
	v_lshl_add_u64 v[240:241], s[28:29], 0, v[134:135]
	ds_read_b128 v[190:193], v153 offset:32768
	ds_read_b128 v[194:197], v153 offset:33792
	ds_read_b128 v[198:201], v153 offset:34816
	ds_read_b128 v[202:205], v153 offset:35840
	ds_read_b128 v[206:209], v153 offset:36864
	ds_read_b128 v[210:213], v153 offset:37888
	ds_read_b128 v[214:217], v153 offset:38912
	ds_read_b128 v[218:221], v153 offset:39936
	global_load_lds_dwordx4 v[240:241], off
	s_mov_b32 m0, s38
	v_lshl_add_u64 v[240:241], s[28:29], 0, v[132:133]
	global_load_lds_dwordx4 v[240:241], off
	s_waitcnt vmcnt(8)
	s_waitcnt lgkmcnt(0)
	s_barrier
	s_setprio 1
	s_waitcnt lgkmcnt(0)
	v_mfma_f32_16x16x32_bf16 v[126:129], v[142:145], v[190:193], v[126:129]
	v_mfma_f32_16x16x32_bf16 v[118:121], v[154:157], v[190:193], v[118:121]
	v_mfma_f32_16x16x32_bf16 v[110:113], v[142:145], v[198:201], v[110:113]
	v_mfma_f32_16x16x32_bf16 v[102:105], v[154:157], v[198:201], v[102:105]
	v_mfma_f32_16x16x32_bf16 v[94:97], v[142:145], v[206:209], v[94:97]
	v_mfma_f32_16x16x32_bf16 v[86:89], v[154:157], v[206:209], v[86:89]
	v_mfma_f32_16x16x32_bf16 v[78:81], v[142:145], v[214:217], v[78:81]
	v_mfma_f32_16x16x32_bf16 v[70:73], v[154:157], v[214:217], v[70:73]
	v_mfma_f32_16x16x32_bf16 v[126:129], v[146:149], v[194:197], v[126:129]
	v_mfma_f32_16x16x32_bf16 v[118:121], v[158:161], v[194:197], v[118:121]
	v_mfma_f32_16x16x32_bf16 v[110:113], v[146:149], v[202:205], v[110:113]
	v_mfma_f32_16x16x32_bf16 v[102:105], v[158:161], v[202:205], v[102:105]
	v_mfma_f32_16x16x32_bf16 v[94:97], v[146:149], v[210:213], v[94:97]
	v_mfma_f32_16x16x32_bf16 v[86:89], v[158:161], v[210:213], v[86:89]
	v_mfma_f32_16x16x32_bf16 v[78:81], v[146:149], v[218:221], v[78:81]
	v_mfma_f32_16x16x32_bf16 v[70:73], v[158:161], v[218:221], v[70:73]
	s_setprio 0
	s_setprio 1
	v_mfma_f32_16x16x32_bf16 v[122:125], v[162:165], v[190:193], v[122:125]
	v_mfma_f32_16x16x32_bf16 v[114:117], v[182:185], v[190:193], v[114:117]
	v_mfma_f32_16x16x32_bf16 v[106:109], v[162:165], v[198:201], v[106:109]
	v_mfma_f32_16x16x32_bf16 v[98:101], v[182:185], v[198:201], v[98:101]
	v_mfma_f32_16x16x32_bf16 v[90:93], v[162:165], v[206:209], v[90:93]
	v_mfma_f32_16x16x32_bf16 v[82:85], v[182:185], v[206:209], v[82:85]
	v_mfma_f32_16x16x32_bf16 v[74:77], v[162:165], v[214:217], v[74:77]
	v_mfma_f32_16x16x32_bf16 v[66:69], v[182:185], v[214:217], v[66:69]
	v_mfma_f32_16x16x32_bf16 v[122:125], v[166:169], v[194:197], v[122:125]
	v_mfma_f32_16x16x32_bf16 v[114:117], v[186:189], v[194:197], v[114:117]
	v_mfma_f32_16x16x32_bf16 v[106:109], v[166:169], v[202:205], v[106:109]
	v_mfma_f32_16x16x32_bf16 v[98:101], v[186:189], v[202:205], v[98:101]
	v_mfma_f32_16x16x32_bf16 v[90:93], v[166:169], v[210:213], v[90:93]
	v_mfma_f32_16x16x32_bf16 v[82:85], v[186:189], v[210:213], v[82:85]
	v_mfma_f32_16x16x32_bf16 v[74:77], v[166:169], v[218:221], v[74:77]
	v_mfma_f32_16x16x32_bf16 v[66:69], v[186:189], v[218:221], v[66:69]
	s_setprio 0
	s_barrier
; #define PG8_STAGE(bufoff, gbase, voff) do { _Pragma("unroll") for (int _i = 0; _i < 2; ++_i) \
;         __builtin_amdgcn_global_load_lds((const unsigned*)((const char*)(gbase) + (voff)[_i]), (PG8_LAS unsigned*)(lds + (bufoff) + ldsw + _i * 8192), 16, 0, 0); } while (0)
; #define PG8_LDA(dst, b, h) do { _Pragma("unroll") for (int m = 0; m < 4; ++m) _Pragma("unroll") for (int k = 0; k < 2; ++k) dst[m][k] = *(const PG8_LAS bf16x8*)(lds + PG8_SA(b, h) + aoff + m * 2048 + k * 1024); } while (0)
; #define PG8_MMA(ai, bj, At, Bt) do { __builtin_amdgcn_s_setprio(1); _Pragma("unroll") for (int m = 0; m < 4; ++m) _Pragma("unroll") for (int n = 0; n < 2; ++n) _Pragma("unroll") for (int k = 0; k < 2; ++k) \
;         acc[ai][bj][m][n] = __builtin_amdgcn_mfma_f32_16x16x32_bf16(Bt[n][k], At[m][k], acc[ai][bj][m][n], 0, 0, 0); __builtin_amdgcn_s_setprio(0); } while (0)
; #define PG8_WAIT_V(n) asm volatile("s_waitcnt vmcnt(" #n ")" ::: "memory")
; #define PG8_WAIT_L(n) asm volatile("s_waitcnt lgkmcnt(" #n ")" ::: "memory")
; #define PG8_BAR __builtin_amdgcn_s_barrier()
; #define PG8_SCHED __builtin_amdgcn_sched_barrier(0)
; template <class Epi, class Sched, bool ALIGN_EPI = false, bool SP2 = false>
; __device__ __forceinline__ void gemm_phase(PG8_LAS unsigned char* lds, const Gemm g, const Sched& S, const Epi& E, int tid_in) {
;     ...
;             PG8_LDA(At, 1, 1); PG8_STAGE(PG8_SB(1, 0), b3, voffB); PG8_STAGE(PG8_SB(1, 1), b3 + hstep, voffB); PG8_STAGE(PG8_SA(1, 0), a3, voffA);
;             PG8_WAIT_V(8); PG8_WAIT_L(0); PG8_BAR; PG8_MMA(1, 0, At, B0); PG8_MMA(1, 1, At, B1); PG8_BAR; PG8_SCHED;
;     ...
;         if constexpr (ALIGN_EPI) { if (wr == 0) PG8_BAR; }
	s_add_i32 s28, s63, s34
	v_lshl_add_u64 v[222:223], v[222:223], 0, s[90:91]
	s_mov_b32 m0, s28
	ds_read_b128 v[190:193], v153 offset:49152
	ds_read_b128 v[194:197], v153 offset:50176
	ds_read_b128 v[198:201], v153 offset:51200
	ds_read_b128 v[202:205], v153 offset:52224
	ds_read_b128 v[206:209], v153 offset:53248
	ds_read_b128 v[210:213], v153 offset:54272
	ds_read_b128 v[214:217], v153 offset:55296
	ds_read_b128 v[218:221], v153 offset:56320
	global_load_lds_dwordx4 v[222:223], off
	s_add_i32 m0, s28, 0x2000
	s_add_u32 s26, s26, 0x80080
	v_lshl_add_u64 v[222:223], v[224:225], 0, s[90:91]
	s_addc_u32 s27, s27, 0
	s_add_i32 s28, s55, s34
	global_load_lds_dwordx4 v[222:223], off
	s_mov_b32 m0, s28
	v_lshl_add_u64 v[222:223], s[26:27], 0, v[0:1]
	global_load_lds_dwordx4 v[222:223], off
	s_add_i32 m0, s28, 0x2000
	v_lshl_add_u64 v[222:223], s[26:27], 0, v[130:131]
	global_load_lds_dwordx4 v[222:223], off
	s_mov_b32 m0, s41
	v_lshl_add_u64 v[222:223], v[226:227], 0, s[90:91]
	global_load_lds_dwordx4 v[222:223], off
	s_mov_b32 m0, s42
	v_lshl_add_u64 v[222:223], v[228:229], 0, s[90:91]
	global_load_lds_dwordx4 v[222:223], off
	s_add_i32 s23, s23, 2
	s_add_u32 s24, s24, 0x100
	s_addc_u32 s25, s25, 0
	s_add_u32 s15, s15, 0x100
	s_addc_u32 s17, s17, 0
	s_cmp_gt_u32 s23, 29
	s_waitcnt vmcnt(8)
	s_waitcnt lgkmcnt(0)
	s_barrier
	s_setprio 1
	s_waitcnt lgkmcnt(0)
	v_mfma_f32_16x16x32_bf16 v[62:65], v[142:145], v[190:193], v[62:65]
	v_mfma_f32_16x16x32_bf16 v[54:57], v[154:157], v[190:193], v[54:57]
	v_mfma_f32_16x16x32_bf16 v[46:49], v[142:145], v[198:201], v[46:49]
	v_mfma_f32_16x16x32_bf16 v[38:41], v[154:157], v[198:201], v[38:41]
	v_mfma_f32_16x16x32_bf16 v[30:33], v[142:145], v[206:209], v[30:33]
	v_mfma_f32_16x16x32_bf16 v[22:25], v[154:157], v[206:209], v[22:25]
	v_mfma_f32_16x16x32_bf16 v[14:17], v[142:145], v[214:217], v[14:17]
	v_mfma_f32_16x16x32_bf16 v[6:9], v[154:157], v[214:217], v[6:9]
	v_mfma_f32_16x16x32_bf16 v[62:65], v[146:149], v[194:197], v[62:65]
	v_mfma_f32_16x16x32_bf16 v[54:57], v[158:161], v[194:197], v[54:57]
	v_mfma_f32_16x16x32_bf16 v[46:49], v[146:149], v[202:205], v[46:49]
	v_mfma_f32_16x16x32_bf16 v[38:41], v[158:161], v[202:205], v[38:41]
	v_mfma_f32_16x16x32_bf16 v[30:33], v[146:149], v[210:213], v[30:33]
	v_mfma_f32_16x16x32_bf16 v[22:25], v[158:161], v[210:213], v[22:25]
	v_mfma_f32_16x16x32_bf16 v[14:17], v[146:149], v[218:221], v[14:17]
	v_mfma_f32_16x16x32_bf16 v[6:9], v[158:161], v[218:221], v[6:9]
	s_setprio 0
	s_setprio 1
	v_mfma_f32_16x16x32_bf16 v[58:61], v[162:165], v[190:193], v[58:61]
	v_mfma_f32_16x16x32_bf16 v[50:53], v[182:185], v[190:193], v[50:53]
	v_mfma_f32_16x16x32_bf16 v[42:45], v[162:165], v[198:201], v[42:45]
	v_mfma_f32_16x16x32_bf16 v[34:37], v[182:185], v[198:201], v[34:37]
	v_mfma_f32_16x16x32_bf16 v[26:29], v[162:165], v[206:209], v[26:29]
	v_mfma_f32_16x16x32_bf16 v[18:21], v[182:185], v[206:209], v[18:21]
	v_mfma_f32_16x16x32_bf16 v[10:13], v[162:165], v[214:217], v[10:13]
	v_mfma_f32_16x16x32_bf16 v[2:5], v[182:185], v[214:217], v[2:5]
	v_mfma_f32_16x16x32_bf16 v[58:61], v[166:169], v[194:197], v[58:61]
	v_mfma_f32_16x16x32_bf16 v[50:53], v[186:189], v[194:197], v[50:53]
	v_mfma_f32_16x16x32_bf16 v[42:45], v[166:169], v[202:205], v[42:45]
	v_mfma_f32_16x16x32_bf16 v[34:37], v[186:189], v[202:205], v[34:37]
	v_mfma_f32_16x16x32_bf16 v[26:29], v[166:169], v[210:213], v[26:29]
	v_mfma_f32_16x16x32_bf16 v[18:21], v[186:189], v[210:213], v[18:21]
	v_mfma_f32_16x16x32_bf16 v[10:13], v[166:169], v[218:221], v[10:13]
	v_mfma_f32_16x16x32_bf16 v[2:5], v[186:189], v[218:221], v[2:5]
	s_setprio 0
	s_barrier
	s_cbranch_scc0 .LBB0_1507
	s_and_b64 vcc, exec, s[12:13]
	s_cbranch_vccz .LBB0_1510
	s_barrier

; #define PG8_STAGE(bufoff, gbase, voff) do { _Pragma("unroll") for (int _i = 0; _i < 2; ++_i) \
;         __builtin_amdgcn_global_load_lds((const unsigned*)((const char*)(gbase) + (voff)[_i]), (PG8_LAS unsigned*)(lds + (bufoff) + ldsw + _i * 8192), 16, 0, 0); } while (0)
; #define PG8_LDA(dst, b, h) do { _Pragma("unroll") for (int m = 0; m < 4; ++m) _Pragma("unroll") for (int k = 0; k < 2; ++k) dst[m][k] = *(const PG8_LAS bf16x8*)(lds + PG8_SA(b, h) + aoff + m * 2048 + k * 1024); } while (0)
; #define PG8_LDB(dst, b, h) do { _Pragma("unroll") for (int n = 0; n < 2; ++n) _Pragma("unroll") for (int k = 0; k < 2; ++k) dst[n][k] = *(const PG8_LAS bf16x8*)(lds + PG8_SB(b, h) + boff + n * 2048 + k * 1024); } while (0)
; #define PG8_MMA(ai, bj, At, Bt) do { __builtin_amdgcn_s_setprio(1); _Pragma("unroll") for (int m = 0; m < 4; ++m) _Pragma("unroll") for (int n = 0; n < 2; ++n) _Pragma("unroll") for (int k = 0; k < 2; ++k) \
;         acc[ai][bj][m][n] = __builtin_amdgcn_mfma_f32_16x16x32_bf16(Bt[n][k], At[m][k], acc[ai][bj][m][n], 0, 0, 0); __builtin_amdgcn_s_setprio(0); } while (0)
; #define PG8_WAIT_V(n) asm volatile("s_waitcnt vmcnt(" #n ")" ::: "memory")
; #define PG8_WAIT_L(n) asm volatile("s_waitcnt lgkmcnt(" #n ")" ::: "memory")
; template <class Epi, class Sched, bool ALIGN_EPI = false, bool SP2 = false>
; __device__ __forceinline__ void gemm_phase(PG8_LAS unsigned char* lds, const Gemm g, const Sched& S, const Epi& E, int tid_in) {
;     ...
;             const bool last = (t == nt - 2);
;             const char* a1 = cA + (size_t)(t + 1) * kstep;
;             const char* a2 = last ? nA : cA + (size_t)(t + 2) * kstep; const char* b2 = last ? nB : cB + (size_t)(t + 2) * kstep;
;             const char* a3 = a2 + kstep; const char* b3 = b2 + kstep;
;             if (last && has_next) S.a_ready(nxt);
;             if constexpr (SP2) {
;             PG8_LDB(B0, 0, 0); PG8_LDB(B1, 0, 1); PG8_SCHED; PG8_LDA(At, 0, 0); PG8_STAGE(PG8_SA(1, 1), a1 + hstepA, voffA);
;             PG8_WAIT_V(8); PG8_WAIT_L(0); PG8_BAR; PG8_MMA(0, 0, At, B0); PG8_MMA(0, 1, At, B1); PG8_BAR; PG8_SCHED;
;             PG8_LDA(At, 0, 1); PG8_STAGE(PG8_SB(0, 0), b2, voffB); PG8_STAGE(PG8_SB(0, 1), b2 + hstep, voffB); PG8_STAGE(PG8_SA(0, 0), a2, voffA);
;             PG8_WAIT_V(8); PG8_WAIT_L(0); PG8_BAR; PG8_MMA(1, 0, At, B0); PG8_MMA(1, 1, At, B1); PG8_BAR; PG8_SCHED;
.LBB0_1577:
	v_add_u32_e32 v0, s4, v164
	ds_read_b128 v[130:133], v0
	ds_read_b128 v[142:145], v0 offset:1024
	ds_read_b128 v[146:149], v0 offset:2048
	ds_read_b128 v[150:153], v0 offset:3072
	v_add_u32_e32 v0, s5, v164
	ds_read_b128 v[154:157], v0
	ds_read_b128 v[158:161], v0 offset:1024
	ds_read_b128 v[166:169], v0 offset:2048
	ds_read_b128 v[182:185], v0 offset:3072
	s_add_i32 vcc_lo, s10, 2
	s_add_u32 s8, s6, 0x100
	s_addc_u32 s9, s7, 0
	s_cmp_eq_u32 s83, s10
	s_cselect_b32 s10, s82, s84
	s_cselect_b32 s37, s46, s9
	s_cselect_b32 s36, s47, s8
	s_cselect_b32 s11, s76, s85
	v_lshl_add_u64 v[218:219], s[6:7], 0, v[138:139]
	s_add_i32 m0, s38, 0xc000
	ds_read_b128 v[186:189], v165
	ds_read_b128 v[190:193], v165 offset:1024
	ds_read_b128 v[194:197], v165 offset:2048
	ds_read_b128 v[198:201], v165 offset:3072
	ds_read_b128 v[202:205], v165 offset:4096
	ds_read_b128 v[206:209], v165 offset:5120
	ds_read_b128 v[210:213], v165 offset:6144
	ds_read_b128 v[214:217], v165 offset:7168
	global_load_lds_dwordx4 v[218:219], off
	s_add_i32 m0, s38, 0xe000
	v_lshl_add_u64 v[218:219], s[6:7], 0, v[140:141]
	global_load_lds_dwordx4 v[218:219], off
	s_waitcnt vmcnt(8)
	s_waitcnt lgkmcnt(0)
	s_barrier
	s_setprio 1
	s_waitcnt lgkmcnt(0)
	v_mfma_f32_16x16x32_bf16 v[126:129], v[130:133], v[186:189], v[126:129]
	v_mfma_f32_16x16x32_bf16 v[122:125], v[146:149], v[186:189], v[122:125]
	v_mfma_f32_16x16x32_bf16 v[118:121], v[130:133], v[194:197], v[118:121]
	v_mfma_f32_16x16x32_bf16 v[114:117], v[146:149], v[194:197], v[114:117]
	v_mfma_f32_16x16x32_bf16 v[110:113], v[130:133], v[202:205], v[110:113]
	v_mfma_f32_16x16x32_bf16 v[106:109], v[146:149], v[202:205], v[106:109]
	v_mfma_f32_16x16x32_bf16 v[102:105], v[130:133], v[210:213], v[102:105]
	v_mfma_f32_16x16x32_bf16 v[98:101], v[146:149], v[210:213], v[98:101]
	v_mfma_f32_16x16x32_bf16 v[126:129], v[142:145], v[190:193], v[126:129]
	v_mfma_f32_16x16x32_bf16 v[122:125], v[150:153], v[190:193], v[122:125]
	v_mfma_f32_16x16x32_bf16 v[118:121], v[142:145], v[198:201], v[118:121]
	v_mfma_f32_16x16x32_bf16 v[114:117], v[150:153], v[198:201], v[114:117]
	v_mfma_f32_16x16x32_bf16 v[110:113], v[142:145], v[206:209], v[110:113]
	v_mfma_f32_16x16x32_bf16 v[106:109], v[150:153], v[206:209], v[106:109]
	v_mfma_f32_16x16x32_bf16 v[102:105], v[142:145], v[214:217], v[102:105]
	v_mfma_f32_16x16x32_bf16 v[98:101], v[150:153], v[214:217], v[98:101]
	s_setprio 0
	s_setprio 1
	v_mfma_f32_16x16x32_bf16 v[94:97], v[154:157], v[186:189], v[94:97]
	v_mfma_f32_16x16x32_bf16 v[90:93], v[166:169], v[186:189], v[90:93]
	v_mfma_f32_16x16x32_bf16 v[86:89], v[154:157], v[194:197], v[86:89]
	v_mfma_f32_16x16x32_bf16 v[82:85], v[166:169], v[194:197], v[82:85]
	v_mfma_f32_16x16x32_bf16 v[78:81], v[154:157], v[202:205], v[78:81]
	v_mfma_f32_16x16x32_bf16 v[74:77], v[166:169], v[202:205], v[74:77]
	v_mfma_f32_16x16x32_bf16 v[70:73], v[154:157], v[210:213], v[70:73]
	v_mfma_f32_16x16x32_bf16 v[66:69], v[166:169], v[210:213], v[66:69]
	v_mfma_f32_16x16x32_bf16 v[94:97], v[158:161], v[190:193], v[94:97]
	v_mfma_f32_16x16x32_bf16 v[90:93], v[182:185], v[190:193], v[90:93]
	v_mfma_f32_16x16x32_bf16 v[86:89], v[158:161], v[198:201], v[86:89]
	v_mfma_f32_16x16x32_bf16 v[82:85], v[182:185], v[198:201], v[82:85]
	v_mfma_f32_16x16x32_bf16 v[78:81], v[158:161], v[206:209], v[78:81]
	v_mfma_f32_16x16x32_bf16 v[74:77], v[182:185], v[206:209], v[74:77]
	v_mfma_f32_16x16x32_bf16 v[70:73], v[158:161], v[214:217], v[70:73]
	v_mfma_f32_16x16x32_bf16 v[66:69], v[182:185], v[214:217], v[66:69]
	s_setprio 0
	s_barrier
	s_add_i32 s6, s4, s33
	v_lshl_add_u64 v[218:219], s[10:11], 0, v[134:135]
	s_mov_b32 m0, s6
	ds_read_b128 v[186:189], v165 offset:16384
	ds_read_b128 v[190:193], v165 offset:17408
	ds_read_b128 v[194:197], v165 offset:18432
	ds_read_b128 v[198:201], v165 offset:19456
	ds_read_b128 v[202:205], v165 offset:20480
	ds_read_b128 v[206:209], v165 offset:21504
	ds_read_b128 v[210:213], v165 offset:22528
	ds_read_b128 v[214:217], v165 offset:23552
	global_load_lds_dwordx4 v[218:219], off
	s_add_i32 m0, s6, 0x2000
	s_add_u32 s6, s10, 0x160000
	v_lshl_add_u64 v[220:221], s[10:11], 0, v[136:137]
	s_addc_u32 s7, s11, 0
	s_add_i32 s64, s5, s33
	global_load_lds_dwordx4 v[220:221], off
	v_lshl_add_u64 v[222:223], s[6:7], 0, v[134:135]
	s_mov_b32 m0, s64
	v_lshl_add_u64 v[224:225], s[36:37], 0, v[136:137]
	global_load_lds_dwordx4 v[222:223], off
	s_add_i32 m0, s64, 0x2000
	v_lshl_add_u64 v[222:223], s[6:7], 0, v[136:137]
	global_load_lds_dwordx4 v[222:223], off
	s_waitcnt vmcnt(6)
	s_waitcnt lgkmcnt(0)
	s_barrier
; #define PG8_STAGE(bufoff, gbase, voff) do { _Pragma("unroll") for (int _i = 0; _i < 2; ++_i) \
;         __builtin_amdgcn_global_load_lds((const unsigned*)((const char*)(gbase) + (voff)[_i]), (PG8_LAS unsigned*)(lds + (bufoff) + ldsw + _i * 8192), 16, 0, 0); } while (0)
; #define PG8_LDA(dst, b, h) do { _Pragma("unroll") for (int m = 0; m < 4; ++m) _Pragma("unroll") for (int k = 0; k < 2; ++k) dst[m][k] = *(const PG8_LAS bf16x8*)(lds + PG8_SA(b, h) + aoff + m * 2048 + k * 1024); } while (0)
; #define PG8_LDB(dst, b, h) do { _Pragma("unroll") for (int n = 0; n < 2; ++n) _Pragma("unroll") for (int k = 0; k < 2; ++k) dst[n][k] = *(const PG8_LAS bf16x8*)(lds + PG8_SB(b, h) + boff + n * 2048 + k * 1024); } while (0)
; #define PG8_MMA(ai, bj, At, Bt) do { __builtin_amdgcn_s_setprio(1); _Pragma("unroll") for (int m = 0; m < 4; ++m) _Pragma("unroll") for (int n = 0; n < 2; ++n) _Pragma("unroll") for (int k = 0; k < 2; ++k) \
;         acc[ai][bj][m][n] = __builtin_amdgcn_mfma_f32_16x16x32_bf16(Bt[n][k], At[m][k], acc[ai][bj][m][n], 0, 0, 0); __builtin_amdgcn_s_setprio(0); } while (0)
; #define PG8_WAIT_V(n) asm volatile("s_waitcnt vmcnt(" #n ")" ::: "memory")
; #define PG8_WAIT_L(n) asm volatile("s_waitcnt lgkmcnt(" #n ")" ::: "memory")
; #define PG8_BAR __builtin_amdgcn_s_barrier()
; #define PG8_SCHED __builtin_amdgcn_sched_barrier(0)
; template <class Epi, class Sched, bool ALIGN_EPI = false, bool SP2 = false>
; __device__ __forceinline__ void gemm_phase(PG8_LAS unsigned char* lds, const Gemm g, const Sched& S, const Epi& E, int tid_in) {
;     ...
;             PG8_WAIT_V(8); PG8_WAIT_L(0); PG8_BAR; PG8_MMA(1, 0, At, B0); PG8_MMA(1, 1, At, B1); PG8_BAR; PG8_SCHED;
;             PG8_LDB(B0, 1, 0); PG8_LDB(B1, 1, 1); PG8_SCHED; PG8_LDA(At, 1, 0); PG8_STAGE(PG8_SA(0, 1), a2 + hstepA, voffA);
;             PG8_WAIT_V(8); PG8_WAIT_L(0); PG8_BAR; PG8_MMA(0, 0, At, B0); PG8_MMA(0, 1, At, B1); PG8_BAR; PG8_SCHED;
;             PG8_LDA(At, 1, 1); PG8_STAGE(PG8_SB(1, 0), b3, voffB); PG8_STAGE(PG8_SB(1, 1), b3 + hstep, voffB); PG8_STAGE(PG8_SA(1, 0), a3, voffA);
;             PG8_WAIT_V(8); PG8_WAIT_L(0); PG8_BAR; PG8_MMA(1, 0, At, B0); PG8_MMA(1, 1, At, B1); PG8_BAR; PG8_SCHED;
	s_setprio 1
	s_waitcnt lgkmcnt(0)
	v_mfma_f32_16x16x32_bf16 v[62:65], v[130:133], v[186:189], v[62:65]
	v_mfma_f32_16x16x32_bf16 v[58:61], v[146:149], v[186:189], v[58:61]
	v_mfma_f32_16x16x32_bf16 v[54:57], v[130:133], v[194:197], v[54:57]
	v_mfma_f32_16x16x32_bf16 v[50:53], v[146:149], v[194:197], v[50:53]
	v_mfma_f32_16x16x32_bf16 v[46:49], v[130:133], v[202:205], v[46:49]
	v_mfma_f32_16x16x32_bf16 v[42:45], v[146:149], v[202:205], v[42:45]
	v_mfma_f32_16x16x32_bf16 v[38:41], v[130:133], v[210:213], v[38:41]
	v_mfma_f32_16x16x32_bf16 v[34:37], v[146:149], v[210:213], v[34:37]
	v_mfma_f32_16x16x32_bf16 v[62:65], v[142:145], v[190:193], v[62:65]
	v_mfma_f32_16x16x32_bf16 v[58:61], v[150:153], v[190:193], v[58:61]
	v_mfma_f32_16x16x32_bf16 v[54:57], v[142:145], v[198:201], v[54:57]
	v_mfma_f32_16x16x32_bf16 v[50:53], v[150:153], v[198:201], v[50:53]
	v_mfma_f32_16x16x32_bf16 v[46:49], v[142:145], v[206:209], v[46:49]
	v_mfma_f32_16x16x32_bf16 v[42:45], v[150:153], v[206:209], v[42:45]
	v_mfma_f32_16x16x32_bf16 v[38:41], v[142:145], v[214:217], v[38:41]
	v_mfma_f32_16x16x32_bf16 v[34:37], v[150:153], v[214:217], v[34:37]
	s_setprio 0
	s_setprio 1
	v_mfma_f32_16x16x32_bf16 v[30:33], v[154:157], v[186:189], v[30:33]
	v_mfma_f32_16x16x32_bf16 v[26:29], v[166:169], v[186:189], v[26:29]
	v_mfma_f32_16x16x32_bf16 v[22:25], v[154:157], v[194:197], v[22:25]
	v_mfma_f32_16x16x32_bf16 v[18:21], v[166:169], v[194:197], v[18:21]
	v_mfma_f32_16x16x32_bf16 v[14:17], v[154:157], v[202:205], v[14:17]
	v_mfma_f32_16x16x32_bf16 v[10:13], v[166:169], v[202:205], v[10:13]
	v_mfma_f32_16x16x32_bf16 v[6:9], v[154:157], v[210:213], v[6:9]
	v_mfma_f32_16x16x32_bf16 v[2:5], v[166:169], v[210:213], v[2:5]
	v_mfma_f32_16x16x32_bf16 v[30:33], v[158:161], v[190:193], v[30:33]
	v_mfma_f32_16x16x32_bf16 v[26:29], v[182:185], v[190:193], v[26:29]
	v_mfma_f32_16x16x32_bf16 v[22:25], v[158:161], v[198:201], v[22:25]
	v_mfma_f32_16x16x32_bf16 v[18:21], v[182:185], v[198:201], v[18:21]
	v_mfma_f32_16x16x32_bf16 v[14:17], v[158:161], v[206:209], v[14:17]
	v_mfma_f32_16x16x32_bf16 v[10:13], v[182:185], v[206:209], v[10:13]
	v_mfma_f32_16x16x32_bf16 v[6:9], v[158:161], v[214:217], v[6:9]
	v_mfma_f32_16x16x32_bf16 v[2:5], v[182:185], v[214:217], v[2:5]
	s_setprio 0
	s_barrier
	s_mov_b32 m0, s38
	v_lshl_add_u64 v[222:223], s[36:37], 0, v[134:135]
	global_load_lds_dwordx4 v[222:223], off
	s_mov_b32 m0, s39
	s_nop 0
	global_load_lds_dwordx4 v[224:225], off
	v_add_u32_e32 v0, s63, v164
	ds_read_b128 v[130:133], v0
	ds_read_b128 v[142:145], v0 offset:1024
	ds_read_b128 v[146:149], v0 offset:2048
	ds_read_b128 v[150:153], v0 offset:3072
	v_add_u32_e32 v0, s55, v164
	ds_read_b128 v[154:157], v0
	ds_read_b128 v[158:161], v0 offset:1024
	ds_read_b128 v[166:169], v0 offset:2048
	ds_read_b128 v[182:185], v0 offset:3072
	s_add_u32 s6, s36, 0x160000
	s_addc_u32 s7, s37, 0
	s_mov_b32 m0, s40
	v_lshl_add_u64 v[226:227], s[6:7], 0, v[134:135]
	ds_read_b128 v[186:189], v165 offset:32768
	ds_read_b128 v[190:193], v165 offset:33792
	ds_read_b128 v[194:197], v165 offset:34816
	ds_read_b128 v[198:201], v165 offset:35840
	ds_read_b128 v[202:205], v165 offset:36864
	ds_read_b128 v[206:209], v165 offset:37888
	ds_read_b128 v[210:213], v165 offset:38912
	ds_read_b128 v[214:217], v165 offset:39936
	global_load_lds_dwordx4 v[226:227], off
	s_mov_b32 m0, s41
	v_lshl_add_u64 v[226:227], s[6:7], 0, v[136:137]
	global_load_lds_dwordx4 v[226:227], off
	s_waitcnt vmcnt(8)
	s_waitcnt lgkmcnt(0)
	s_barrier
	s_setprio 1
	s_waitcnt lgkmcnt(0)
	v_mfma_f32_16x16x32_bf16 v[126:129], v[130:133], v[186:189], v[126:129]
	v_mfma_f32_16x16x32_bf16 v[122:125], v[146:149], v[186:189], v[122:125]
	v_mfma_f32_16x16x32_bf16 v[118:121], v[130:133], v[194:197], v[118:121]
	v_mfma_f32_16x16x32_bf16 v[114:117], v[146:149], v[194:197], v[114:117]
	v_mfma_f32_16x16x32_bf16 v[110:113], v[130:133], v[202:205], v[110:113]
	v_mfma_f32_16x16x32_bf16 v[106:109], v[146:149], v[202:205], v[106:109]
	v_mfma_f32_16x16x32_bf16 v[102:105], v[130:133], v[210:213], v[102:105]
	v_mfma_f32_16x16x32_bf16 v[98:101], v[146:149], v[210:213], v[98:101]
	v_mfma_f32_16x16x32_bf16 v[126:129], v[142:145], v[190:193], v[126:129]
	v_mfma_f32_16x16x32_bf16 v[122:125], v[150:153], v[190:193], v[122:125]
	v_mfma_f32_16x16x32_bf16 v[118:121], v[142:145], v[198:201], v[118:121]
	v_mfma_f32_16x16x32_bf16 v[114:117], v[150:153], v[198:201], v[114:117]
	v_mfma_f32_16x16x32_bf16 v[110:113], v[142:145], v[206:209], v[110:113]
	v_mfma_f32_16x16x32_bf16 v[106:109], v[150:153], v[206:209], v[106:109]
	v_mfma_f32_16x16x32_bf16 v[102:105], v[142:145], v[214:217], v[102:105]
	v_mfma_f32_16x16x32_bf16 v[98:101], v[150:153], v[214:217], v[98:101]
	s_setprio 0
	s_setprio 1
	v_mfma_f32_16x16x32_bf16 v[94:97], v[154:157], v[186:189], v[94:97]
	v_mfma_f32_16x16x32_bf16 v[90:93], v[166:169], v[186:189], v[90:93]
	v_mfma_f32_16x16x32_bf16 v[86:89], v[154:157], v[194:197], v[86:89]
	v_mfma_f32_16x16x32_bf16 v[82:85], v[166:169], v[194:197], v[82:85]
	v_mfma_f32_16x16x32_bf16 v[78:81], v[154:157], v[202:205], v[78:81]
	v_mfma_f32_16x16x32_bf16 v[74:77], v[166:169], v[202:205], v[74:77]
	v_mfma_f32_16x16x32_bf16 v[70:73], v[154:157], v[210:213], v[70:73]
	v_mfma_f32_16x16x32_bf16 v[66:69], v[166:169], v[210:213], v[66:69]
	v_mfma_f32_16x16x32_bf16 v[94:97], v[158:161], v[190:193], v[94:97]
	v_mfma_f32_16x16x32_bf16 v[90:93], v[182:185], v[190:193], v[90:93]
	v_mfma_f32_16x16x32_bf16 v[86:89], v[158:161], v[198:201], v[86:89]
	v_mfma_f32_16x16x32_bf16 v[82:85], v[182:185], v[198:201], v[82:85]
	v_mfma_f32_16x16x32_bf16 v[78:81], v[158:161], v[206:209], v[78:81]
	v_mfma_f32_16x16x32_bf16 v[74:77], v[182:185], v[206:209], v[74:77]
	v_mfma_f32_16x16x32_bf16 v[70:73], v[158:161], v[214:217], v[70:73]
	v_mfma_f32_16x16x32_bf16 v[66:69], v[182:185], v[214:217], v[66:69]
	s_setprio 0
	s_barrier
; #define PG8_STAGE(bufoff, gbase, voff) do { _Pragma("unroll") for (int _i = 0; _i < 2; ++_i) \
;         __builtin_amdgcn_global_load_lds((const unsigned*)((const char*)(gbase) + (voff)[_i]), (PG8_LAS unsigned*)(lds + (bufoff) + ldsw + _i * 8192), 16, 0, 0); } while (0)
; #define PG8_LDA(dst, b, h) do { _Pragma("unroll") for (int m = 0; m < 4; ++m) _Pragma("unroll") for (int k = 0; k < 2; ++k) dst[m][k] = *(const PG8_LAS bf16x8*)(lds + PG8_SA(b, h) + aoff + m * 2048 + k * 1024); } while (0)
; #define PG8_MMA(ai, bj, At, Bt) do { __builtin_amdgcn_s_setprio(1); _Pragma("unroll") for (int m = 0; m < 4; ++m) _Pragma("unroll") for (int n = 0; n < 2; ++n) _Pragma("unroll") for (int k = 0; k < 2; ++k) \
;         acc[ai][bj][m][n] = __builtin_amdgcn_mfma_f32_16x16x32_bf16(Bt[n][k], At[m][k], acc[ai][bj][m][n], 0, 0, 0); __builtin_amdgcn_s_setprio(0); } while (0)
; #define PG8_WAIT_V(n) asm volatile("s_waitcnt vmcnt(" #n ")" ::: "memory")
; #define PG8_WAIT_L(n) asm volatile("s_waitcnt lgkmcnt(" #n ")" ::: "memory")
; #define PG8_BAR __builtin_amdgcn_s_barrier()
; #define PG8_SCHED __builtin_amdgcn_sched_barrier(0)
; template <class Epi, class Sched, bool ALIGN_EPI = false, bool SP2 = false>
; __device__ __forceinline__ void gemm_phase(PG8_LAS unsigned char* lds, const Gemm g, const Sched& S, const Epi& E, int tid_in) {
;     ...
;             PG8_LDA(At, 1, 1); PG8_STAGE(PG8_SB(1, 0), b3, voffB); PG8_STAGE(PG8_SB(1, 1), b3 + hstep, voffB); PG8_STAGE(PG8_SA(1, 0), a3, voffA);
;             PG8_WAIT_V(8); PG8_WAIT_L(0); PG8_BAR; PG8_MMA(1, 0, At, B0); PG8_MMA(1, 1, At, B1); PG8_BAR; PG8_SCHED;
;     ...
;         if constexpr (ALIGN_EPI) { if (wr == 0) PG8_BAR; }
	s_add_i32 s6, s63, s33
	v_lshl_add_u64 v[218:219], v[218:219], 0, s[90:91]
	s_mov_b32 m0, s6
	ds_read_b128 v[186:189], v165 offset:49152
	ds_read_b128 v[190:193], v165 offset:50176
	ds_read_b128 v[194:197], v165 offset:51200
	ds_read_b128 v[198:201], v165 offset:52224
	ds_read_b128 v[202:205], v165 offset:53248
	ds_read_b128 v[206:209], v165 offset:54272
	ds_read_b128 v[210:213], v165 offset:55296
	ds_read_b128 v[214:217], v165 offset:56320
	global_load_lds_dwordx4 v[218:219], off
	s_add_i32 m0, s6, 0x2000
	s_add_u32 s6, s10, 0x160080
	v_lshl_add_u64 v[218:219], v[220:221], 0, s[90:91]
	s_addc_u32 s7, s11, 0
	s_add_i32 s10, s55, s33
	global_load_lds_dwordx4 v[218:219], off
	s_mov_b32 m0, s10
	v_lshl_add_u64 v[218:219], s[6:7], 0, v[134:135]
	global_load_lds_dwordx4 v[218:219], off
	s_add_i32 m0, s10, 0x2000
	v_lshl_add_u64 v[218:219], s[6:7], 0, v[136:137]
	global_load_lds_dwordx4 v[218:219], off
	s_mov_b32 m0, s49
	v_lshl_add_u64 v[218:219], v[222:223], 0, s[90:91]
	global_load_lds_dwordx4 v[218:219], off
	s_mov_b32 m0, s66
	v_lshl_add_u64 v[218:219], v[224:225], 0, s[90:91]
	global_load_lds_dwordx4 v[218:219], off
	s_add_u32 s84, s84, 0x100
	s_addc_u32 s85, s85, 0
	s_cmp_ge_u32 vcc_lo, s79
	s_mov_b64 s[6:7], s[8:9]
	s_mov_b32 s10, vcc_lo
	s_waitcnt vmcnt(8)
	s_waitcnt lgkmcnt(0)
	s_barrier
	s_setprio 1
	s_waitcnt lgkmcnt(0)
	v_mfma_f32_16x16x32_bf16 v[62:65], v[130:133], v[186:189], v[62:65]
	v_mfma_f32_16x16x32_bf16 v[58:61], v[146:149], v[186:189], v[58:61]
	v_mfma_f32_16x16x32_bf16 v[54:57], v[130:133], v[194:197], v[54:57]
	v_mfma_f32_16x16x32_bf16 v[50:53], v[146:149], v[194:197], v[50:53]
	v_mfma_f32_16x16x32_bf16 v[46:49], v[130:133], v[202:205], v[46:49]
	v_mfma_f32_16x16x32_bf16 v[42:45], v[146:149], v[202:205], v[42:45]
	v_mfma_f32_16x16x32_bf16 v[38:41], v[130:133], v[210:213], v[38:41]
	v_mfma_f32_16x16x32_bf16 v[34:37], v[146:149], v[210:213], v[34:37]
	v_mfma_f32_16x16x32_bf16 v[62:65], v[142:145], v[190:193], v[62:65]
	v_mfma_f32_16x16x32_bf16 v[58:61], v[150:153], v[190:193], v[58:61]
	v_mfma_f32_16x16x32_bf16 v[54:57], v[142:145], v[198:201], v[54:57]
	v_mfma_f32_16x16x32_bf16 v[50:53], v[150:153], v[198:201], v[50:53]
	v_mfma_f32_16x16x32_bf16 v[46:49], v[142:145], v[206:209], v[46:49]
	v_mfma_f32_16x16x32_bf16 v[42:45], v[150:153], v[206:209], v[42:45]
	v_mfma_f32_16x16x32_bf16 v[38:41], v[142:145], v[214:217], v[38:41]
	v_mfma_f32_16x16x32_bf16 v[34:37], v[150:153], v[214:217], v[34:37]
	s_setprio 0
	s_setprio 1
	v_mfma_f32_16x16x32_bf16 v[30:33], v[154:157], v[186:189], v[30:33]
	v_mfma_f32_16x16x32_bf16 v[26:29], v[166:169], v[186:189], v[26:29]
	v_mfma_f32_16x16x32_bf16 v[22:25], v[154:157], v[194:197], v[22:25]
	v_mfma_f32_16x16x32_bf16 v[18:21], v[166:169], v[194:197], v[18:21]
	v_mfma_f32_16x16x32_bf16 v[14:17], v[154:157], v[202:205], v[14:17]
	v_mfma_f32_16x16x32_bf16 v[10:13], v[166:169], v[202:205], v[10:13]
	v_mfma_f32_16x16x32_bf16 v[6:9], v[154:157], v[210:213], v[6:9]
	v_mfma_f32_16x16x32_bf16 v[2:5], v[166:169], v[210:213], v[2:5]
	v_mfma_f32_16x16x32_bf16 v[30:33], v[158:161], v[190:193], v[30:33]
	v_mfma_f32_16x16x32_bf16 v[26:29], v[182:185], v[190:193], v[26:29]
	v_mfma_f32_16x16x32_bf16 v[22:25], v[158:161], v[198:201], v[22:25]
	v_mfma_f32_16x16x32_bf16 v[18:21], v[182:185], v[198:201], v[18:21]
	v_mfma_f32_16x16x32_bf16 v[14:17], v[158:161], v[206:209], v[14:17]
	v_mfma_f32_16x16x32_bf16 v[10:13], v[182:185], v[206:209], v[10:13]
	v_mfma_f32_16x16x32_bf16 v[6:9], v[158:161], v[214:217], v[6:9]
	v_mfma_f32_16x16x32_bf16 v[2:5], v[182:185], v[214:217], v[2:5]
	s_setprio 0
	s_barrier
	s_cbranch_scc0 .LBB0_1577
	s_and_b64 vcc, exec, s[24:25]
	s_cbranch_vccz .LBB0_1580
	s_barrier
